# v12 + load-segment issue slots trimmed: address add placed in the m0 wait state (no s_nop), the two segment-opening waits merged into one s_waitcnt
# speedup vs baseline: 1.0062x; 1.0030x over previous
.LBB0_642:
	ds_read_b128 v[148:151], v139
	ds_read_b128 v[152:155], v139 offset:1024
	ds_read_b128 v[156:159], v139 offset:2048
	ds_read_b128 v[160:163], v139 offset:3072
	ds_read_b128 v[164:167], v140
	ds_read_b128 v[168:171], v140 offset:1024
	ds_read_b128 v[172:175], v140 offset:2048
	ds_read_b128 v[176:179], v140 offset:3072
	s_add_i32 s18, s71, 0xffe80080
	s_cmp_eq_u32 s58, s73
	s_cselect_b32 s74, s69, s18
	s_cselect_b32 s76, s70, s72
	s_or_b32 s75, s74, 0x80
	s_add_i32 s18, s71, 0xfff80000
	s_mov_b32 m0, s59
	ds_read_b128 v[180:183], v141
	ds_read_b128 v[184:187], v141 offset:1024
	ds_read_b128 v[188:191], v141 offset:2048
	ds_read_b128 v[192:195], v141 offset:3072
	ds_read_b128 v[196:199], v141 offset:4096
	ds_read_b128 v[200:203], v141 offset:5120
	ds_read_b128 v[204:207], v141 offset:6144
	ds_read_b128 v[208:211], v141 offset:7168
	buffer_load_dwordx4 v137, s[12:15], s18 offen lds
	s_mov_b32 m0, s60
	s_nop 0
	buffer_load_dwordx4 v137, s[12:15], s71 offen lds
	s_waitcnt vmcnt(8) lgkmcnt(0)
	s_setprio 1
	v_mfma_f32_16x16x32_bf16 v[118:121], v[148:151], v[180:183], v[118:121]
	s_barrier
	v_mfma_f32_16x16x32_bf16 v[118:121], v[152:155], v[184:187], v[118:121]
	v_mfma_f32_16x16x32_bf16 v[114:117], v[156:159], v[180:183], v[114:117]
	v_mfma_f32_16x16x32_bf16 v[114:117], v[160:163], v[184:187], v[114:117]
	v_mfma_f32_16x16x32_bf16 v[126:129], v[164:167], v[180:183], v[126:129]
	v_mfma_f32_16x16x32_bf16 v[126:129], v[168:171], v[184:187], v[126:129]
	v_mfma_f32_16x16x32_bf16 v[122:125], v[172:175], v[180:183], v[122:125]
	v_mfma_f32_16x16x32_bf16 v[122:125], v[176:179], v[184:187], v[122:125]
	v_mfma_f32_16x16x32_bf16 v[98:101], v[172:175], v[188:191], v[98:101]
	v_mfma_f32_16x16x32_bf16 v[98:101], v[176:179], v[192:195], v[98:101]
	v_mfma_f32_16x16x32_bf16 v[106:109], v[164:167], v[188:191], v[106:109]
	v_mfma_f32_16x16x32_bf16 v[106:109], v[168:171], v[192:195], v[106:109]
	v_mfma_f32_16x16x32_bf16 v[102:105], v[156:159], v[188:191], v[102:105]
	v_mfma_f32_16x16x32_bf16 v[102:105], v[160:163], v[192:195], v[102:105]
	v_mfma_f32_16x16x32_bf16 v[110:113], v[148:151], v[188:191], v[110:113]
	v_mfma_f32_16x16x32_bf16 v[110:113], v[152:155], v[192:195], v[110:113]
	v_mfma_f32_16x16x32_bf16 v[94:97], v[148:151], v[196:199], v[94:97]
	v_mfma_f32_16x16x32_bf16 v[94:97], v[152:155], v[200:203], v[94:97]
	v_mfma_f32_16x16x32_bf16 v[86:89], v[156:159], v[196:199], v[86:89]
	v_mfma_f32_16x16x32_bf16 v[86:89], v[160:163], v[200:203], v[86:89]
	v_mfma_f32_16x16x32_bf16 v[90:93], v[164:167], v[196:199], v[90:93]
	v_mfma_f32_16x16x32_bf16 v[90:93], v[168:171], v[200:203], v[90:93]
	v_mfma_f32_16x16x32_bf16 v[82:85], v[172:175], v[196:199], v[82:85]
	v_mfma_f32_16x16x32_bf16 v[82:85], v[176:179], v[200:203], v[82:85]
	v_mfma_f32_16x16x32_bf16 v[70:73], v[172:175], v[204:207], v[70:73]
	v_mfma_f32_16x16x32_bf16 v[70:73], v[176:179], v[208:211], v[70:73]
	v_mfma_f32_16x16x32_bf16 v[74:77], v[164:167], v[204:207], v[74:77]
	v_mfma_f32_16x16x32_bf16 v[74:77], v[168:171], v[208:211], v[74:77]
	v_mfma_f32_16x16x32_bf16 v[66:69], v[156:159], v[204:207], v[66:69]
	v_mfma_f32_16x16x32_bf16 v[66:69], v[160:163], v[208:211], v[66:69]
	v_mfma_f32_16x16x32_bf16 v[78:81], v[148:151], v[204:207], v[78:81]
	v_mfma_f32_16x16x32_bf16 v[78:81], v[152:155], v[208:211], v[78:81]
	s_setprio 0
	s_barrier
	s_mov_b32 m0, s30
	s_mov_b32 s18, s14
	s_mov_b32 s19, s15
	ds_read_b128 v[180:183], v141 offset:16384
	ds_read_b128 v[184:187], v141 offset:17408
	ds_read_b128 v[188:191], v141 offset:18432
	ds_read_b128 v[192:195], v141 offset:19456
	ds_read_b128 v[196:199], v141 offset:20480
	ds_read_b128 v[200:203], v141 offset:21504
	ds_read_b128 v[204:207], v141 offset:22528
	ds_read_b128 v[208:211], v141 offset:23552
	buffer_load_dwordx4 v138, s[16:19], s76 offen lds
	s_mov_b32 m0, s31
	s_add_i32 s77, s76, 0x80000
	buffer_load_dwordx4 v138, s[16:19], s77 offen lds
	s_mov_b32 m0, s44
	s_add_i32 s77, s76, 0x100000
	buffer_load_dwordx4 v138, s[16:19], s77 offen lds
	s_mov_b32 m0, s45
	s_add_i32 s77, s76, 0x180000
	buffer_load_dwordx4 v138, s[16:19], s77 offen lds
	s_mov_b32 m0, s27
	s_add_i32 s77, s74, 0x80000
	buffer_load_dwordx4 v137, s[12:15], s74 offen lds
	s_mov_b32 m0, s46
	s_nop 0
	buffer_load_dwordx4 v137, s[12:15], s77 offen lds
	s_waitcnt vmcnt(8) lgkmcnt(0)
	s_setprio 1
	v_mfma_f32_16x16x32_bf16 v[62:65], v[148:151], v[180:183], v[62:65]
	s_barrier
	v_mfma_f32_16x16x32_bf16 v[62:65], v[152:155], v[184:187], v[62:65]
	v_mfma_f32_16x16x32_bf16 v[54:57], v[156:159], v[180:183], v[54:57]
	v_mfma_f32_16x16x32_bf16 v[54:57], v[160:163], v[184:187], v[54:57]
	v_mfma_f32_16x16x32_bf16 v[58:61], v[164:167], v[180:183], v[58:61]
	v_mfma_f32_16x16x32_bf16 v[58:61], v[168:171], v[184:187], v[58:61]
	v_mfma_f32_16x16x32_bf16 v[50:53], v[172:175], v[180:183], v[50:53]
	v_mfma_f32_16x16x32_bf16 v[50:53], v[176:179], v[184:187], v[50:53]
	v_mfma_f32_16x16x32_bf16 v[34:37], v[172:175], v[188:191], v[34:37]
	v_mfma_f32_16x16x32_bf16 v[34:37], v[176:179], v[192:195], v[34:37]
	v_mfma_f32_16x16x32_bf16 v[42:45], v[164:167], v[188:191], v[42:45]
	v_mfma_f32_16x16x32_bf16 v[42:45], v[168:171], v[192:195], v[42:45]
	v_mfma_f32_16x16x32_bf16 v[38:41], v[156:159], v[188:191], v[38:41]
	v_mfma_f32_16x16x32_bf16 v[38:41], v[160:163], v[192:195], v[38:41]
	v_mfma_f32_16x16x32_bf16 v[46:49], v[148:151], v[188:191], v[46:49]
	v_mfma_f32_16x16x32_bf16 v[46:49], v[152:155], v[192:195], v[46:49]
	v_mfma_f32_16x16x32_bf16 v[30:33], v[148:151], v[196:199], v[30:33]
	v_mfma_f32_16x16x32_bf16 v[30:33], v[152:155], v[200:203], v[30:33]
	v_mfma_f32_16x16x32_bf16 v[22:25], v[156:159], v[196:199], v[22:25]
	v_mfma_f32_16x16x32_bf16 v[22:25], v[160:163], v[200:203], v[22:25]
	v_mfma_f32_16x16x32_bf16 v[26:29], v[164:167], v[196:199], v[26:29]
	v_mfma_f32_16x16x32_bf16 v[26:29], v[168:171], v[200:203], v[26:29]
	v_mfma_f32_16x16x32_bf16 v[18:21], v[172:175], v[196:199], v[18:21]
	v_mfma_f32_16x16x32_bf16 v[18:21], v[176:179], v[200:203], v[18:21]
	v_mfma_f32_16x16x32_bf16 v[2:5], v[172:175], v[204:207], v[2:5]
	v_mfma_f32_16x16x32_bf16 v[2:5], v[176:179], v[208:211], v[2:5]
	v_mfma_f32_16x16x32_bf16 v[10:13], v[164:167], v[204:207], v[10:13]
	v_mfma_f32_16x16x32_bf16 v[10:13], v[168:171], v[208:211], v[10:13]
	v_mfma_f32_16x16x32_bf16 v[6:9], v[156:159], v[204:207], v[6:9]
	v_mfma_f32_16x16x32_bf16 v[6:9], v[160:163], v[208:211], v[6:9]
	v_mfma_f32_16x16x32_bf16 v[14:17], v[148:151], v[204:207], v[14:17]
	v_mfma_f32_16x16x32_bf16 v[14:17], v[152:155], v[208:211], v[14:17]
	s_setprio 0
	s_barrier
	ds_read_b128 v[148:151], v142
	ds_read_b128 v[152:155], v142 offset:1024
	ds_read_b128 v[156:159], v142 offset:2048
	ds_read_b128 v[160:163], v142 offset:3072
	ds_read_b128 v[164:167], v143
	ds_read_b128 v[168:171], v143 offset:1024
	ds_read_b128 v[172:175], v143 offset:2048
	ds_read_b128 v[176:179], v143 offset:3072
	s_mov_b32 m0, s47
	s_add_i32 s77, s74, 0x100000
	ds_read_b128 v[180:183], v141 offset:32768
	ds_read_b128 v[184:187], v141 offset:33792
	ds_read_b128 v[188:191], v141 offset:34816
	ds_read_b128 v[192:195], v141 offset:35840
	ds_read_b128 v[196:199], v141 offset:36864
	ds_read_b128 v[200:203], v141 offset:37888
	ds_read_b128 v[204:207], v141 offset:38912
	ds_read_b128 v[208:211], v141 offset:39936
	buffer_load_dwordx4 v137, s[12:15], s77 offen lds
	s_mov_b32 m0, s48
	s_add_i32 s77, s74, 0x180000
	buffer_load_dwordx4 v137, s[12:15], s77 offen lds
	s_waitcnt vmcnt(8) lgkmcnt(0)
	s_setprio 1
	v_mfma_f32_16x16x32_bf16 v[118:121], v[148:151], v[180:183], v[118:121]
	s_barrier
	v_mfma_f32_16x16x32_bf16 v[118:121], v[152:155], v[184:187], v[118:121]
	v_mfma_f32_16x16x32_bf16 v[114:117], v[156:159], v[180:183], v[114:117]
	v_mfma_f32_16x16x32_bf16 v[114:117], v[160:163], v[184:187], v[114:117]
	v_mfma_f32_16x16x32_bf16 v[126:129], v[164:167], v[180:183], v[126:129]
	v_mfma_f32_16x16x32_bf16 v[126:129], v[168:171], v[184:187], v[126:129]
	v_mfma_f32_16x16x32_bf16 v[122:125], v[172:175], v[180:183], v[122:125]
	v_mfma_f32_16x16x32_bf16 v[122:125], v[176:179], v[184:187], v[122:125]
	v_mfma_f32_16x16x32_bf16 v[98:101], v[172:175], v[188:191], v[98:101]
	v_mfma_f32_16x16x32_bf16 v[98:101], v[176:179], v[192:195], v[98:101]
	v_mfma_f32_16x16x32_bf16 v[106:109], v[164:167], v[188:191], v[106:109]
	v_mfma_f32_16x16x32_bf16 v[106:109], v[168:171], v[192:195], v[106:109]
	v_mfma_f32_16x16x32_bf16 v[102:105], v[156:159], v[188:191], v[102:105]
	v_mfma_f32_16x16x32_bf16 v[102:105], v[160:163], v[192:195], v[102:105]
	v_mfma_f32_16x16x32_bf16 v[110:113], v[148:151], v[188:191], v[110:113]
	v_mfma_f32_16x16x32_bf16 v[110:113], v[152:155], v[192:195], v[110:113]
	v_mfma_f32_16x16x32_bf16 v[94:97], v[148:151], v[196:199], v[94:97]
	v_mfma_f32_16x16x32_bf16 v[94:97], v[152:155], v[200:203], v[94:97]
	v_mfma_f32_16x16x32_bf16 v[86:89], v[156:159], v[196:199], v[86:89]
	v_mfma_f32_16x16x32_bf16 v[86:89], v[160:163], v[200:203], v[86:89]
	v_mfma_f32_16x16x32_bf16 v[90:93], v[164:167], v[196:199], v[90:93]
	v_mfma_f32_16x16x32_bf16 v[90:93], v[168:171], v[200:203], v[90:93]
	v_mfma_f32_16x16x32_bf16 v[82:85], v[172:175], v[196:199], v[82:85]
	v_mfma_f32_16x16x32_bf16 v[82:85], v[176:179], v[200:203], v[82:85]
	v_mfma_f32_16x16x32_bf16 v[70:73], v[172:175], v[204:207], v[70:73]
	v_mfma_f32_16x16x32_bf16 v[70:73], v[176:179], v[208:211], v[70:73]
	v_mfma_f32_16x16x32_bf16 v[74:77], v[164:167], v[204:207], v[74:77]
	v_mfma_f32_16x16x32_bf16 v[74:77], v[168:171], v[208:211], v[74:77]
	v_mfma_f32_16x16x32_bf16 v[66:69], v[156:159], v[204:207], v[66:69]
	v_mfma_f32_16x16x32_bf16 v[66:69], v[160:163], v[208:211], v[66:69]
	v_mfma_f32_16x16x32_bf16 v[78:81], v[148:151], v[204:207], v[78:81]
	v_mfma_f32_16x16x32_bf16 v[78:81], v[152:155], v[208:211], v[78:81]
	s_setprio 0
	s_barrier
	s_mov_b32 m0, s50
	s_or_b32 s77, s76, 0x80
	ds_read_b128 v[180:183], v141 offset:49152
	ds_read_b128 v[184:187], v141 offset:50176
	ds_read_b128 v[188:191], v141 offset:51200
	ds_read_b128 v[192:195], v141 offset:52224
	ds_read_b128 v[196:199], v141 offset:53248
	ds_read_b128 v[200:203], v141 offset:54272
	ds_read_b128 v[204:207], v141 offset:55296
	ds_read_b128 v[208:211], v141 offset:56320
	buffer_load_dwordx4 v138, s[16:19], s77 offen lds
	s_add_i32 s77, s76, 0x80080
	s_mov_b32 m0, s51
	s_add_i32 s74, s74, 0x80080
	buffer_load_dwordx4 v138, s[16:19], s77 offen lds
	s_add_i32 s77, s76, 0x100080
	s_mov_b32 m0, s54
	s_add_i32 s76, s76, 0x180080
	buffer_load_dwordx4 v138, s[16:19], s77 offen lds
	s_mov_b32 m0, s55
	s_nop 0
	buffer_load_dwordx4 v138, s[16:19], s76 offen lds
	s_mov_b32 m0, s52
	s_nop 0
	buffer_load_dwordx4 v137, s[12:15], s75 offen lds
	s_mov_b32 m0, s53
	s_nop 0
	buffer_load_dwordx4 v137, s[12:15], s74 offen lds
	s_waitcnt vmcnt(8) lgkmcnt(0)
	s_setprio 1
	v_mfma_f32_16x16x32_bf16 v[62:65], v[148:151], v[180:183], v[62:65]
	s_barrier
	v_mfma_f32_16x16x32_bf16 v[62:65], v[152:155], v[184:187], v[62:65]
	v_mfma_f32_16x16x32_bf16 v[54:57], v[156:159], v[180:183], v[54:57]
	v_mfma_f32_16x16x32_bf16 v[54:57], v[160:163], v[184:187], v[54:57]
	v_mfma_f32_16x16x32_bf16 v[58:61], v[164:167], v[180:183], v[58:61]
	v_mfma_f32_16x16x32_bf16 v[58:61], v[168:171], v[184:187], v[58:61]
	v_mfma_f32_16x16x32_bf16 v[50:53], v[172:175], v[180:183], v[50:53]
	v_mfma_f32_16x16x32_bf16 v[50:53], v[176:179], v[184:187], v[50:53]
	v_mfma_f32_16x16x32_bf16 v[34:37], v[172:175], v[188:191], v[34:37]
	v_mfma_f32_16x16x32_bf16 v[34:37], v[176:179], v[192:195], v[34:37]
	v_mfma_f32_16x16x32_bf16 v[42:45], v[164:167], v[188:191], v[42:45]
	v_mfma_f32_16x16x32_bf16 v[42:45], v[168:171], v[192:195], v[42:45]
	v_mfma_f32_16x16x32_bf16 v[38:41], v[156:159], v[188:191], v[38:41]
	v_mfma_f32_16x16x32_bf16 v[38:41], v[160:163], v[192:195], v[38:41]
	v_mfma_f32_16x16x32_bf16 v[46:49], v[148:151], v[188:191], v[46:49]
	v_mfma_f32_16x16x32_bf16 v[46:49], v[152:155], v[192:195], v[46:49]
	v_mfma_f32_16x16x32_bf16 v[30:33], v[148:151], v[196:199], v[30:33]
	v_mfma_f32_16x16x32_bf16 v[30:33], v[152:155], v[200:203], v[30:33]
	v_mfma_f32_16x16x32_bf16 v[22:25], v[156:159], v[196:199], v[22:25]
	v_mfma_f32_16x16x32_bf16 v[22:25], v[160:163], v[200:203], v[22:25]
	v_mfma_f32_16x16x32_bf16 v[26:29], v[164:167], v[196:199], v[26:29]
	v_mfma_f32_16x16x32_bf16 v[26:29], v[168:171], v[200:203], v[26:29]
	v_mfma_f32_16x16x32_bf16 v[18:21], v[172:175], v[196:199], v[18:21]
	v_mfma_f32_16x16x32_bf16 v[18:21], v[176:179], v[200:203], v[18:21]
	v_mfma_f32_16x16x32_bf16 v[2:5], v[172:175], v[204:207], v[2:5]
	v_mfma_f32_16x16x32_bf16 v[2:5], v[176:179], v[208:211], v[2:5]
	v_mfma_f32_16x16x32_bf16 v[10:13], v[164:167], v[204:207], v[10:13]
	v_mfma_f32_16x16x32_bf16 v[10:13], v[168:171], v[208:211], v[10:13]
	v_mfma_f32_16x16x32_bf16 v[6:9], v[156:159], v[204:207], v[6:9]
	v_mfma_f32_16x16x32_bf16 v[6:9], v[160:163], v[208:211], v[6:9]
	v_mfma_f32_16x16x32_bf16 v[14:17], v[148:151], v[204:207], v[14:17]
	v_mfma_f32_16x16x32_bf16 v[14:17], v[152:155], v[208:211], v[14:17]
	s_setprio 0
	s_barrier
	s_add_i32 s73, s73, 2
	s_addk_i32 s71, 0x100
	s_addk_i32 s72, 0x100
	s_cmp_ge_i32 s73, s3
	s_cbranch_scc0 .LBB0_642
	s_and_b64 vcc, exec, s[42:43]
	s_cbranch_vccz .LBB0_645

.LBB0_799:
	ds_read_b128 v[134:137], v210
	ds_read_b128 v[138:141], v210 offset:1024
	ds_read_b128 v[142:145], v210 offset:2048
	ds_read_b128 v[148:151], v210 offset:3072
	ds_read_b128 v[152:155], v211
	ds_read_b128 v[156:159], v211 offset:1024
	ds_read_b128 v[160:163], v211 offset:2048
	ds_read_b128 v[164:167], v211 offset:3072
	s_add_i32 s18, s77, 0xffbf8080
	s_cmp_eq_u32 s62, s79
	s_cselect_b32 s80, s6, s18
	s_cselect_b32 s82, s7, s78
	s_or_b32 s81, s80, 0x80
	s_add_i32 s18, s77, 0xffea8000
	s_mov_b32 m0, s63
	ds_read_b128 v[168:171], v212
	ds_read_b128 v[172:175], v212 offset:1024
	ds_read_b128 v[176:179], v212 offset:2048
	ds_read_b128 v[180:183], v212 offset:3072
	ds_read_b128 v[184:187], v212 offset:4096
	ds_read_b128 v[188:191], v212 offset:5120
	ds_read_b128 v[192:195], v212 offset:6144
	ds_read_b128 v[196:199], v212 offset:7168
	buffer_load_dwordx4 v208, s[12:15], s18 offen lds
	s_mov_b32 m0, s66
	s_nop 0
	buffer_load_dwordx4 v208, s[12:15], s77 offen lds
	s_waitcnt vmcnt(8) lgkmcnt(0)
	s_setprio 1
	v_mfma_f32_16x16x32_bf16 v[126:129], v[134:137], v[168:171], v[126:129]
	s_barrier
	v_mfma_f32_16x16x32_bf16 v[126:129], v[138:141], v[172:175], v[126:129]
	v_mfma_f32_16x16x32_bf16 v[122:125], v[142:145], v[168:171], v[122:125]
	v_mfma_f32_16x16x32_bf16 v[122:125], v[148:151], v[172:175], v[122:125]
	v_mfma_f32_16x16x32_bf16 v[110:113], v[152:155], v[168:171], v[110:113]
	v_mfma_f32_16x16x32_bf16 v[110:113], v[156:159], v[172:175], v[110:113]
	v_mfma_f32_16x16x32_bf16 v[102:105], v[160:163], v[168:171], v[102:105]
	v_mfma_f32_16x16x32_bf16 v[102:105], v[164:167], v[172:175], v[102:105]
	v_mfma_f32_16x16x32_bf16 v[86:89], v[160:163], v[176:179], v[86:89]
	v_mfma_f32_16x16x32_bf16 v[86:89], v[164:167], v[180:183], v[86:89]
	v_mfma_f32_16x16x32_bf16 v[94:97], v[152:155], v[176:179], v[94:97]
	v_mfma_f32_16x16x32_bf16 v[94:97], v[156:159], v[180:183], v[94:97]
	v_mfma_f32_16x16x32_bf16 v[114:117], v[142:145], v[176:179], v[114:117]
	v_mfma_f32_16x16x32_bf16 v[114:117], v[148:151], v[180:183], v[114:117]
	v_mfma_f32_16x16x32_bf16 v[118:121], v[134:137], v[176:179], v[118:121]
	v_mfma_f32_16x16x32_bf16 v[118:121], v[138:141], v[180:183], v[118:121]
	v_mfma_f32_16x16x32_bf16 v[106:109], v[134:137], v[184:187], v[106:109]
	v_mfma_f32_16x16x32_bf16 v[106:109], v[138:141], v[188:191], v[106:109]
	v_mfma_f32_16x16x32_bf16 v[98:101], v[142:145], v[184:187], v[98:101]
	v_mfma_f32_16x16x32_bf16 v[98:101], v[148:151], v[188:191], v[98:101]
	v_mfma_f32_16x16x32_bf16 v[78:81], v[152:155], v[184:187], v[78:81]
	v_mfma_f32_16x16x32_bf16 v[78:81], v[156:159], v[188:191], v[78:81]
	v_mfma_f32_16x16x32_bf16 v[74:77], v[160:163], v[184:187], v[74:77]
	v_mfma_f32_16x16x32_bf16 v[74:77], v[164:167], v[188:191], v[74:77]
	v_mfma_f32_16x16x32_bf16 v[66:69], v[160:163], v[192:195], v[66:69]
	v_mfma_f32_16x16x32_bf16 v[66:69], v[164:167], v[196:199], v[66:69]
	v_mfma_f32_16x16x32_bf16 v[70:73], v[152:155], v[192:195], v[70:73]
	v_mfma_f32_16x16x32_bf16 v[70:73], v[156:159], v[196:199], v[70:73]
	v_mfma_f32_16x16x32_bf16 v[82:85], v[142:145], v[192:195], v[82:85]
	v_mfma_f32_16x16x32_bf16 v[82:85], v[148:151], v[196:199], v[82:85]
	v_mfma_f32_16x16x32_bf16 v[90:93], v[134:137], v[192:195], v[90:93]
	v_mfma_f32_16x16x32_bf16 v[90:93], v[138:141], v[196:199], v[90:93]
	s_setprio 0
	s_barrier
	s_mov_b32 m0, s25
	s_mov_b32 s18, s14
	s_mov_b32 s19, s15
	ds_read_b128 v[168:171], v212 offset:16384
	ds_read_b128 v[172:175], v212 offset:17408
	ds_read_b128 v[176:179], v212 offset:18432
	ds_read_b128 v[180:183], v212 offset:19456
	ds_read_b128 v[184:187], v212 offset:20480
	ds_read_b128 v[188:191], v212 offset:21504
	ds_read_b128 v[192:195], v212 offset:22528
	ds_read_b128 v[196:199], v212 offset:23552
	buffer_load_dwordx4 v209, s[16:19], s82 offen lds
	s_mov_b32 m0, s27
	s_add_i32 s83, s82, 0x158000
	buffer_load_dwordx4 v209, s[16:19], s83 offen lds
	s_mov_b32 m0, s30
	s_add_i32 s83, s82, 0x2b0000
	buffer_load_dwordx4 v209, s[16:19], s83 offen lds
	s_mov_b32 m0, s31
	s_add_i32 s83, s82, 0x408000
	buffer_load_dwordx4 v209, s[16:19], s83 offen lds
	s_mov_b32 m0, s21
	s_add_i32 s83, s80, 0x158000
	buffer_load_dwordx4 v208, s[12:15], s80 offen lds
	s_mov_b32 m0, s48
	s_nop 0
	buffer_load_dwordx4 v208, s[12:15], s83 offen lds
	s_waitcnt vmcnt(8) lgkmcnt(0)
	s_setprio 1
	v_mfma_f32_16x16x32_bf16 v[62:65], v[134:137], v[168:171], v[62:65]
	s_barrier
	v_mfma_f32_16x16x32_bf16 v[62:65], v[138:141], v[172:175], v[62:65]
	v_mfma_f32_16x16x32_bf16 v[58:61], v[142:145], v[168:171], v[58:61]
	v_mfma_f32_16x16x32_bf16 v[58:61], v[148:151], v[172:175], v[58:61]
	v_mfma_f32_16x16x32_bf16 v[46:49], v[152:155], v[168:171], v[46:49]
	v_mfma_f32_16x16x32_bf16 v[46:49], v[156:159], v[172:175], v[46:49]
	v_mfma_f32_16x16x32_bf16 v[38:41], v[160:163], v[168:171], v[38:41]
	v_mfma_f32_16x16x32_bf16 v[38:41], v[164:167], v[172:175], v[38:41]
	v_mfma_f32_16x16x32_bf16 v[22:25], v[160:163], v[176:179], v[22:25]
	v_mfma_f32_16x16x32_bf16 v[22:25], v[164:167], v[180:183], v[22:25]
	v_mfma_f32_16x16x32_bf16 v[30:33], v[152:155], v[176:179], v[30:33]
	v_mfma_f32_16x16x32_bf16 v[30:33], v[156:159], v[180:183], v[30:33]
	v_mfma_f32_16x16x32_bf16 v[50:53], v[142:145], v[176:179], v[50:53]
	v_mfma_f32_16x16x32_bf16 v[50:53], v[148:151], v[180:183], v[50:53]
	v_mfma_f32_16x16x32_bf16 v[54:57], v[134:137], v[176:179], v[54:57]
	v_mfma_f32_16x16x32_bf16 v[54:57], v[138:141], v[180:183], v[54:57]
	v_mfma_f32_16x16x32_bf16 v[42:45], v[134:137], v[184:187], v[42:45]
	v_mfma_f32_16x16x32_bf16 v[42:45], v[138:141], v[188:191], v[42:45]
	v_mfma_f32_16x16x32_bf16 v[34:37], v[142:145], v[184:187], v[34:37]
	v_mfma_f32_16x16x32_bf16 v[34:37], v[148:151], v[188:191], v[34:37]
	v_mfma_f32_16x16x32_bf16 v[14:17], v[152:155], v[184:187], v[14:17]
	v_mfma_f32_16x16x32_bf16 v[14:17], v[156:159], v[188:191], v[14:17]
	v_mfma_f32_16x16x32_bf16 v[10:13], v[160:163], v[184:187], v[10:13]
	v_mfma_f32_16x16x32_bf16 v[10:13], v[164:167], v[188:191], v[10:13]
	v_mfma_f32_16x16x32_bf16 v[2:5], v[160:163], v[192:195], v[2:5]
	v_mfma_f32_16x16x32_bf16 v[2:5], v[164:167], v[196:199], v[2:5]
	v_mfma_f32_16x16x32_bf16 v[6:9], v[152:155], v[192:195], v[6:9]
	v_mfma_f32_16x16x32_bf16 v[6:9], v[156:159], v[196:199], v[6:9]
	v_mfma_f32_16x16x32_bf16 v[18:21], v[142:145], v[192:195], v[18:21]
	v_mfma_f32_16x16x32_bf16 v[18:21], v[148:151], v[196:199], v[18:21]
	v_mfma_f32_16x16x32_bf16 v[26:29], v[134:137], v[192:195], v[26:29]
	v_mfma_f32_16x16x32_bf16 v[26:29], v[138:141], v[196:199], v[26:29]
	s_setprio 0
	s_barrier
	ds_read_b128 v[134:137], v213
	ds_read_b128 v[138:141], v213 offset:1024
	ds_read_b128 v[142:145], v213 offset:2048
	ds_read_b128 v[148:151], v213 offset:3072
	ds_read_b128 v[152:155], v214
	ds_read_b128 v[156:159], v214 offset:1024
	ds_read_b128 v[160:163], v214 offset:2048
	ds_read_b128 v[164:167], v214 offset:3072
	s_mov_b32 m0, s49
	s_add_i32 s83, s80, 0x2b0000
	ds_read_b128 v[168:171], v212 offset:32768
	ds_read_b128 v[172:175], v212 offset:33792
	ds_read_b128 v[176:179], v212 offset:34816
	ds_read_b128 v[180:183], v212 offset:35840
	ds_read_b128 v[184:187], v212 offset:36864
	ds_read_b128 v[188:191], v212 offset:37888
	ds_read_b128 v[192:195], v212 offset:38912
	ds_read_b128 v[196:199], v212 offset:39936
	buffer_load_dwordx4 v208, s[12:15], s83 offen lds
	s_mov_b32 m0, s50
	s_add_i32 s83, s80, 0x408000
	buffer_load_dwordx4 v208, s[12:15], s83 offen lds
	s_waitcnt vmcnt(8) lgkmcnt(0)
	s_setprio 1
	v_mfma_f32_16x16x32_bf16 v[126:129], v[134:137], v[168:171], v[126:129]
	s_barrier
	v_mfma_f32_16x16x32_bf16 v[126:129], v[138:141], v[172:175], v[126:129]
	v_mfma_f32_16x16x32_bf16 v[122:125], v[142:145], v[168:171], v[122:125]
	v_mfma_f32_16x16x32_bf16 v[122:125], v[148:151], v[172:175], v[122:125]
	v_mfma_f32_16x16x32_bf16 v[110:113], v[152:155], v[168:171], v[110:113]
	v_mfma_f32_16x16x32_bf16 v[110:113], v[156:159], v[172:175], v[110:113]
	v_mfma_f32_16x16x32_bf16 v[102:105], v[160:163], v[168:171], v[102:105]
	v_mfma_f32_16x16x32_bf16 v[102:105], v[164:167], v[172:175], v[102:105]
	v_mfma_f32_16x16x32_bf16 v[86:89], v[160:163], v[176:179], v[86:89]
	v_mfma_f32_16x16x32_bf16 v[86:89], v[164:167], v[180:183], v[86:89]
	v_mfma_f32_16x16x32_bf16 v[94:97], v[152:155], v[176:179], v[94:97]
	v_mfma_f32_16x16x32_bf16 v[94:97], v[156:159], v[180:183], v[94:97]
	v_mfma_f32_16x16x32_bf16 v[114:117], v[142:145], v[176:179], v[114:117]
	v_mfma_f32_16x16x32_bf16 v[114:117], v[148:151], v[180:183], v[114:117]
	v_mfma_f32_16x16x32_bf16 v[118:121], v[134:137], v[176:179], v[118:121]
	v_mfma_f32_16x16x32_bf16 v[118:121], v[138:141], v[180:183], v[118:121]
	v_mfma_f32_16x16x32_bf16 v[106:109], v[134:137], v[184:187], v[106:109]
	v_mfma_f32_16x16x32_bf16 v[106:109], v[138:141], v[188:191], v[106:109]
	v_mfma_f32_16x16x32_bf16 v[98:101], v[142:145], v[184:187], v[98:101]
	v_mfma_f32_16x16x32_bf16 v[98:101], v[148:151], v[188:191], v[98:101]
	v_mfma_f32_16x16x32_bf16 v[78:81], v[152:155], v[184:187], v[78:81]
	v_mfma_f32_16x16x32_bf16 v[78:81], v[156:159], v[188:191], v[78:81]
	v_mfma_f32_16x16x32_bf16 v[74:77], v[160:163], v[184:187], v[74:77]
	v_mfma_f32_16x16x32_bf16 v[74:77], v[164:167], v[188:191], v[74:77]
	v_mfma_f32_16x16x32_bf16 v[66:69], v[160:163], v[192:195], v[66:69]
	v_mfma_f32_16x16x32_bf16 v[66:69], v[164:167], v[196:199], v[66:69]
	v_mfma_f32_16x16x32_bf16 v[70:73], v[152:155], v[192:195], v[70:73]
	v_mfma_f32_16x16x32_bf16 v[70:73], v[156:159], v[196:199], v[70:73]
	v_mfma_f32_16x16x32_bf16 v[82:85], v[142:145], v[192:195], v[82:85]
	v_mfma_f32_16x16x32_bf16 v[82:85], v[148:151], v[196:199], v[82:85]
	v_mfma_f32_16x16x32_bf16 v[90:93], v[134:137], v[192:195], v[90:93]
	v_mfma_f32_16x16x32_bf16 v[90:93], v[138:141], v[196:199], v[90:93]
	s_setprio 0
	s_barrier
	s_mov_b32 m0, s54
	s_or_b32 s83, s82, 0x80
	ds_read_b128 v[168:171], v212 offset:49152
	ds_read_b128 v[172:175], v212 offset:50176
	ds_read_b128 v[176:179], v212 offset:51200
	ds_read_b128 v[180:183], v212 offset:52224
	ds_read_b128 v[184:187], v212 offset:53248
	ds_read_b128 v[188:191], v212 offset:54272
	ds_read_b128 v[192:195], v212 offset:55296
	ds_read_b128 v[196:199], v212 offset:56320
	buffer_load_dwordx4 v209, s[16:19], s83 offen lds
	s_add_i32 s83, s82, 0x158080
	s_mov_b32 m0, s55
	s_add_i32 s80, s80, 0x158080
	buffer_load_dwordx4 v209, s[16:19], s83 offen lds
	s_add_i32 s83, s82, 0x2b0080
	s_mov_b32 m0, s58
	s_add_i32 s82, s82, 0x408080
	buffer_load_dwordx4 v209, s[16:19], s83 offen lds
	s_mov_b32 m0, s59
	s_nop 0
	buffer_load_dwordx4 v209, s[16:19], s82 offen lds
	s_mov_b32 m0, s56
	s_nop 0
	buffer_load_dwordx4 v208, s[12:15], s81 offen lds
	s_mov_b32 m0, s57
	s_nop 0
	buffer_load_dwordx4 v208, s[12:15], s80 offen lds
	s_waitcnt vmcnt(8) lgkmcnt(0)
	s_setprio 1
	v_mfma_f32_16x16x32_bf16 v[62:65], v[134:137], v[168:171], v[62:65]
	s_barrier
	v_mfma_f32_16x16x32_bf16 v[62:65], v[138:141], v[172:175], v[62:65]
	v_mfma_f32_16x16x32_bf16 v[58:61], v[142:145], v[168:171], v[58:61]
	v_mfma_f32_16x16x32_bf16 v[58:61], v[148:151], v[172:175], v[58:61]
	v_mfma_f32_16x16x32_bf16 v[46:49], v[152:155], v[168:171], v[46:49]
	v_mfma_f32_16x16x32_bf16 v[46:49], v[156:159], v[172:175], v[46:49]
	v_mfma_f32_16x16x32_bf16 v[38:41], v[160:163], v[168:171], v[38:41]
	v_mfma_f32_16x16x32_bf16 v[38:41], v[164:167], v[172:175], v[38:41]
	v_mfma_f32_16x16x32_bf16 v[22:25], v[160:163], v[176:179], v[22:25]
	v_mfma_f32_16x16x32_bf16 v[22:25], v[164:167], v[180:183], v[22:25]
	v_mfma_f32_16x16x32_bf16 v[30:33], v[152:155], v[176:179], v[30:33]
	v_mfma_f32_16x16x32_bf16 v[30:33], v[156:159], v[180:183], v[30:33]
	v_mfma_f32_16x16x32_bf16 v[50:53], v[142:145], v[176:179], v[50:53]
	v_mfma_f32_16x16x32_bf16 v[50:53], v[148:151], v[180:183], v[50:53]
	v_mfma_f32_16x16x32_bf16 v[54:57], v[134:137], v[176:179], v[54:57]
	v_mfma_f32_16x16x32_bf16 v[54:57], v[138:141], v[180:183], v[54:57]
	v_mfma_f32_16x16x32_bf16 v[42:45], v[134:137], v[184:187], v[42:45]
	v_mfma_f32_16x16x32_bf16 v[42:45], v[138:141], v[188:191], v[42:45]
	v_mfma_f32_16x16x32_bf16 v[34:37], v[142:145], v[184:187], v[34:37]
	v_mfma_f32_16x16x32_bf16 v[34:37], v[148:151], v[188:191], v[34:37]
	v_mfma_f32_16x16x32_bf16 v[14:17], v[152:155], v[184:187], v[14:17]
	v_mfma_f32_16x16x32_bf16 v[14:17], v[156:159], v[188:191], v[14:17]
	v_mfma_f32_16x16x32_bf16 v[10:13], v[160:163], v[184:187], v[10:13]
	v_mfma_f32_16x16x32_bf16 v[10:13], v[164:167], v[188:191], v[10:13]
	v_mfma_f32_16x16x32_bf16 v[2:5], v[160:163], v[192:195], v[2:5]
	v_mfma_f32_16x16x32_bf16 v[2:5], v[164:167], v[196:199], v[2:5]
	v_mfma_f32_16x16x32_bf16 v[6:9], v[152:155], v[192:195], v[6:9]
	v_mfma_f32_16x16x32_bf16 v[6:9], v[156:159], v[196:199], v[6:9]
	v_mfma_f32_16x16x32_bf16 v[18:21], v[142:145], v[192:195], v[18:21]
	v_mfma_f32_16x16x32_bf16 v[18:21], v[148:151], v[196:199], v[18:21]
	v_mfma_f32_16x16x32_bf16 v[26:29], v[134:137], v[192:195], v[26:29]
	v_mfma_f32_16x16x32_bf16 v[26:29], v[138:141], v[196:199], v[26:29]
	s_setprio 0
	s_barrier
	s_add_i32 s79, s79, 2
	s_addk_i32 s77, 0x100
	s_addk_i32 s78, 0x100
	s_cmp_ge_i32 s79, s3
	s_cbranch_scc0 .LBB0_799
	v_pk_mul_f32 v[184:185], v[128:129], 0.5 op_sel_hi:[1,0]
	v_pk_mul_f32 v[186:187], v[126:127], 0.5 op_sel_hi:[1,0]
	v_pk_mul_f32 v[188:189], v[124:125], 0.5 op_sel_hi:[1,0]
	v_pk_mul_f32 v[190:191], v[122:123], 0.5 op_sel_hi:[1,0]
	v_pk_mul_f32 v[198:199], v[112:113], 0.5 op_sel_hi:[1,0]
	v_pk_mul_f32 v[196:197], v[110:111], 0.5 op_sel_hi:[1,0]
	v_pk_mul_f32 v[194:195], v[104:105], 0.5 op_sel_hi:[1,0]
	v_pk_mul_f32 v[192:193], v[102:103], 0.5 op_sel_hi:[1,0]
	v_pk_mul_f32 v[182:183], v[120:121], 0.5 op_sel_hi:[1,0]
	v_pk_mul_f32 v[180:181], v[118:119], 0.5 op_sel_hi:[1,0]
	v_pk_mul_f32 v[178:179], v[116:117], 0.5 op_sel_hi:[1,0]
	v_pk_mul_f32 v[176:177], v[114:115], 0.5 op_sel_hi:[1,0]
	v_pk_mul_f32 v[172:173], v[96:97], 0.5 op_sel_hi:[1,0]
	v_pk_mul_f32 v[170:171], v[94:95], 0.5 op_sel_hi:[1,0]
	v_pk_mul_f32 v[168:169], v[88:89], 0.5 op_sel_hi:[1,0]
	v_pk_mul_f32 v[166:167], v[86:87], 0.5 op_sel_hi:[1,0]
	v_pk_mul_f32 v[164:165], v[108:109], 0.5 op_sel_hi:[1,0]
	v_pk_mul_f32 v[162:163], v[106:107], 0.5 op_sel_hi:[1,0]
	v_pk_mul_f32 v[160:161], v[100:101], 0.5 op_sel_hi:[1,0]
	v_pk_mul_f32 v[158:159], v[98:99], 0.5 op_sel_hi:[1,0]
	v_pk_mul_f32 v[156:157], v[80:81], 0.5 op_sel_hi:[1,0]
	v_pk_mul_f32 v[154:155], v[78:79], 0.5 op_sel_hi:[1,0]
	v_pk_mul_f32 v[152:153], v[76:77], 0.5 op_sel_hi:[1,0]
	v_pk_mul_f32 v[150:151], v[74:75], 0.5 op_sel_hi:[1,0]
	v_pk_mul_f32 v[144:145], v[92:93], 0.5 op_sel_hi:[1,0]
	v_pk_mul_f32 v[142:143], v[90:91], 0.5 op_sel_hi:[1,0]
	v_pk_mul_f32 v[140:141], v[84:85], 0.5 op_sel_hi:[1,0]
	v_pk_mul_f32 v[138:139], v[82:83], 0.5 op_sel_hi:[1,0]
	v_pk_mul_f32 v[136:137], v[72:73], 0.5 op_sel_hi:[1,0]
	v_pk_mul_f32 v[134:135], v[70:71], 0.5 op_sel_hi:[1,0]
	v_pk_mul_f32 v[128:129], v[68:69], 0.5 op_sel_hi:[1,0]
	v_pk_mul_f32 v[126:127], v[66:67], 0.5 op_sel_hi:[1,0]
	v_pk_mul_f32 v[122:123], v[64:65], 0.5 op_sel_hi:[1,0]
	v_pk_mul_f32 v[120:121], v[62:63], 0.5 op_sel_hi:[1,0]
	v_pk_mul_f32 v[118:119], v[60:61], 0.5 op_sel_hi:[1,0]
	v_pk_mul_f32 v[116:117], v[58:59], 0.5 op_sel_hi:[1,0]
	v_pk_mul_f32 v[112:113], v[48:49], 0.5 op_sel_hi:[1,0]
	v_pk_mul_f32 v[110:111], v[46:47], 0.5 op_sel_hi:[1,0]
	v_pk_mul_f32 v[108:109], v[40:41], 0.5 op_sel_hi:[1,0]
	v_pk_mul_f32 v[106:107], v[38:39], 0.5 op_sel_hi:[1,0]
	v_pk_mul_f32 v[104:105], v[56:57], 0.5 op_sel_hi:[1,0]
	v_pk_mul_f32 v[102:103], v[54:55], 0.5 op_sel_hi:[1,0]
	v_pk_mul_f32 v[100:101], v[52:53], 0.5 op_sel_hi:[1,0]
	v_pk_mul_f32 v[98:99], v[50:51], 0.5 op_sel_hi:[1,0]
	v_pk_mul_f32 v[96:97], v[32:33], 0.5 op_sel_hi:[1,0]
	v_pk_mul_f32 v[94:95], v[30:31], 0.5 op_sel_hi:[1,0]
	v_pk_mul_f32 v[92:93], v[24:25], 0.5 op_sel_hi:[1,0]
	v_pk_mul_f32 v[90:91], v[22:23], 0.5 op_sel_hi:[1,0]
	v_pk_mul_f32 v[88:89], v[44:45], 0.5 op_sel_hi:[1,0]
	v_pk_mul_f32 v[86:87], v[42:43], 0.5 op_sel_hi:[1,0]
	v_pk_mul_f32 v[84:85], v[36:37], 0.5 op_sel_hi:[1,0]
	v_pk_mul_f32 v[82:83], v[34:35], 0.5 op_sel_hi:[1,0]
	v_pk_mul_f32 v[80:81], v[16:17], 0.5 op_sel_hi:[1,0]
	v_pk_mul_f32 v[78:79], v[14:15], 0.5 op_sel_hi:[1,0]
	v_pk_mul_f32 v[76:77], v[12:13], 0.5 op_sel_hi:[1,0]
	v_pk_mul_f32 v[74:75], v[10:11], 0.5 op_sel_hi:[1,0]
	v_pk_mul_f32 v[72:73], v[28:29], 0.5 op_sel_hi:[1,0]
	v_pk_mul_f32 v[70:71], v[26:27], 0.5 op_sel_hi:[1,0]
	v_pk_mul_f32 v[68:69], v[20:21], 0.5 op_sel_hi:[1,0]
	v_pk_mul_f32 v[66:67], v[18:19], 0.5 op_sel_hi:[1,0]
	v_pk_mul_f32 v[64:65], v[8:9], 0.5 op_sel_hi:[1,0]
	v_pk_mul_f32 v[62:63], v[6:7], 0.5 op_sel_hi:[1,0]
	v_pk_mul_f32 v[60:61], v[4:5], 0.5 op_sel_hi:[1,0]
	v_pk_mul_f32 v[58:59], v[2:3], 0.5 op_sel_hi:[1,0]
	s_and_b64 vcc, exec, s[38:39]
	s_cbranch_vccz .LBB0_802

.LBB0_892:
	ds_read_b128 v[130:133], v172
	ds_read_b128 v[134:137], v172 offset:1024
	ds_read_b128 v[148:151], v172 offset:2048
	ds_read_b128 v[152:155], v172 offset:3072
	ds_read_b128 v[156:159], v173
	ds_read_b128 v[160:163], v173 offset:1024
	ds_read_b128 v[164:167], v173 offset:2048
	ds_read_b128 v[180:183], v173 offset:3072
	s_add_i32 s18, s8, 0xffe80080
	s_cmp_eq_u32 s77, s52
	s_cselect_b32 s53, s6, s18
	s_cselect_b32 s58, s7, s9
	s_or_b32 s57, s53, 0x80
	s_add_i32 s18, s8, 0xfff80000
	s_mov_b32 m0, s78
	ds_read_b128 v[184:187], v174
	ds_read_b128 v[188:191], v174 offset:1024
	ds_read_b128 v[192:195], v174 offset:2048
	ds_read_b128 v[196:199], v174 offset:3072
	ds_read_b128 v[200:203], v174 offset:4096
	ds_read_b128 v[204:207], v174 offset:5120
	ds_read_b128 v[208:211], v174 offset:6144
	ds_read_b128 v[212:215], v174 offset:7168
	buffer_load_dwordx4 v170, s[12:15], s18 offen lds
	s_mov_b32 m0, s79
	s_nop 0
	buffer_load_dwordx4 v170, s[12:15], s8 offen lds
	s_waitcnt vmcnt(8) lgkmcnt(0)
	s_setprio 1
	v_mfma_f32_16x16x32_bf16 v[126:129], v[130:133], v[184:187], v[126:129]
	s_barrier
	v_mfma_f32_16x16x32_bf16 v[126:129], v[134:137], v[188:191], v[126:129]
	v_mfma_f32_16x16x32_bf16 v[118:121], v[148:151], v[184:187], v[118:121]
	v_mfma_f32_16x16x32_bf16 v[118:121], v[152:155], v[188:191], v[118:121]
	v_mfma_f32_16x16x32_bf16 v[122:125], v[156:159], v[184:187], v[122:125]
	v_mfma_f32_16x16x32_bf16 v[122:125], v[160:163], v[188:191], v[122:125]
	v_mfma_f32_16x16x32_bf16 v[114:117], v[164:167], v[184:187], v[114:117]
	v_mfma_f32_16x16x32_bf16 v[114:117], v[180:183], v[188:191], v[114:117]
	v_mfma_f32_16x16x32_bf16 v[98:101], v[164:167], v[192:195], v[98:101]
	v_mfma_f32_16x16x32_bf16 v[98:101], v[180:183], v[196:199], v[98:101]
	v_mfma_f32_16x16x32_bf16 v[106:109], v[156:159], v[192:195], v[106:109]
	v_mfma_f32_16x16x32_bf16 v[106:109], v[160:163], v[196:199], v[106:109]
	v_mfma_f32_16x16x32_bf16 v[102:105], v[148:151], v[192:195], v[102:105]
	v_mfma_f32_16x16x32_bf16 v[102:105], v[152:155], v[196:199], v[102:105]
	v_mfma_f32_16x16x32_bf16 v[110:113], v[130:133], v[192:195], v[110:113]
	v_mfma_f32_16x16x32_bf16 v[110:113], v[134:137], v[196:199], v[110:113]
	v_mfma_f32_16x16x32_bf16 v[94:97], v[130:133], v[200:203], v[94:97]
	v_mfma_f32_16x16x32_bf16 v[94:97], v[134:137], v[204:207], v[94:97]
	v_mfma_f32_16x16x32_bf16 v[90:93], v[148:151], v[200:203], v[90:93]
	v_mfma_f32_16x16x32_bf16 v[90:93], v[152:155], v[204:207], v[90:93]
	v_mfma_f32_16x16x32_bf16 v[86:89], v[156:159], v[200:203], v[86:89]
	v_mfma_f32_16x16x32_bf16 v[86:89], v[160:163], v[204:207], v[86:89]
	v_mfma_f32_16x16x32_bf16 v[82:85], v[164:167], v[200:203], v[82:85]
	v_mfma_f32_16x16x32_bf16 v[82:85], v[180:183], v[204:207], v[82:85]
	v_mfma_f32_16x16x32_bf16 v[66:69], v[164:167], v[208:211], v[66:69]
	v_mfma_f32_16x16x32_bf16 v[66:69], v[180:183], v[212:215], v[66:69]
	v_mfma_f32_16x16x32_bf16 v[74:77], v[156:159], v[208:211], v[74:77]
	v_mfma_f32_16x16x32_bf16 v[74:77], v[160:163], v[212:215], v[74:77]
	v_mfma_f32_16x16x32_bf16 v[70:73], v[148:151], v[208:211], v[70:73]
	v_mfma_f32_16x16x32_bf16 v[70:73], v[152:155], v[212:215], v[70:73]
	v_mfma_f32_16x16x32_bf16 v[78:81], v[130:133], v[208:211], v[78:81]
	v_mfma_f32_16x16x32_bf16 v[78:81], v[134:137], v[212:215], v[78:81]
	s_setprio 0
	s_barrier
	s_mov_b32 m0, s27
	s_mov_b32 s18, s14
	s_mov_b32 s19, s15
	ds_read_b128 v[184:187], v174 offset:16384
	ds_read_b128 v[188:191], v174 offset:17408
	ds_read_b128 v[192:195], v174 offset:18432
	ds_read_b128 v[196:199], v174 offset:19456
	ds_read_b128 v[200:203], v174 offset:20480
	ds_read_b128 v[204:207], v174 offset:21504
	ds_read_b128 v[208:211], v174 offset:22528
	ds_read_b128 v[212:215], v174 offset:23552
	buffer_load_dwordx4 v171, s[16:19], s58 offen lds
	s_mov_b32 m0, s60
	s_add_i32 s59, s58, 0x80000
	buffer_load_dwordx4 v171, s[16:19], s59 offen lds
	s_mov_b32 m0, s61
	s_add_i32 s59, s58, 0x100000
	buffer_load_dwordx4 v171, s[16:19], s59 offen lds
	s_mov_b32 m0, s62
	s_add_i32 s59, s58, 0x180000
	buffer_load_dwordx4 v171, s[16:19], s59 offen lds
	s_mov_b32 m0, s25
	s_add_i32 s59, s53, 0x80000
	buffer_load_dwordx4 v170, s[12:15], s53 offen lds
	s_mov_b32 m0, s63
	s_nop 0
	buffer_load_dwordx4 v170, s[12:15], s59 offen lds
	s_waitcnt vmcnt(8) lgkmcnt(0)
	s_setprio 1
	v_mfma_f32_16x16x32_bf16 v[62:65], v[130:133], v[184:187], v[62:65]
	s_barrier
	v_mfma_f32_16x16x32_bf16 v[62:65], v[134:137], v[188:191], v[62:65]
	v_mfma_f32_16x16x32_bf16 v[54:57], v[148:151], v[184:187], v[54:57]
	v_mfma_f32_16x16x32_bf16 v[54:57], v[152:155], v[188:191], v[54:57]
	v_mfma_f32_16x16x32_bf16 v[58:61], v[156:159], v[184:187], v[58:61]
	v_mfma_f32_16x16x32_bf16 v[58:61], v[160:163], v[188:191], v[58:61]
	v_mfma_f32_16x16x32_bf16 v[50:53], v[164:167], v[184:187], v[50:53]
	v_mfma_f32_16x16x32_bf16 v[50:53], v[180:183], v[188:191], v[50:53]
	v_mfma_f32_16x16x32_bf16 v[34:37], v[164:167], v[192:195], v[34:37]
	v_mfma_f32_16x16x32_bf16 v[34:37], v[180:183], v[196:199], v[34:37]
	v_mfma_f32_16x16x32_bf16 v[42:45], v[156:159], v[192:195], v[42:45]
	v_mfma_f32_16x16x32_bf16 v[42:45], v[160:163], v[196:199], v[42:45]
	v_mfma_f32_16x16x32_bf16 v[38:41], v[148:151], v[192:195], v[38:41]
	v_mfma_f32_16x16x32_bf16 v[38:41], v[152:155], v[196:199], v[38:41]
	v_mfma_f32_16x16x32_bf16 v[46:49], v[130:133], v[192:195], v[46:49]
	v_mfma_f32_16x16x32_bf16 v[46:49], v[134:137], v[196:199], v[46:49]
	v_mfma_f32_16x16x32_bf16 v[30:33], v[130:133], v[200:203], v[30:33]
	v_mfma_f32_16x16x32_bf16 v[30:33], v[134:137], v[204:207], v[30:33]
	v_mfma_f32_16x16x32_bf16 v[22:25], v[148:151], v[200:203], v[22:25]
	v_mfma_f32_16x16x32_bf16 v[22:25], v[152:155], v[204:207], v[22:25]
	v_mfma_f32_16x16x32_bf16 v[26:29], v[156:159], v[200:203], v[26:29]
	v_mfma_f32_16x16x32_bf16 v[26:29], v[160:163], v[204:207], v[26:29]
	v_mfma_f32_16x16x32_bf16 v[18:21], v[164:167], v[200:203], v[18:21]
	v_mfma_f32_16x16x32_bf16 v[18:21], v[180:183], v[204:207], v[18:21]
	v_mfma_f32_16x16x32_bf16 v[2:5], v[164:167], v[208:211], v[2:5]
	v_mfma_f32_16x16x32_bf16 v[2:5], v[180:183], v[212:215], v[2:5]
	v_mfma_f32_16x16x32_bf16 v[10:13], v[156:159], v[208:211], v[10:13]
	v_mfma_f32_16x16x32_bf16 v[10:13], v[160:163], v[212:215], v[10:13]
	v_mfma_f32_16x16x32_bf16 v[6:9], v[148:151], v[208:211], v[6:9]
	v_mfma_f32_16x16x32_bf16 v[6:9], v[152:155], v[212:215], v[6:9]
	v_mfma_f32_16x16x32_bf16 v[14:17], v[130:133], v[208:211], v[14:17]
	v_mfma_f32_16x16x32_bf16 v[14:17], v[134:137], v[212:215], v[14:17]
	s_setprio 0
	s_barrier
	ds_read_b128 v[130:133], v175
	ds_read_b128 v[134:137], v175 offset:1024
	ds_read_b128 v[148:151], v175 offset:2048
	ds_read_b128 v[152:155], v175 offset:3072
	ds_read_b128 v[156:159], v176
	ds_read_b128 v[160:163], v176 offset:1024
	ds_read_b128 v[164:167], v176 offset:2048
	ds_read_b128 v[180:183], v176 offset:3072
	s_mov_b32 m0, s64
	s_add_i32 s59, s53, 0x100000
	ds_read_b128 v[184:187], v174 offset:32768
	ds_read_b128 v[188:191], v174 offset:33792
	ds_read_b128 v[192:195], v174 offset:34816
	ds_read_b128 v[196:199], v174 offset:35840
	ds_read_b128 v[200:203], v174 offset:36864
	ds_read_b128 v[204:207], v174 offset:37888
	ds_read_b128 v[208:211], v174 offset:38912
	ds_read_b128 v[212:215], v174 offset:39936
	buffer_load_dwordx4 v170, s[12:15], s59 offen lds
	s_mov_b32 m0, s65
	s_add_i32 s59, s53, 0x180000
	buffer_load_dwordx4 v170, s[12:15], s59 offen lds
	s_waitcnt vmcnt(8) lgkmcnt(0)
	s_setprio 1
	v_mfma_f32_16x16x32_bf16 v[126:129], v[130:133], v[184:187], v[126:129]
	s_barrier
	v_mfma_f32_16x16x32_bf16 v[126:129], v[134:137], v[188:191], v[126:129]
	v_mfma_f32_16x16x32_bf16 v[118:121], v[148:151], v[184:187], v[118:121]
	v_mfma_f32_16x16x32_bf16 v[118:121], v[152:155], v[188:191], v[118:121]
	v_mfma_f32_16x16x32_bf16 v[122:125], v[156:159], v[184:187], v[122:125]
	v_mfma_f32_16x16x32_bf16 v[122:125], v[160:163], v[188:191], v[122:125]
	v_mfma_f32_16x16x32_bf16 v[114:117], v[164:167], v[184:187], v[114:117]
	v_mfma_f32_16x16x32_bf16 v[114:117], v[180:183], v[188:191], v[114:117]
	v_mfma_f32_16x16x32_bf16 v[98:101], v[164:167], v[192:195], v[98:101]
	v_mfma_f32_16x16x32_bf16 v[98:101], v[180:183], v[196:199], v[98:101]
	v_mfma_f32_16x16x32_bf16 v[106:109], v[156:159], v[192:195], v[106:109]
	v_mfma_f32_16x16x32_bf16 v[106:109], v[160:163], v[196:199], v[106:109]
	v_mfma_f32_16x16x32_bf16 v[102:105], v[148:151], v[192:195], v[102:105]
	v_mfma_f32_16x16x32_bf16 v[102:105], v[152:155], v[196:199], v[102:105]
	v_mfma_f32_16x16x32_bf16 v[110:113], v[130:133], v[192:195], v[110:113]
	v_mfma_f32_16x16x32_bf16 v[110:113], v[134:137], v[196:199], v[110:113]
	v_mfma_f32_16x16x32_bf16 v[94:97], v[130:133], v[200:203], v[94:97]
	v_mfma_f32_16x16x32_bf16 v[94:97], v[134:137], v[204:207], v[94:97]
	v_mfma_f32_16x16x32_bf16 v[90:93], v[148:151], v[200:203], v[90:93]
	v_mfma_f32_16x16x32_bf16 v[90:93], v[152:155], v[204:207], v[90:93]
	v_mfma_f32_16x16x32_bf16 v[86:89], v[156:159], v[200:203], v[86:89]
	v_mfma_f32_16x16x32_bf16 v[86:89], v[160:163], v[204:207], v[86:89]
	v_mfma_f32_16x16x32_bf16 v[82:85], v[164:167], v[200:203], v[82:85]
	v_mfma_f32_16x16x32_bf16 v[82:85], v[180:183], v[204:207], v[82:85]
	v_mfma_f32_16x16x32_bf16 v[66:69], v[164:167], v[208:211], v[66:69]
	v_mfma_f32_16x16x32_bf16 v[66:69], v[180:183], v[212:215], v[66:69]
	v_mfma_f32_16x16x32_bf16 v[74:77], v[156:159], v[208:211], v[74:77]
	v_mfma_f32_16x16x32_bf16 v[74:77], v[160:163], v[212:215], v[74:77]
	v_mfma_f32_16x16x32_bf16 v[70:73], v[148:151], v[208:211], v[70:73]
	v_mfma_f32_16x16x32_bf16 v[70:73], v[152:155], v[212:215], v[70:73]
	v_mfma_f32_16x16x32_bf16 v[78:81], v[130:133], v[208:211], v[78:81]
	v_mfma_f32_16x16x32_bf16 v[78:81], v[134:137], v[212:215], v[78:81]
	s_setprio 0
	s_barrier
	s_mov_b32 m0, s70
	s_or_b32 s59, s58, 0x80
	ds_read_b128 v[184:187], v174 offset:49152
	ds_read_b128 v[188:191], v174 offset:50176
	ds_read_b128 v[192:195], v174 offset:51200
	ds_read_b128 v[196:199], v174 offset:52224
	ds_read_b128 v[200:203], v174 offset:53248
	ds_read_b128 v[204:207], v174 offset:54272
	ds_read_b128 v[208:211], v174 offset:55296
	ds_read_b128 v[212:215], v174 offset:56320
	buffer_load_dwordx4 v171, s[16:19], s59 offen lds
	s_add_i32 s59, s58, 0x80080
	s_mov_b32 m0, s71
	s_add_i32 s53, s53, 0x80080
	buffer_load_dwordx4 v171, s[16:19], s59 offen lds
	s_add_i32 s59, s58, 0x100080
	s_mov_b32 m0, s74
	s_add_i32 s58, s58, 0x180080
	buffer_load_dwordx4 v171, s[16:19], s59 offen lds
	s_mov_b32 m0, s75
	s_nop 0
	buffer_load_dwordx4 v171, s[16:19], s58 offen lds
	s_mov_b32 m0, s72
	s_nop 0
	buffer_load_dwordx4 v170, s[12:15], s57 offen lds
	s_mov_b32 m0, s73
	s_nop 0
	buffer_load_dwordx4 v170, s[12:15], s53 offen lds
	s_waitcnt vmcnt(8) lgkmcnt(0)
	s_setprio 1
	v_mfma_f32_16x16x32_bf16 v[62:65], v[130:133], v[184:187], v[62:65]
	s_barrier
	v_mfma_f32_16x16x32_bf16 v[62:65], v[134:137], v[188:191], v[62:65]
	v_mfma_f32_16x16x32_bf16 v[54:57], v[148:151], v[184:187], v[54:57]
	v_mfma_f32_16x16x32_bf16 v[54:57], v[152:155], v[188:191], v[54:57]
	v_mfma_f32_16x16x32_bf16 v[58:61], v[156:159], v[184:187], v[58:61]
	v_mfma_f32_16x16x32_bf16 v[58:61], v[160:163], v[188:191], v[58:61]
	v_mfma_f32_16x16x32_bf16 v[50:53], v[164:167], v[184:187], v[50:53]
	v_mfma_f32_16x16x32_bf16 v[50:53], v[180:183], v[188:191], v[50:53]
	v_mfma_f32_16x16x32_bf16 v[34:37], v[164:167], v[192:195], v[34:37]
	v_mfma_f32_16x16x32_bf16 v[34:37], v[180:183], v[196:199], v[34:37]
	v_mfma_f32_16x16x32_bf16 v[42:45], v[156:159], v[192:195], v[42:45]
	v_mfma_f32_16x16x32_bf16 v[42:45], v[160:163], v[196:199], v[42:45]
	v_mfma_f32_16x16x32_bf16 v[38:41], v[148:151], v[192:195], v[38:41]
	v_mfma_f32_16x16x32_bf16 v[38:41], v[152:155], v[196:199], v[38:41]
	v_mfma_f32_16x16x32_bf16 v[46:49], v[130:133], v[192:195], v[46:49]
	v_mfma_f32_16x16x32_bf16 v[46:49], v[134:137], v[196:199], v[46:49]
	v_mfma_f32_16x16x32_bf16 v[30:33], v[130:133], v[200:203], v[30:33]
	v_mfma_f32_16x16x32_bf16 v[30:33], v[134:137], v[204:207], v[30:33]
	v_mfma_f32_16x16x32_bf16 v[22:25], v[148:151], v[200:203], v[22:25]
	v_mfma_f32_16x16x32_bf16 v[22:25], v[152:155], v[204:207], v[22:25]
	v_mfma_f32_16x16x32_bf16 v[26:29], v[156:159], v[200:203], v[26:29]
	v_mfma_f32_16x16x32_bf16 v[26:29], v[160:163], v[204:207], v[26:29]
	v_mfma_f32_16x16x32_bf16 v[18:21], v[164:167], v[200:203], v[18:21]
	v_mfma_f32_16x16x32_bf16 v[18:21], v[180:183], v[204:207], v[18:21]
	v_mfma_f32_16x16x32_bf16 v[2:5], v[164:167], v[208:211], v[2:5]
	v_mfma_f32_16x16x32_bf16 v[2:5], v[180:183], v[212:215], v[2:5]
	v_mfma_f32_16x16x32_bf16 v[10:13], v[156:159], v[208:211], v[10:13]
	v_mfma_f32_16x16x32_bf16 v[10:13], v[160:163], v[212:215], v[10:13]
	v_mfma_f32_16x16x32_bf16 v[6:9], v[148:151], v[208:211], v[6:9]
	v_mfma_f32_16x16x32_bf16 v[6:9], v[152:155], v[212:215], v[6:9]
	v_mfma_f32_16x16x32_bf16 v[14:17], v[130:133], v[208:211], v[14:17]
	v_mfma_f32_16x16x32_bf16 v[14:17], v[134:137], v[212:215], v[14:17]
	s_setprio 0
	s_barrier
	s_add_i32 s52, s52, 2
	s_addk_i32 s8, 0x100
	s_addk_i32 s9, 0x100
	s_cmp_ge_i32 s52, s21
	s_cbranch_scc0 .LBB0_892
	s_and_b64 vcc, exec, s[48:49]
	s_cbranch_vccz .LBB0_895

.LBB0_1020:
	v_add_u32_e32 v142, 0x10000, v162
	v_add_u32_e32 v150, 0x14000, v162
	ds_read_b128 v[130:133], v142
	ds_read_b128 v[134:137], v142 offset:1024
	ds_read_b128 v[138:141], v142 offset:2048
	ds_read_b128 v[142:145], v142 offset:3072
	ds_read_b128 v[154:157], v150
	ds_read_b128 v[164:167], v150 offset:1024
	ds_read_b128 v[168:171], v150 offset:2048
	ds_read_b128 v[172:175], v150 offset:3072
	s_add_i32 s90, s6, 0x100
	s_add_i32 s7, s88, s6
	s_cmp_eq_u32 s81, s89
	s_cselect_b32 s91, 0, s90
	s_cselect_b32 s93, s87, s7
	s_add_i32 s91, s91, s70
	s_or_b32 s92, s91, 0x80
	s_add_i32 s6, s3, s6
	s_mov_b32 m0, s82
	s_add_i32 s7, s6, 0x20080
	ds_read_b128 v[176:179], v163
	ds_read_b128 v[180:183], v163 offset:1024
	ds_read_b128 v[184:187], v163 offset:2048
	ds_read_b128 v[188:191], v163 offset:3072
	ds_read_b128 v[192:195], v163 offset:4096
	ds_read_b128 v[196:199], v163 offset:5120
	ds_read_b128 v[200:203], v163 offset:6144
	ds_read_b128 v[204:207], v163 offset:7168
	buffer_load_dwordx4 v161, s[12:15], s7 offen lds
	s_mov_b32 m0, s83
	s_add_i32 s6, s6, 0x30080
	buffer_load_dwordx4 v161, s[12:15], s6 offen lds
	s_waitcnt vmcnt(8) lgkmcnt(0)
	s_setprio 1
	v_mfma_f32_16x16x32_bf16 v[126:129], v[130:133], v[176:179], v[126:129]
	s_barrier
	v_mfma_f32_16x16x32_bf16 v[126:129], v[134:137], v[180:183], v[126:129]
	v_mfma_f32_16x16x32_bf16 v[122:125], v[138:141], v[176:179], v[122:125]
	v_mfma_f32_16x16x32_bf16 v[122:125], v[142:145], v[180:183], v[122:125]
	v_mfma_f32_16x16x32_bf16 v[118:121], v[154:157], v[176:179], v[118:121]
	v_mfma_f32_16x16x32_bf16 v[118:121], v[164:167], v[180:183], v[118:121]
	v_mfma_f32_16x16x32_bf16 v[114:117], v[168:171], v[176:179], v[114:117]
	v_mfma_f32_16x16x32_bf16 v[114:117], v[172:175], v[180:183], v[114:117]
	v_mfma_f32_16x16x32_bf16 v[98:101], v[168:171], v[184:187], v[98:101]
	v_mfma_f32_16x16x32_bf16 v[98:101], v[172:175], v[188:191], v[98:101]
	v_mfma_f32_16x16x32_bf16 v[102:105], v[154:157], v[184:187], v[102:105]
	v_mfma_f32_16x16x32_bf16 v[102:105], v[164:167], v[188:191], v[102:105]
	v_mfma_f32_16x16x32_bf16 v[106:109], v[138:141], v[184:187], v[106:109]
	v_mfma_f32_16x16x32_bf16 v[106:109], v[142:145], v[188:191], v[106:109]
	v_mfma_f32_16x16x32_bf16 v[110:113], v[130:133], v[184:187], v[110:113]
	v_mfma_f32_16x16x32_bf16 v[110:113], v[134:137], v[188:191], v[110:113]
	v_mfma_f32_16x16x32_bf16 v[94:97], v[130:133], v[192:195], v[94:97]
	v_mfma_f32_16x16x32_bf16 v[94:97], v[134:137], v[196:199], v[94:97]
	v_mfma_f32_16x16x32_bf16 v[90:93], v[138:141], v[192:195], v[90:93]
	v_mfma_f32_16x16x32_bf16 v[90:93], v[142:145], v[196:199], v[90:93]
	v_mfma_f32_16x16x32_bf16 v[86:89], v[154:157], v[192:195], v[86:89]
	v_mfma_f32_16x16x32_bf16 v[86:89], v[164:167], v[196:199], v[86:89]
	v_mfma_f32_16x16x32_bf16 v[82:85], v[168:171], v[192:195], v[82:85]
	v_mfma_f32_16x16x32_bf16 v[82:85], v[172:175], v[196:199], v[82:85]
	v_mfma_f32_16x16x32_bf16 v[66:69], v[168:171], v[200:203], v[66:69]
	v_mfma_f32_16x16x32_bf16 v[66:69], v[172:175], v[204:207], v[66:69]
	v_mfma_f32_16x16x32_bf16 v[70:73], v[154:157], v[200:203], v[70:73]
	v_mfma_f32_16x16x32_bf16 v[70:73], v[164:167], v[204:207], v[70:73]
	v_mfma_f32_16x16x32_bf16 v[74:77], v[138:141], v[200:203], v[74:77]
	v_mfma_f32_16x16x32_bf16 v[74:77], v[142:145], v[204:207], v[74:77]
	v_mfma_f32_16x16x32_bf16 v[78:81], v[130:133], v[200:203], v[78:81]
	v_mfma_f32_16x16x32_bf16 v[78:81], v[134:137], v[204:207], v[78:81]
	s_setprio 0
	s_barrier
	s_mov_b32 m0, s66
	s_mov_b32 s6, s14
	s_mov_b32 s7, s15
	ds_read_b128 v[176:179], v163 offset:16384
	ds_read_b128 v[180:183], v163 offset:17408
	ds_read_b128 v[184:187], v163 offset:18432
	ds_read_b128 v[188:191], v163 offset:19456
	ds_read_b128 v[192:195], v163 offset:20480
	ds_read_b128 v[196:199], v163 offset:21504
	ds_read_b128 v[200:203], v163 offset:22528
	ds_read_b128 v[204:207], v163 offset:23552
	buffer_load_dwordx4 v160, s[4:7], s93 offen lds
	s_mov_b32 m0, s67
	s_add_i32 s94, s93, 0x10000
	buffer_load_dwordx4 v160, s[4:7], s94 offen lds
	s_mov_b32 m0, s68
	s_add_i32 s94, s93, 0x20000
	buffer_load_dwordx4 v160, s[4:7], s94 offen lds
	s_mov_b32 m0, s69
	s_add_i32 s94, s93, 0x30000
	buffer_load_dwordx4 v160, s[4:7], s94 offen lds
	s_mov_b32 m0, s65
	s_add_i32 s94, s91, 0x10000
	buffer_load_dwordx4 v161, s[12:15], s91 offen lds
	s_mov_b32 m0, s71
	s_nop 0
	buffer_load_dwordx4 v161, s[12:15], s94 offen lds
	s_waitcnt vmcnt(8) lgkmcnt(0)
	s_setprio 1
	v_mfma_f32_16x16x32_bf16 v[62:65], v[130:133], v[176:179], v[62:65]
	s_barrier
	v_mfma_f32_16x16x32_bf16 v[62:65], v[134:137], v[180:183], v[62:65]
	v_mfma_f32_16x16x32_bf16 v[58:61], v[138:141], v[176:179], v[58:61]
	v_mfma_f32_16x16x32_bf16 v[58:61], v[142:145], v[180:183], v[58:61]
	v_mfma_f32_16x16x32_bf16 v[54:57], v[154:157], v[176:179], v[54:57]
	v_mfma_f32_16x16x32_bf16 v[54:57], v[164:167], v[180:183], v[54:57]
	v_mfma_f32_16x16x32_bf16 v[50:53], v[168:171], v[176:179], v[50:53]
	v_mfma_f32_16x16x32_bf16 v[50:53], v[172:175], v[180:183], v[50:53]
	v_mfma_f32_16x16x32_bf16 v[34:37], v[168:171], v[184:187], v[34:37]
	v_mfma_f32_16x16x32_bf16 v[34:37], v[172:175], v[188:191], v[34:37]
	v_mfma_f32_16x16x32_bf16 v[38:41], v[154:157], v[184:187], v[38:41]
	v_mfma_f32_16x16x32_bf16 v[38:41], v[164:167], v[188:191], v[38:41]
	v_mfma_f32_16x16x32_bf16 v[42:45], v[138:141], v[184:187], v[42:45]
	v_mfma_f32_16x16x32_bf16 v[42:45], v[142:145], v[188:191], v[42:45]
	v_mfma_f32_16x16x32_bf16 v[46:49], v[130:133], v[184:187], v[46:49]
	v_mfma_f32_16x16x32_bf16 v[46:49], v[134:137], v[188:191], v[46:49]
	v_mfma_f32_16x16x32_bf16 v[30:33], v[130:133], v[192:195], v[30:33]
	v_mfma_f32_16x16x32_bf16 v[30:33], v[134:137], v[196:199], v[30:33]
	v_mfma_f32_16x16x32_bf16 v[26:29], v[138:141], v[192:195], v[26:29]
	v_mfma_f32_16x16x32_bf16 v[26:29], v[142:145], v[196:199], v[26:29]
	v_mfma_f32_16x16x32_bf16 v[22:25], v[154:157], v[192:195], v[22:25]
	v_mfma_f32_16x16x32_bf16 v[22:25], v[164:167], v[196:199], v[22:25]
	v_mfma_f32_16x16x32_bf16 v[18:21], v[168:171], v[192:195], v[18:21]
	v_mfma_f32_16x16x32_bf16 v[18:21], v[172:175], v[196:199], v[18:21]
	v_mfma_f32_16x16x32_bf16 v[2:5], v[168:171], v[200:203], v[2:5]
	v_mfma_f32_16x16x32_bf16 v[2:5], v[172:175], v[204:207], v[2:5]
	v_mfma_f32_16x16x32_bf16 v[6:9], v[154:157], v[200:203], v[6:9]
	v_mfma_f32_16x16x32_bf16 v[6:9], v[164:167], v[204:207], v[6:9]
	v_mfma_f32_16x16x32_bf16 v[10:13], v[138:141], v[200:203], v[10:13]
	v_mfma_f32_16x16x32_bf16 v[10:13], v[142:145], v[204:207], v[10:13]
	v_mfma_f32_16x16x32_bf16 v[14:17], v[130:133], v[200:203], v[14:17]
	v_mfma_f32_16x16x32_bf16 v[14:17], v[134:137], v[204:207], v[14:17]
	s_setprio 0
	s_barrier
	v_add_u32_e32 v142, 0x18000, v162
	v_add_u32_e32 v150, 0x1c000, v162
	ds_read_b128 v[130:133], v142
	ds_read_b128 v[134:137], v142 offset:1024
	ds_read_b128 v[138:141], v142 offset:2048
	ds_read_b128 v[142:145], v142 offset:3072
	ds_read_b128 v[154:157], v150
	ds_read_b128 v[164:167], v150 offset:1024
	ds_read_b128 v[168:171], v150 offset:2048
	ds_read_b128 v[172:175], v150 offset:3072
	s_mov_b32 m0, s72
	s_add_i32 s94, s91, 0x20000
	ds_read_b128 v[176:179], v163 offset:32768
	ds_read_b128 v[180:183], v163 offset:33792
	ds_read_b128 v[184:187], v163 offset:34816
	ds_read_b128 v[188:191], v163 offset:35840
	ds_read_b128 v[192:195], v163 offset:36864
	ds_read_b128 v[196:199], v163 offset:37888
	ds_read_b128 v[200:203], v163 offset:38912
	ds_read_b128 v[204:207], v163 offset:39936
	buffer_load_dwordx4 v161, s[12:15], s94 offen lds
	s_mov_b32 m0, s73
	s_add_i32 s94, s91, 0x30000
	buffer_load_dwordx4 v161, s[12:15], s94 offen lds
	s_waitcnt vmcnt(8) lgkmcnt(0)
	s_setprio 1
	v_mfma_f32_16x16x32_bf16 v[126:129], v[130:133], v[176:179], v[126:129]
	s_barrier
	v_mfma_f32_16x16x32_bf16 v[126:129], v[134:137], v[180:183], v[126:129]
	v_mfma_f32_16x16x32_bf16 v[122:125], v[138:141], v[176:179], v[122:125]
	v_mfma_f32_16x16x32_bf16 v[122:125], v[142:145], v[180:183], v[122:125]
	v_mfma_f32_16x16x32_bf16 v[118:121], v[154:157], v[176:179], v[118:121]
	v_mfma_f32_16x16x32_bf16 v[118:121], v[164:167], v[180:183], v[118:121]
	v_mfma_f32_16x16x32_bf16 v[114:117], v[168:171], v[176:179], v[114:117]
	v_mfma_f32_16x16x32_bf16 v[114:117], v[172:175], v[180:183], v[114:117]
	v_mfma_f32_16x16x32_bf16 v[98:101], v[168:171], v[184:187], v[98:101]
	v_mfma_f32_16x16x32_bf16 v[98:101], v[172:175], v[188:191], v[98:101]
	v_mfma_f32_16x16x32_bf16 v[102:105], v[154:157], v[184:187], v[102:105]
	v_mfma_f32_16x16x32_bf16 v[102:105], v[164:167], v[188:191], v[102:105]
	v_mfma_f32_16x16x32_bf16 v[106:109], v[138:141], v[184:187], v[106:109]
	v_mfma_f32_16x16x32_bf16 v[106:109], v[142:145], v[188:191], v[106:109]
	v_mfma_f32_16x16x32_bf16 v[110:113], v[130:133], v[184:187], v[110:113]
	v_mfma_f32_16x16x32_bf16 v[110:113], v[134:137], v[188:191], v[110:113]
	v_mfma_f32_16x16x32_bf16 v[94:97], v[130:133], v[192:195], v[94:97]
	v_mfma_f32_16x16x32_bf16 v[94:97], v[134:137], v[196:199], v[94:97]
	v_mfma_f32_16x16x32_bf16 v[90:93], v[138:141], v[192:195], v[90:93]
	v_mfma_f32_16x16x32_bf16 v[90:93], v[142:145], v[196:199], v[90:93]
	v_mfma_f32_16x16x32_bf16 v[86:89], v[154:157], v[192:195], v[86:89]
	v_mfma_f32_16x16x32_bf16 v[86:89], v[164:167], v[196:199], v[86:89]
	v_mfma_f32_16x16x32_bf16 v[82:85], v[168:171], v[192:195], v[82:85]
	v_mfma_f32_16x16x32_bf16 v[82:85], v[172:175], v[196:199], v[82:85]
	v_mfma_f32_16x16x32_bf16 v[66:69], v[168:171], v[200:203], v[66:69]
	v_mfma_f32_16x16x32_bf16 v[66:69], v[172:175], v[204:207], v[66:69]
	v_mfma_f32_16x16x32_bf16 v[70:73], v[154:157], v[200:203], v[70:73]
	v_mfma_f32_16x16x32_bf16 v[70:73], v[164:167], v[204:207], v[70:73]
	v_mfma_f32_16x16x32_bf16 v[74:77], v[138:141], v[200:203], v[74:77]
	v_mfma_f32_16x16x32_bf16 v[74:77], v[142:145], v[204:207], v[74:77]
	v_mfma_f32_16x16x32_bf16 v[78:81], v[130:133], v[200:203], v[78:81]
	v_mfma_f32_16x16x32_bf16 v[78:81], v[134:137], v[204:207], v[78:81]
	s_setprio 0
	s_barrier
	s_mov_b32 m0, s74
	s_or_b32 s94, s93, 0x80
	ds_read_b128 v[176:179], v163 offset:49152
	ds_read_b128 v[180:183], v163 offset:50176
	ds_read_b128 v[184:187], v163 offset:51200
	ds_read_b128 v[188:191], v163 offset:52224
	ds_read_b128 v[192:195], v163 offset:53248
	ds_read_b128 v[196:199], v163 offset:54272
	ds_read_b128 v[200:203], v163 offset:55296
	ds_read_b128 v[204:207], v163 offset:56320
	buffer_load_dwordx4 v160, s[4:7], s94 offen lds
	s_add_i32 s94, s93, 0x10080
	s_mov_b32 m0, s75
	s_add_i32 s91, s91, 0x10080
	buffer_load_dwordx4 v160, s[4:7], s94 offen lds
	s_add_i32 s94, s93, 0x20080
	s_mov_b32 m0, s78
	s_add_i32 s93, s93, 0x30080
	buffer_load_dwordx4 v160, s[4:7], s94 offen lds
	s_mov_b32 m0, s79
	s_nop 0
	buffer_load_dwordx4 v160, s[4:7], s93 offen lds
	s_mov_b32 m0, s76
	s_nop 0
	buffer_load_dwordx4 v161, s[12:15], s92 offen lds
	s_mov_b32 m0, s77
	s_nop 0
	buffer_load_dwordx4 v161, s[12:15], s91 offen lds
	s_waitcnt vmcnt(8) lgkmcnt(0)
	s_setprio 1
	v_mfma_f32_16x16x32_bf16 v[62:65], v[130:133], v[176:179], v[62:65]
	s_barrier
	v_mfma_f32_16x16x32_bf16 v[62:65], v[134:137], v[180:183], v[62:65]
	v_mfma_f32_16x16x32_bf16 v[58:61], v[138:141], v[176:179], v[58:61]
	v_mfma_f32_16x16x32_bf16 v[58:61], v[142:145], v[180:183], v[58:61]
	v_mfma_f32_16x16x32_bf16 v[54:57], v[154:157], v[176:179], v[54:57]
	v_mfma_f32_16x16x32_bf16 v[54:57], v[164:167], v[180:183], v[54:57]
	v_mfma_f32_16x16x32_bf16 v[50:53], v[168:171], v[176:179], v[50:53]
	v_mfma_f32_16x16x32_bf16 v[50:53], v[172:175], v[180:183], v[50:53]
	v_mfma_f32_16x16x32_bf16 v[34:37], v[168:171], v[184:187], v[34:37]
	v_mfma_f32_16x16x32_bf16 v[34:37], v[172:175], v[188:191], v[34:37]
	v_mfma_f32_16x16x32_bf16 v[38:41], v[154:157], v[184:187], v[38:41]
	v_mfma_f32_16x16x32_bf16 v[38:41], v[164:167], v[188:191], v[38:41]
	v_mfma_f32_16x16x32_bf16 v[42:45], v[138:141], v[184:187], v[42:45]
	v_mfma_f32_16x16x32_bf16 v[42:45], v[142:145], v[188:191], v[42:45]
	v_mfma_f32_16x16x32_bf16 v[46:49], v[130:133], v[184:187], v[46:49]
	v_mfma_f32_16x16x32_bf16 v[46:49], v[134:137], v[188:191], v[46:49]
	v_mfma_f32_16x16x32_bf16 v[30:33], v[130:133], v[192:195], v[30:33]
	v_mfma_f32_16x16x32_bf16 v[30:33], v[134:137], v[196:199], v[30:33]
	v_mfma_f32_16x16x32_bf16 v[26:29], v[138:141], v[192:195], v[26:29]
	v_mfma_f32_16x16x32_bf16 v[26:29], v[142:145], v[196:199], v[26:29]
	v_mfma_f32_16x16x32_bf16 v[22:25], v[154:157], v[192:195], v[22:25]
	v_mfma_f32_16x16x32_bf16 v[22:25], v[164:167], v[196:199], v[22:25]
	v_mfma_f32_16x16x32_bf16 v[18:21], v[168:171], v[192:195], v[18:21]
	v_mfma_f32_16x16x32_bf16 v[18:21], v[172:175], v[196:199], v[18:21]
	v_mfma_f32_16x16x32_bf16 v[2:5], v[168:171], v[200:203], v[2:5]
	v_mfma_f32_16x16x32_bf16 v[2:5], v[172:175], v[204:207], v[2:5]
	v_mfma_f32_16x16x32_bf16 v[6:9], v[154:157], v[200:203], v[6:9]
	v_mfma_f32_16x16x32_bf16 v[6:9], v[164:167], v[204:207], v[6:9]
	v_mfma_f32_16x16x32_bf16 v[10:13], v[138:141], v[200:203], v[10:13]
	v_mfma_f32_16x16x32_bf16 v[10:13], v[142:145], v[204:207], v[10:13]
	v_mfma_f32_16x16x32_bf16 v[14:17], v[130:133], v[200:203], v[14:17]
	v_mfma_f32_16x16x32_bf16 v[14:17], v[134:137], v[204:207], v[14:17]
	s_setprio 0
	s_barrier
	s_add_i32 s89, s89, 2
	s_cmp_ge_i32 s89, s63
	s_mov_b32 s6, s90
	s_cbranch_scc0 .LBB0_1020
	s_and_b64 vcc, exec, s[54:55]
	s_cbranch_vccz .LBB0_1023

.LBB0_1035:
	ds_read_b128 v[140:143], v134
	ds_read_b128 v[148:151], v134 offset:1024
	ds_read_b128 v[152:155], v134 offset:2048
	ds_read_b128 v[156:159], v134 offset:3072
	ds_read_b128 v[160:163], v135
	ds_read_b128 v[164:167], v135 offset:1024
	ds_read_b128 v[168:171], v135 offset:2048
	ds_read_b128 v[172:175], v135 offset:3072
	s_add_i32 s73, s70, 0xfffb8080
	s_cmp_eq_u32 s53, s72
	s_cselect_b32 s73, s68, s73
	s_cselect_b32 s75, s69, s71
	s_add_i32 s74, s73, 0x80
	s_add_i32 s76, s70, 0xfffe8000
	s_mov_b32 m0, s54
	ds_read_b128 v[176:179], v136
	ds_read_b128 v[180:183], v136 offset:1024
	ds_read_b128 v[184:187], v136 offset:2048
	ds_read_b128 v[188:191], v136 offset:3072
	ds_read_b128 v[192:195], v136 offset:4096
	ds_read_b128 v[196:199], v136 offset:5120
	ds_read_b128 v[200:203], v136 offset:6144
	ds_read_b128 v[204:207], v136 offset:7168
	buffer_load_dwordx4 v132, s[12:15], s76 offen lds
	s_mov_b32 m0, s55
	s_nop 0
	buffer_load_dwordx4 v132, s[12:15], s70 offen lds
	s_waitcnt vmcnt(8) lgkmcnt(0)
	s_setprio 1
	v_mfma_f32_16x16x32_bf16 v[126:129], v[140:143], v[176:179], v[126:129]
	s_barrier
	v_mfma_f32_16x16x32_bf16 v[126:129], v[148:151], v[180:183], v[126:129]
	v_mfma_f32_16x16x32_bf16 v[122:125], v[152:155], v[176:179], v[122:125]
	v_mfma_f32_16x16x32_bf16 v[122:125], v[156:159], v[180:183], v[122:125]
	v_mfma_f32_16x16x32_bf16 v[118:121], v[160:163], v[176:179], v[118:121]
	v_mfma_f32_16x16x32_bf16 v[118:121], v[164:167], v[180:183], v[118:121]
	v_mfma_f32_16x16x32_bf16 v[114:117], v[168:171], v[176:179], v[114:117]
	v_mfma_f32_16x16x32_bf16 v[114:117], v[172:175], v[180:183], v[114:117]
	v_mfma_f32_16x16x32_bf16 v[98:101], v[168:171], v[184:187], v[98:101]
	v_mfma_f32_16x16x32_bf16 v[98:101], v[172:175], v[188:191], v[98:101]
	v_mfma_f32_16x16x32_bf16 v[102:105], v[160:163], v[184:187], v[102:105]
	v_mfma_f32_16x16x32_bf16 v[102:105], v[164:167], v[188:191], v[102:105]
	v_mfma_f32_16x16x32_bf16 v[106:109], v[152:155], v[184:187], v[106:109]
	v_mfma_f32_16x16x32_bf16 v[106:109], v[156:159], v[188:191], v[106:109]
	v_mfma_f32_16x16x32_bf16 v[110:113], v[140:143], v[184:187], v[110:113]
	v_mfma_f32_16x16x32_bf16 v[110:113], v[148:151], v[188:191], v[110:113]
	v_mfma_f32_16x16x32_bf16 v[94:97], v[140:143], v[192:195], v[94:97]
	v_mfma_f32_16x16x32_bf16 v[94:97], v[148:151], v[196:199], v[94:97]
	v_mfma_f32_16x16x32_bf16 v[90:93], v[152:155], v[192:195], v[90:93]
	v_mfma_f32_16x16x32_bf16 v[90:93], v[156:159], v[196:199], v[90:93]
	v_mfma_f32_16x16x32_bf16 v[86:89], v[160:163], v[192:195], v[86:89]
	v_mfma_f32_16x16x32_bf16 v[86:89], v[164:167], v[196:199], v[86:89]
	v_mfma_f32_16x16x32_bf16 v[82:85], v[168:171], v[192:195], v[82:85]
	v_mfma_f32_16x16x32_bf16 v[82:85], v[172:175], v[196:199], v[82:85]
	v_mfma_f32_16x16x32_bf16 v[66:69], v[168:171], v[200:203], v[66:69]
	v_mfma_f32_16x16x32_bf16 v[66:69], v[172:175], v[204:207], v[66:69]
	v_mfma_f32_16x16x32_bf16 v[70:73], v[160:163], v[200:203], v[70:73]
	v_mfma_f32_16x16x32_bf16 v[70:73], v[164:167], v[204:207], v[70:73]
	v_mfma_f32_16x16x32_bf16 v[74:77], v[152:155], v[200:203], v[74:77]
	v_mfma_f32_16x16x32_bf16 v[74:77], v[156:159], v[204:207], v[74:77]
	v_mfma_f32_16x16x32_bf16 v[78:81], v[140:143], v[200:203], v[78:81]
	v_mfma_f32_16x16x32_bf16 v[78:81], v[148:151], v[204:207], v[78:81]
	s_setprio 0
	s_barrier
	s_mov_b32 m0, s30
	ds_read_b128 v[176:179], v136 offset:16384
	ds_read_b128 v[180:183], v136 offset:17408
	ds_read_b128 v[184:187], v136 offset:18432
	ds_read_b128 v[188:191], v136 offset:19456
	ds_read_b128 v[192:195], v136 offset:20480
	ds_read_b128 v[196:199], v136 offset:21504
	ds_read_b128 v[200:203], v136 offset:22528
	ds_read_b128 v[204:207], v136 offset:23552
	buffer_load_dwordx4 v133, s[16:19], s75 offen lds
	s_mov_b32 m0, s31
	s_add_i32 s76, s75, 0x200000
	buffer_load_dwordx4 v133, s[16:19], s76 offen lds
	s_mov_b32 m0, s35
	s_add_i32 s76, s75, 0x400000
	buffer_load_dwordx4 v133, s[16:19], s76 offen lds
	s_mov_b32 m0, s42
	s_add_i32 s76, s75, 0x600000
	buffer_load_dwordx4 v133, s[16:19], s76 offen lds
	s_mov_b32 m0, s27
	s_add_i32 s76, s73, 0x18000
	buffer_load_dwordx4 v132, s[12:15], s73 offen lds
	s_mov_b32 m0, s43
	s_nop 0
	buffer_load_dwordx4 v132, s[12:15], s76 offen lds
	s_waitcnt vmcnt(8) lgkmcnt(0)
	s_setprio 1
	v_mfma_f32_16x16x32_bf16 v[62:65], v[140:143], v[176:179], v[62:65]
	s_barrier
	v_mfma_f32_16x16x32_bf16 v[62:65], v[148:151], v[180:183], v[62:65]
	v_mfma_f32_16x16x32_bf16 v[58:61], v[152:155], v[176:179], v[58:61]
	v_mfma_f32_16x16x32_bf16 v[58:61], v[156:159], v[180:183], v[58:61]
	v_mfma_f32_16x16x32_bf16 v[54:57], v[160:163], v[176:179], v[54:57]
	v_mfma_f32_16x16x32_bf16 v[54:57], v[164:167], v[180:183], v[54:57]
	v_mfma_f32_16x16x32_bf16 v[50:53], v[168:171], v[176:179], v[50:53]
	v_mfma_f32_16x16x32_bf16 v[50:53], v[172:175], v[180:183], v[50:53]
	v_mfma_f32_16x16x32_bf16 v[34:37], v[168:171], v[184:187], v[34:37]
	v_mfma_f32_16x16x32_bf16 v[34:37], v[172:175], v[188:191], v[34:37]
	v_mfma_f32_16x16x32_bf16 v[38:41], v[160:163], v[184:187], v[38:41]
	v_mfma_f32_16x16x32_bf16 v[38:41], v[164:167], v[188:191], v[38:41]
	v_mfma_f32_16x16x32_bf16 v[42:45], v[152:155], v[184:187], v[42:45]
	v_mfma_f32_16x16x32_bf16 v[42:45], v[156:159], v[188:191], v[42:45]
	v_mfma_f32_16x16x32_bf16 v[46:49], v[140:143], v[184:187], v[46:49]
	v_mfma_f32_16x16x32_bf16 v[46:49], v[148:151], v[188:191], v[46:49]
	v_mfma_f32_16x16x32_bf16 v[30:33], v[140:143], v[192:195], v[30:33]
	v_mfma_f32_16x16x32_bf16 v[30:33], v[148:151], v[196:199], v[30:33]
	v_mfma_f32_16x16x32_bf16 v[26:29], v[152:155], v[192:195], v[26:29]
	v_mfma_f32_16x16x32_bf16 v[26:29], v[156:159], v[196:199], v[26:29]
	v_mfma_f32_16x16x32_bf16 v[22:25], v[160:163], v[192:195], v[22:25]
	v_mfma_f32_16x16x32_bf16 v[22:25], v[164:167], v[196:199], v[22:25]
	v_mfma_f32_16x16x32_bf16 v[18:21], v[168:171], v[192:195], v[18:21]
	v_mfma_f32_16x16x32_bf16 v[18:21], v[172:175], v[196:199], v[18:21]
	v_mfma_f32_16x16x32_bf16 v[2:5], v[168:171], v[200:203], v[2:5]
	v_mfma_f32_16x16x32_bf16 v[2:5], v[172:175], v[204:207], v[2:5]
	v_mfma_f32_16x16x32_bf16 v[6:9], v[160:163], v[200:203], v[6:9]
	v_mfma_f32_16x16x32_bf16 v[6:9], v[164:167], v[204:207], v[6:9]
	v_mfma_f32_16x16x32_bf16 v[10:13], v[152:155], v[200:203], v[10:13]
	v_mfma_f32_16x16x32_bf16 v[10:13], v[156:159], v[204:207], v[10:13]
	v_mfma_f32_16x16x32_bf16 v[14:17], v[140:143], v[200:203], v[14:17]
	v_mfma_f32_16x16x32_bf16 v[14:17], v[148:151], v[204:207], v[14:17]
	s_setprio 0
	s_barrier
	ds_read_b128 v[140:143], v137
	ds_read_b128 v[148:151], v137 offset:1024
	ds_read_b128 v[152:155], v137 offset:2048
	ds_read_b128 v[156:159], v137 offset:3072
	ds_read_b128 v[160:163], v138
	ds_read_b128 v[164:167], v138 offset:1024
	ds_read_b128 v[168:171], v138 offset:2048
	ds_read_b128 v[172:175], v138 offset:3072
	s_mov_b32 m0, s44
	s_add_i32 s76, s73, 0x30000
	ds_read_b128 v[176:179], v136 offset:32768
	ds_read_b128 v[180:183], v136 offset:33792
	ds_read_b128 v[184:187], v136 offset:34816
	ds_read_b128 v[188:191], v136 offset:35840
	ds_read_b128 v[192:195], v136 offset:36864
	ds_read_b128 v[196:199], v136 offset:37888
	ds_read_b128 v[200:203], v136 offset:38912
	ds_read_b128 v[204:207], v136 offset:39936
	buffer_load_dwordx4 v132, s[12:15], s76 offen lds
	s_mov_b32 m0, s45
	s_add_i32 s76, s73, 0x48000
	buffer_load_dwordx4 v132, s[12:15], s76 offen lds
	s_waitcnt vmcnt(8) lgkmcnt(0)
	s_setprio 1
	v_mfma_f32_16x16x32_bf16 v[126:129], v[140:143], v[176:179], v[126:129]
	s_barrier
	v_mfma_f32_16x16x32_bf16 v[126:129], v[148:151], v[180:183], v[126:129]
	v_mfma_f32_16x16x32_bf16 v[122:125], v[152:155], v[176:179], v[122:125]
	v_mfma_f32_16x16x32_bf16 v[122:125], v[156:159], v[180:183], v[122:125]
	v_mfma_f32_16x16x32_bf16 v[118:121], v[160:163], v[176:179], v[118:121]
	v_mfma_f32_16x16x32_bf16 v[118:121], v[164:167], v[180:183], v[118:121]
	v_mfma_f32_16x16x32_bf16 v[114:117], v[168:171], v[176:179], v[114:117]
	v_mfma_f32_16x16x32_bf16 v[114:117], v[172:175], v[180:183], v[114:117]
	v_mfma_f32_16x16x32_bf16 v[98:101], v[168:171], v[184:187], v[98:101]
	v_mfma_f32_16x16x32_bf16 v[98:101], v[172:175], v[188:191], v[98:101]
	v_mfma_f32_16x16x32_bf16 v[102:105], v[160:163], v[184:187], v[102:105]
	v_mfma_f32_16x16x32_bf16 v[102:105], v[164:167], v[188:191], v[102:105]
	v_mfma_f32_16x16x32_bf16 v[106:109], v[152:155], v[184:187], v[106:109]
	v_mfma_f32_16x16x32_bf16 v[106:109], v[156:159], v[188:191], v[106:109]
	v_mfma_f32_16x16x32_bf16 v[110:113], v[140:143], v[184:187], v[110:113]
	v_mfma_f32_16x16x32_bf16 v[110:113], v[148:151], v[188:191], v[110:113]
	v_mfma_f32_16x16x32_bf16 v[94:97], v[140:143], v[192:195], v[94:97]
	v_mfma_f32_16x16x32_bf16 v[94:97], v[148:151], v[196:199], v[94:97]
	v_mfma_f32_16x16x32_bf16 v[90:93], v[152:155], v[192:195], v[90:93]
	v_mfma_f32_16x16x32_bf16 v[90:93], v[156:159], v[196:199], v[90:93]
	v_mfma_f32_16x16x32_bf16 v[86:89], v[160:163], v[192:195], v[86:89]
	v_mfma_f32_16x16x32_bf16 v[86:89], v[164:167], v[196:199], v[86:89]
	v_mfma_f32_16x16x32_bf16 v[82:85], v[168:171], v[192:195], v[82:85]
	v_mfma_f32_16x16x32_bf16 v[82:85], v[172:175], v[196:199], v[82:85]
	v_mfma_f32_16x16x32_bf16 v[66:69], v[168:171], v[200:203], v[66:69]
	v_mfma_f32_16x16x32_bf16 v[66:69], v[172:175], v[204:207], v[66:69]
	v_mfma_f32_16x16x32_bf16 v[70:73], v[160:163], v[200:203], v[70:73]
	v_mfma_f32_16x16x32_bf16 v[70:73], v[164:167], v[204:207], v[70:73]
	v_mfma_f32_16x16x32_bf16 v[74:77], v[152:155], v[200:203], v[74:77]
	v_mfma_f32_16x16x32_bf16 v[74:77], v[156:159], v[204:207], v[74:77]
	v_mfma_f32_16x16x32_bf16 v[78:81], v[140:143], v[200:203], v[78:81]
	v_mfma_f32_16x16x32_bf16 v[78:81], v[148:151], v[204:207], v[78:81]
	s_setprio 0
	s_barrier
	s_mov_b32 m0, s46
	s_add_i32 s76, s75, 0x80
	ds_read_b128 v[176:179], v136 offset:49152
	ds_read_b128 v[180:183], v136 offset:50176
	ds_read_b128 v[184:187], v136 offset:51200
	ds_read_b128 v[188:191], v136 offset:52224
	ds_read_b128 v[192:195], v136 offset:53248
	ds_read_b128 v[196:199], v136 offset:54272
	ds_read_b128 v[200:203], v136 offset:55296
	ds_read_b128 v[204:207], v136 offset:56320
	buffer_load_dwordx4 v133, s[16:19], s76 offen lds
	s_add_i32 s76, s75, 0x200080
	s_mov_b32 m0, s47
	s_add_i32 s73, s73, 0x18080
	buffer_load_dwordx4 v133, s[16:19], s76 offen lds
	s_add_i32 s76, s75, 0x400080
	s_mov_b32 m0, s50
	s_add_i32 s75, s75, 0x600080
	buffer_load_dwordx4 v133, s[16:19], s76 offen lds
	s_mov_b32 m0, s51
	s_nop 0
	buffer_load_dwordx4 v133, s[16:19], s75 offen lds
	s_mov_b32 m0, s48
	s_nop 0
	buffer_load_dwordx4 v132, s[12:15], s74 offen lds
	s_mov_b32 m0, s49
	s_nop 0
	buffer_load_dwordx4 v132, s[12:15], s73 offen lds
	s_waitcnt vmcnt(8) lgkmcnt(0)
	s_setprio 1
	v_mfma_f32_16x16x32_bf16 v[62:65], v[140:143], v[176:179], v[62:65]
	s_barrier
	v_mfma_f32_16x16x32_bf16 v[62:65], v[148:151], v[180:183], v[62:65]
	v_mfma_f32_16x16x32_bf16 v[58:61], v[152:155], v[176:179], v[58:61]
	v_mfma_f32_16x16x32_bf16 v[58:61], v[156:159], v[180:183], v[58:61]
	v_mfma_f32_16x16x32_bf16 v[54:57], v[160:163], v[176:179], v[54:57]
	v_mfma_f32_16x16x32_bf16 v[54:57], v[164:167], v[180:183], v[54:57]
	v_mfma_f32_16x16x32_bf16 v[50:53], v[168:171], v[176:179], v[50:53]
	v_mfma_f32_16x16x32_bf16 v[50:53], v[172:175], v[180:183], v[50:53]
	v_mfma_f32_16x16x32_bf16 v[34:37], v[168:171], v[184:187], v[34:37]
	v_mfma_f32_16x16x32_bf16 v[34:37], v[172:175], v[188:191], v[34:37]
	v_mfma_f32_16x16x32_bf16 v[38:41], v[160:163], v[184:187], v[38:41]
	v_mfma_f32_16x16x32_bf16 v[38:41], v[164:167], v[188:191], v[38:41]
	v_mfma_f32_16x16x32_bf16 v[42:45], v[152:155], v[184:187], v[42:45]
	v_mfma_f32_16x16x32_bf16 v[42:45], v[156:159], v[188:191], v[42:45]
	v_mfma_f32_16x16x32_bf16 v[46:49], v[140:143], v[184:187], v[46:49]
	v_mfma_f32_16x16x32_bf16 v[46:49], v[148:151], v[188:191], v[46:49]
	v_mfma_f32_16x16x32_bf16 v[30:33], v[140:143], v[192:195], v[30:33]
	v_mfma_f32_16x16x32_bf16 v[30:33], v[148:151], v[196:199], v[30:33]
	v_mfma_f32_16x16x32_bf16 v[26:29], v[152:155], v[192:195], v[26:29]
	v_mfma_f32_16x16x32_bf16 v[26:29], v[156:159], v[196:199], v[26:29]
	v_mfma_f32_16x16x32_bf16 v[22:25], v[160:163], v[192:195], v[22:25]
	v_mfma_f32_16x16x32_bf16 v[22:25], v[164:167], v[196:199], v[22:25]
	v_mfma_f32_16x16x32_bf16 v[18:21], v[168:171], v[192:195], v[18:21]
	v_mfma_f32_16x16x32_bf16 v[18:21], v[172:175], v[196:199], v[18:21]
	v_mfma_f32_16x16x32_bf16 v[2:5], v[168:171], v[200:203], v[2:5]
	v_mfma_f32_16x16x32_bf16 v[2:5], v[172:175], v[204:207], v[2:5]
	v_mfma_f32_16x16x32_bf16 v[6:9], v[160:163], v[200:203], v[6:9]
	v_mfma_f32_16x16x32_bf16 v[6:9], v[164:167], v[204:207], v[6:9]
	v_mfma_f32_16x16x32_bf16 v[10:13], v[152:155], v[200:203], v[10:13]
	v_mfma_f32_16x16x32_bf16 v[10:13], v[156:159], v[204:207], v[10:13]
	v_mfma_f32_16x16x32_bf16 v[14:17], v[140:143], v[200:203], v[14:17]
	v_mfma_f32_16x16x32_bf16 v[14:17], v[148:151], v[204:207], v[14:17]
	s_setprio 0
	s_barrier
	s_add_i32 s72, s72, 2
	s_addk_i32 s70, 0x100
	s_addk_i32 s71, 0x100
	s_cmp_ge_i32 s72, s21
	s_cbranch_scc0 .LBB0_1035

.LBB0_1050:
	ds_read_b128 v[132:135], v142
	ds_read_b128 v[136:139], v142 offset:1024
	ds_read_b128 v[148:151], v142 offset:2048
	ds_read_b128 v[152:155], v142 offset:3072
	ds_read_b128 v[156:159], v143
	ds_read_b128 v[160:163], v143 offset:1024
	ds_read_b128 v[164:167], v143 offset:2048
	ds_read_b128 v[168:171], v143 offset:3072
	s_add_i32 s18, s61, 0xfff40080
	s_cmp_eq_u32 s54, s62
	s_cselect_b32 s64, s35, s18
	s_add_i32 s63, s64, 0x80
	s_add_i32 s18, s61, 0xfffc0000
	s_mov_b32 m0, s55
	ds_read_b128 v[172:175], v144
	ds_read_b128 v[176:179], v144 offset:1024
	ds_read_b128 v[180:183], v144 offset:2048
	ds_read_b128 v[184:187], v144 offset:3072
	ds_read_b128 v[188:191], v144 offset:4096
	ds_read_b128 v[192:195], v144 offset:5120
	ds_read_b128 v[196:199], v144 offset:6144
	ds_read_b128 v[200:203], v144 offset:7168
	buffer_load_dwordx4 v140, s[12:15], s18 offen lds
	s_mov_b32 m0, s56
	s_nop 0
	buffer_load_dwordx4 v140, s[12:15], s61 offen lds
	s_waitcnt vmcnt(8) lgkmcnt(0)
	s_setprio 1
	v_mfma_f32_16x16x32_bf16 v[126:129], v[132:135], v[172:175], v[126:129]
	s_barrier
	v_mfma_f32_16x16x32_bf16 v[126:129], v[136:139], v[176:179], v[126:129]
	v_mfma_f32_16x16x32_bf16 v[122:125], v[148:151], v[172:175], v[122:125]
	v_mfma_f32_16x16x32_bf16 v[122:125], v[152:155], v[176:179], v[122:125]
	v_mfma_f32_16x16x32_bf16 v[118:121], v[156:159], v[172:175], v[118:121]
	v_mfma_f32_16x16x32_bf16 v[118:121], v[160:163], v[176:179], v[118:121]
	v_mfma_f32_16x16x32_bf16 v[114:117], v[164:167], v[172:175], v[114:117]
	v_mfma_f32_16x16x32_bf16 v[114:117], v[168:171], v[176:179], v[114:117]
	v_mfma_f32_16x16x32_bf16 v[98:101], v[164:167], v[180:183], v[98:101]
	v_mfma_f32_16x16x32_bf16 v[98:101], v[168:171], v[184:187], v[98:101]
	v_mfma_f32_16x16x32_bf16 v[102:105], v[156:159], v[180:183], v[102:105]
	v_mfma_f32_16x16x32_bf16 v[102:105], v[160:163], v[184:187], v[102:105]
	v_mfma_f32_16x16x32_bf16 v[106:109], v[148:151], v[180:183], v[106:109]
	v_mfma_f32_16x16x32_bf16 v[106:109], v[152:155], v[184:187], v[106:109]
	v_mfma_f32_16x16x32_bf16 v[110:113], v[132:135], v[180:183], v[110:113]
	v_mfma_f32_16x16x32_bf16 v[110:113], v[136:139], v[184:187], v[110:113]
	v_mfma_f32_16x16x32_bf16 v[94:97], v[132:135], v[188:191], v[94:97]
	v_mfma_f32_16x16x32_bf16 v[94:97], v[136:139], v[192:195], v[94:97]
	v_mfma_f32_16x16x32_bf16 v[90:93], v[148:151], v[188:191], v[90:93]
	v_mfma_f32_16x16x32_bf16 v[90:93], v[152:155], v[192:195], v[90:93]
	v_mfma_f32_16x16x32_bf16 v[86:89], v[156:159], v[188:191], v[86:89]
	v_mfma_f32_16x16x32_bf16 v[86:89], v[160:163], v[192:195], v[86:89]
	v_mfma_f32_16x16x32_bf16 v[82:85], v[164:167], v[188:191], v[82:85]
	v_mfma_f32_16x16x32_bf16 v[82:85], v[168:171], v[192:195], v[82:85]
	v_mfma_f32_16x16x32_bf16 v[66:69], v[164:167], v[196:199], v[66:69]
	v_mfma_f32_16x16x32_bf16 v[66:69], v[168:171], v[200:203], v[66:69]
	v_mfma_f32_16x16x32_bf16 v[70:73], v[156:159], v[196:199], v[70:73]
	v_mfma_f32_16x16x32_bf16 v[70:73], v[160:163], v[200:203], v[70:73]
	v_mfma_f32_16x16x32_bf16 v[74:77], v[148:151], v[196:199], v[74:77]
	v_mfma_f32_16x16x32_bf16 v[74:77], v[152:155], v[200:203], v[74:77]
	v_mfma_f32_16x16x32_bf16 v[78:81], v[132:135], v[196:199], v[78:81]
	v_mfma_f32_16x16x32_bf16 v[78:81], v[136:139], v[200:203], v[78:81]
	s_setprio 0
	s_barrier
	s_mov_b32 m0, s25
	s_mov_b32 s18, s14
	s_mov_b32 s19, s15
	ds_read_b128 v[172:175], v144 offset:16384
	ds_read_b128 v[176:179], v144 offset:17408
	ds_read_b128 v[180:183], v144 offset:18432
	ds_read_b128 v[184:187], v144 offset:19456
	ds_read_b128 v[188:191], v144 offset:20480
	ds_read_b128 v[192:195], v144 offset:21504
	ds_read_b128 v[196:199], v144 offset:22528
	ds_read_b128 v[200:203], v144 offset:23552
	buffer_load_dwordx4 v141, s[16:19], s64 offen lds
	s_add_i32 s65, s64, 0x40000
	s_mov_b32 m0, s27
	s_add_i32 s66, s64, 0x80000
	buffer_load_dwordx4 v141, s[16:19], s65 offen lds
	s_mov_b32 m0, s30
	s_add_i32 s67, s64, 0xc0000
	buffer_load_dwordx4 v141, s[16:19], s66 offen lds
	s_mov_b32 m0, s31
	s_nop 0
	buffer_load_dwordx4 v141, s[16:19], s67 offen lds
	s_mov_b32 m0, s21
	s_nop 0
	buffer_load_dwordx4 v140, s[12:15], s64 offen lds
	s_mov_b32 m0, s38
	s_nop 0
	buffer_load_dwordx4 v140, s[12:15], s65 offen lds
	s_waitcnt vmcnt(8) lgkmcnt(0)
	s_setprio 1
	v_mfma_f32_16x16x32_bf16 v[62:65], v[132:135], v[172:175], v[62:65]
	s_barrier
	v_mfma_f32_16x16x32_bf16 v[62:65], v[136:139], v[176:179], v[62:65]
	v_mfma_f32_16x16x32_bf16 v[58:61], v[148:151], v[172:175], v[58:61]
	v_mfma_f32_16x16x32_bf16 v[58:61], v[152:155], v[176:179], v[58:61]
	v_mfma_f32_16x16x32_bf16 v[54:57], v[156:159], v[172:175], v[54:57]
	v_mfma_f32_16x16x32_bf16 v[54:57], v[160:163], v[176:179], v[54:57]
	v_mfma_f32_16x16x32_bf16 v[50:53], v[164:167], v[172:175], v[50:53]
	v_mfma_f32_16x16x32_bf16 v[50:53], v[168:171], v[176:179], v[50:53]
	v_mfma_f32_16x16x32_bf16 v[34:37], v[164:167], v[180:183], v[34:37]
	v_mfma_f32_16x16x32_bf16 v[34:37], v[168:171], v[184:187], v[34:37]
	v_mfma_f32_16x16x32_bf16 v[38:41], v[156:159], v[180:183], v[38:41]
	v_mfma_f32_16x16x32_bf16 v[38:41], v[160:163], v[184:187], v[38:41]
	v_mfma_f32_16x16x32_bf16 v[42:45], v[148:151], v[180:183], v[42:45]
	v_mfma_f32_16x16x32_bf16 v[42:45], v[152:155], v[184:187], v[42:45]
	v_mfma_f32_16x16x32_bf16 v[46:49], v[132:135], v[180:183], v[46:49]
	v_mfma_f32_16x16x32_bf16 v[46:49], v[136:139], v[184:187], v[46:49]
	v_mfma_f32_16x16x32_bf16 v[30:33], v[132:135], v[188:191], v[30:33]
	v_mfma_f32_16x16x32_bf16 v[30:33], v[136:139], v[192:195], v[30:33]
	v_mfma_f32_16x16x32_bf16 v[26:29], v[148:151], v[188:191], v[26:29]
	v_mfma_f32_16x16x32_bf16 v[26:29], v[152:155], v[192:195], v[26:29]
	v_mfma_f32_16x16x32_bf16 v[22:25], v[156:159], v[188:191], v[22:25]
	v_mfma_f32_16x16x32_bf16 v[22:25], v[160:163], v[192:195], v[22:25]
	v_mfma_f32_16x16x32_bf16 v[18:21], v[164:167], v[188:191], v[18:21]
	v_mfma_f32_16x16x32_bf16 v[18:21], v[168:171], v[192:195], v[18:21]
	v_mfma_f32_16x16x32_bf16 v[2:5], v[164:167], v[196:199], v[2:5]
	v_mfma_f32_16x16x32_bf16 v[2:5], v[168:171], v[200:203], v[2:5]
	v_mfma_f32_16x16x32_bf16 v[6:9], v[156:159], v[196:199], v[6:9]
	v_mfma_f32_16x16x32_bf16 v[6:9], v[160:163], v[200:203], v[6:9]
	v_mfma_f32_16x16x32_bf16 v[10:13], v[148:151], v[196:199], v[10:13]
	v_mfma_f32_16x16x32_bf16 v[10:13], v[152:155], v[200:203], v[10:13]
	v_mfma_f32_16x16x32_bf16 v[14:17], v[132:135], v[196:199], v[14:17]
	v_mfma_f32_16x16x32_bf16 v[14:17], v[136:139], v[200:203], v[14:17]
	s_setprio 0
	s_barrier
	ds_read_b128 v[132:135], v145
	ds_read_b128 v[136:139], v145 offset:1024
	ds_read_b128 v[148:151], v145 offset:2048
	ds_read_b128 v[152:155], v145 offset:3072
	ds_read_b128 v[156:159], v147
	ds_read_b128 v[160:163], v147 offset:1024
	ds_read_b128 v[164:167], v147 offset:2048
	ds_read_b128 v[168:171], v147 offset:3072
	s_mov_b32 m0, s39
	ds_read_b128 v[172:175], v144 offset:32768
	ds_read_b128 v[176:179], v144 offset:33792
	ds_read_b128 v[180:183], v144 offset:34816
	ds_read_b128 v[184:187], v144 offset:35840
	ds_read_b128 v[188:191], v144 offset:36864
	ds_read_b128 v[192:195], v144 offset:37888
	ds_read_b128 v[196:199], v144 offset:38912
	ds_read_b128 v[200:203], v144 offset:39936
	buffer_load_dwordx4 v140, s[12:15], s66 offen lds
	s_mov_b32 m0, s40
	s_nop 0
	buffer_load_dwordx4 v140, s[12:15], s67 offen lds
	s_waitcnt vmcnt(8) lgkmcnt(0)
	s_setprio 1
	v_mfma_f32_16x16x32_bf16 v[126:129], v[132:135], v[172:175], v[126:129]
	s_barrier
	v_mfma_f32_16x16x32_bf16 v[126:129], v[136:139], v[176:179], v[126:129]
	v_mfma_f32_16x16x32_bf16 v[122:125], v[148:151], v[172:175], v[122:125]
	v_mfma_f32_16x16x32_bf16 v[122:125], v[152:155], v[176:179], v[122:125]
	v_mfma_f32_16x16x32_bf16 v[118:121], v[156:159], v[172:175], v[118:121]
	v_mfma_f32_16x16x32_bf16 v[118:121], v[160:163], v[176:179], v[118:121]
	v_mfma_f32_16x16x32_bf16 v[114:117], v[164:167], v[172:175], v[114:117]
	v_mfma_f32_16x16x32_bf16 v[114:117], v[168:171], v[176:179], v[114:117]
	v_mfma_f32_16x16x32_bf16 v[98:101], v[164:167], v[180:183], v[98:101]
	v_mfma_f32_16x16x32_bf16 v[98:101], v[168:171], v[184:187], v[98:101]
	v_mfma_f32_16x16x32_bf16 v[102:105], v[156:159], v[180:183], v[102:105]
	v_mfma_f32_16x16x32_bf16 v[102:105], v[160:163], v[184:187], v[102:105]
	v_mfma_f32_16x16x32_bf16 v[106:109], v[148:151], v[180:183], v[106:109]
	v_mfma_f32_16x16x32_bf16 v[106:109], v[152:155], v[184:187], v[106:109]
	v_mfma_f32_16x16x32_bf16 v[110:113], v[132:135], v[180:183], v[110:113]
	v_mfma_f32_16x16x32_bf16 v[110:113], v[136:139], v[184:187], v[110:113]
	v_mfma_f32_16x16x32_bf16 v[94:97], v[132:135], v[188:191], v[94:97]
	v_mfma_f32_16x16x32_bf16 v[94:97], v[136:139], v[192:195], v[94:97]
	v_mfma_f32_16x16x32_bf16 v[90:93], v[148:151], v[188:191], v[90:93]
	v_mfma_f32_16x16x32_bf16 v[90:93], v[152:155], v[192:195], v[90:93]
	v_mfma_f32_16x16x32_bf16 v[86:89], v[156:159], v[188:191], v[86:89]
	v_mfma_f32_16x16x32_bf16 v[86:89], v[160:163], v[192:195], v[86:89]
	v_mfma_f32_16x16x32_bf16 v[82:85], v[164:167], v[188:191], v[82:85]
	v_mfma_f32_16x16x32_bf16 v[82:85], v[168:171], v[192:195], v[82:85]
	v_mfma_f32_16x16x32_bf16 v[66:69], v[164:167], v[196:199], v[66:69]
	v_mfma_f32_16x16x32_bf16 v[66:69], v[168:171], v[200:203], v[66:69]
	v_mfma_f32_16x16x32_bf16 v[70:73], v[156:159], v[196:199], v[70:73]
	v_mfma_f32_16x16x32_bf16 v[70:73], v[160:163], v[200:203], v[70:73]
	v_mfma_f32_16x16x32_bf16 v[74:77], v[148:151], v[196:199], v[74:77]
	v_mfma_f32_16x16x32_bf16 v[74:77], v[152:155], v[200:203], v[74:77]
	v_mfma_f32_16x16x32_bf16 v[78:81], v[132:135], v[196:199], v[78:81]
	v_mfma_f32_16x16x32_bf16 v[78:81], v[136:139], v[200:203], v[78:81]
	s_setprio 0
	s_barrier
	s_mov_b32 m0, s48
	ds_read_b128 v[172:175], v144 offset:49152
	ds_read_b128 v[176:179], v144 offset:50176
	ds_read_b128 v[180:183], v144 offset:51200
	ds_read_b128 v[184:187], v144 offset:52224
	ds_read_b128 v[188:191], v144 offset:53248
	ds_read_b128 v[192:195], v144 offset:54272
	ds_read_b128 v[196:199], v144 offset:55296
	ds_read_b128 v[200:203], v144 offset:56320
	buffer_load_dwordx4 v141, s[16:19], s63 offen lds
	s_add_i32 s65, s64, 0x40080
	s_mov_b32 m0, s49
	s_add_i32 s66, s64, 0x80080
	buffer_load_dwordx4 v141, s[16:19], s65 offen lds
	s_mov_b32 m0, s52
	s_add_i32 s64, s64, 0xc0080
	buffer_load_dwordx4 v141, s[16:19], s66 offen lds
	s_mov_b32 m0, s53
	s_nop 0
	buffer_load_dwordx4 v141, s[16:19], s64 offen lds
	s_mov_b32 m0, s50
	s_nop 0
	buffer_load_dwordx4 v140, s[12:15], s63 offen lds
	s_mov_b32 m0, s51
	s_nop 0
	buffer_load_dwordx4 v140, s[12:15], s65 offen lds
	s_waitcnt vmcnt(8) lgkmcnt(0)
	s_setprio 1
	v_mfma_f32_16x16x32_bf16 v[62:65], v[132:135], v[172:175], v[62:65]
	s_barrier
	v_mfma_f32_16x16x32_bf16 v[62:65], v[136:139], v[176:179], v[62:65]
	v_mfma_f32_16x16x32_bf16 v[58:61], v[148:151], v[172:175], v[58:61]
	v_mfma_f32_16x16x32_bf16 v[58:61], v[152:155], v[176:179], v[58:61]
	v_mfma_f32_16x16x32_bf16 v[54:57], v[156:159], v[172:175], v[54:57]
	v_mfma_f32_16x16x32_bf16 v[54:57], v[160:163], v[176:179], v[54:57]
	v_mfma_f32_16x16x32_bf16 v[50:53], v[164:167], v[172:175], v[50:53]
	v_mfma_f32_16x16x32_bf16 v[50:53], v[168:171], v[176:179], v[50:53]
	v_mfma_f32_16x16x32_bf16 v[34:37], v[164:167], v[180:183], v[34:37]
	v_mfma_f32_16x16x32_bf16 v[34:37], v[168:171], v[184:187], v[34:37]
	v_mfma_f32_16x16x32_bf16 v[38:41], v[156:159], v[180:183], v[38:41]
	v_mfma_f32_16x16x32_bf16 v[38:41], v[160:163], v[184:187], v[38:41]
	v_mfma_f32_16x16x32_bf16 v[42:45], v[148:151], v[180:183], v[42:45]
	v_mfma_f32_16x16x32_bf16 v[42:45], v[152:155], v[184:187], v[42:45]
	v_mfma_f32_16x16x32_bf16 v[46:49], v[132:135], v[180:183], v[46:49]
	v_mfma_f32_16x16x32_bf16 v[46:49], v[136:139], v[184:187], v[46:49]
	v_mfma_f32_16x16x32_bf16 v[30:33], v[132:135], v[188:191], v[30:33]
	v_mfma_f32_16x16x32_bf16 v[30:33], v[136:139], v[192:195], v[30:33]
	v_mfma_f32_16x16x32_bf16 v[26:29], v[148:151], v[188:191], v[26:29]
	v_mfma_f32_16x16x32_bf16 v[26:29], v[152:155], v[192:195], v[26:29]
	v_mfma_f32_16x16x32_bf16 v[22:25], v[156:159], v[188:191], v[22:25]
	v_mfma_f32_16x16x32_bf16 v[22:25], v[160:163], v[192:195], v[22:25]
	v_mfma_f32_16x16x32_bf16 v[18:21], v[164:167], v[188:191], v[18:21]
	v_mfma_f32_16x16x32_bf16 v[18:21], v[168:171], v[192:195], v[18:21]
	v_mfma_f32_16x16x32_bf16 v[2:5], v[164:167], v[196:199], v[2:5]
	v_mfma_f32_16x16x32_bf16 v[2:5], v[168:171], v[200:203], v[2:5]
	v_mfma_f32_16x16x32_bf16 v[6:9], v[156:159], v[196:199], v[6:9]
	v_mfma_f32_16x16x32_bf16 v[6:9], v[160:163], v[200:203], v[6:9]
	v_mfma_f32_16x16x32_bf16 v[10:13], v[148:151], v[196:199], v[10:13]
	v_mfma_f32_16x16x32_bf16 v[10:13], v[152:155], v[200:203], v[10:13]
	v_mfma_f32_16x16x32_bf16 v[14:17], v[132:135], v[196:199], v[14:17]
	v_mfma_f32_16x16x32_bf16 v[14:17], v[136:139], v[200:203], v[14:17]
	s_setprio 0
	s_barrier
	s_add_i32 s62, s62, 2
	s_addk_i32 s61, 0x100
	s_cmp_ge_i32 s62, s3
	s_cbranch_scc0 .LBB0_1050

.LBB0_1181:
	v_add_u32_e32 v2, 0x10000, v232
	ds_read_b128 v[134:137], v2
	ds_read_b128 v[138:141], v2 offset:1024
	ds_read_b128 v[142:145], v2 offset:2048
	ds_read_b128 v[146:149], v2 offset:3072
	v_add_u32_e32 v2, 0x14000, v232
	ds_read_b128 v[150:153], v2
	ds_read_b128 v[154:157], v2 offset:1024
	ds_read_b128 v[158:161], v2 offset:2048
	ds_read_b128 v[162:165], v2 offset:3072
	s_add_i32 s50, s47, s90
	s_and_b64 s[18:19], exec, s[18:19]
	s_cselect_b32 s51, s88, s50
	s_add_i32 s50, s92, 0x80
	s_or_b32 s52, s51, 0x80
	s_add_i32 s18, s89, s93
	s_add_i32 s94, s94, 0x1bfffc80
	s_cmp_lt_u32 s91, 8
	s_cselect_b32 s18, s18, s94
	s_mov_b32 m0, s74
	s_add_i32 s19, s18, 0x80000
	ds_read_b128 v[166:169], v233
	ds_read_b128 v[170:173], v233 offset:1024
	ds_read_b128 v[174:177], v233 offset:2048
	ds_read_b128 v[178:181], v233 offset:3072
	ds_read_b128 v[182:185], v233 offset:4096
	ds_read_b128 v[186:189], v233 offset:5120
	ds_read_b128 v[190:193], v233 offset:6144
	ds_read_b128 v[194:197], v233 offset:7168
	buffer_load_dwordx4 v230, s[12:15], s19 offen lds
	s_mov_b32 m0, s75
	s_add_i32 s18, s18, 0xc0000
	buffer_load_dwordx4 v230, s[12:15], s18 offen lds
	s_waitcnt vmcnt(8) lgkmcnt(0)
	s_setprio 1
	v_mfma_f32_16x16x32_bf16 v[130:133], v[134:137], v[166:169], v[130:133]
	s_barrier
	v_mfma_f32_16x16x32_bf16 v[130:133], v[138:141], v[170:173], v[130:133]
	v_mfma_f32_16x16x32_bf16 v[126:129], v[142:145], v[166:169], v[126:129]
	v_mfma_f32_16x16x32_bf16 v[126:129], v[146:149], v[170:173], v[126:129]
	v_mfma_f32_16x16x32_bf16 v[122:125], v[150:153], v[166:169], v[122:125]
	v_mfma_f32_16x16x32_bf16 v[122:125], v[154:157], v[170:173], v[122:125]
	v_mfma_f32_16x16x32_bf16 v[118:121], v[158:161], v[166:169], v[118:121]
	v_mfma_f32_16x16x32_bf16 v[118:121], v[162:165], v[170:173], v[118:121]
	v_mfma_f32_16x16x32_bf16 v[102:105], v[158:161], v[174:177], v[102:105]
	v_mfma_f32_16x16x32_bf16 v[102:105], v[162:165], v[178:181], v[102:105]
	v_mfma_f32_16x16x32_bf16 v[106:109], v[150:153], v[174:177], v[106:109]
	v_mfma_f32_16x16x32_bf16 v[106:109], v[154:157], v[178:181], v[106:109]
	v_mfma_f32_16x16x32_bf16 v[110:113], v[142:145], v[174:177], v[110:113]
	v_mfma_f32_16x16x32_bf16 v[110:113], v[146:149], v[178:181], v[110:113]
	v_mfma_f32_16x16x32_bf16 v[114:117], v[134:137], v[174:177], v[114:117]
	v_mfma_f32_16x16x32_bf16 v[114:117], v[138:141], v[178:181], v[114:117]
	v_mfma_f32_16x16x32_bf16 v[98:101], v[134:137], v[182:185], v[98:101]
	v_mfma_f32_16x16x32_bf16 v[98:101], v[138:141], v[186:189], v[98:101]
	v_mfma_f32_16x16x32_bf16 v[94:97], v[142:145], v[182:185], v[94:97]
	v_mfma_f32_16x16x32_bf16 v[94:97], v[146:149], v[186:189], v[94:97]
	v_mfma_f32_16x16x32_bf16 v[90:93], v[150:153], v[182:185], v[90:93]
	v_mfma_f32_16x16x32_bf16 v[90:93], v[154:157], v[186:189], v[90:93]
	v_mfma_f32_16x16x32_bf16 v[86:89], v[158:161], v[182:185], v[86:89]
	v_mfma_f32_16x16x32_bf16 v[86:89], v[162:165], v[186:189], v[86:89]
	v_mfma_f32_16x16x32_bf16 v[70:73], v[158:161], v[190:193], v[70:73]
	v_mfma_f32_16x16x32_bf16 v[70:73], v[162:165], v[194:197], v[70:73]
	v_mfma_f32_16x16x32_bf16 v[74:77], v[150:153], v[190:193], v[74:77]
	v_mfma_f32_16x16x32_bf16 v[74:77], v[154:157], v[194:197], v[74:77]
	v_mfma_f32_16x16x32_bf16 v[78:81], v[142:145], v[190:193], v[78:81]
	v_mfma_f32_16x16x32_bf16 v[78:81], v[146:149], v[194:197], v[78:81]
	v_mfma_f32_16x16x32_bf16 v[82:85], v[134:137], v[190:193], v[82:85]
	v_mfma_f32_16x16x32_bf16 v[82:85], v[138:141], v[194:197], v[82:85]
	s_setprio 0
	s_barrier
	s_mov_b32 m0, s27
	s_mov_b32 s18, s14
	s_mov_b32 s19, s15
	ds_read_b128 v[166:169], v233 offset:16384
	ds_read_b128 v[170:173], v233 offset:17408
	ds_read_b128 v[174:177], v233 offset:18432
	ds_read_b128 v[178:181], v233 offset:19456
	ds_read_b128 v[182:185], v233 offset:20480
	ds_read_b128 v[186:189], v233 offset:21504
	ds_read_b128 v[190:193], v233 offset:22528
	ds_read_b128 v[194:197], v233 offset:23552
	buffer_load_dwordx4 v231, s[16:19], s51 offen lds
	s_mov_b32 m0, s30
	s_add_i32 s53, s51, 0x18000
	buffer_load_dwordx4 v231, s[16:19], s53 offen lds
	s_mov_b32 m0, s31
	s_add_i32 s53, s51, 0x30000
	buffer_load_dwordx4 v231, s[16:19], s53 offen lds
	s_mov_b32 m0, s54
	s_add_i32 s53, s51, 0x48000
	buffer_load_dwordx4 v231, s[16:19], s53 offen lds
	s_mov_b32 m0, s25
	s_add_i32 s53, s92, 0x40000
	buffer_load_dwordx4 v230, s[12:15], s92 offen lds
	s_mov_b32 m0, s55
	s_nop 0
	buffer_load_dwordx4 v230, s[12:15], s53 offen lds
	s_waitcnt vmcnt(8) lgkmcnt(0)
	s_setprio 1
	v_mfma_f32_16x16x32_bf16 v[66:69], v[134:137], v[166:169], v[66:69]
	s_barrier
	v_mfma_f32_16x16x32_bf16 v[62:65], v[142:145], v[166:169], v[62:65]
	v_mfma_f32_16x16x32_bf16 v[50:53], v[134:137], v[174:177], v[50:53]
	v_mfma_f32_16x16x32_bf16 v[46:49], v[142:145], v[174:177], v[46:49]
	v_mfma_f32_16x16x32_bf16 v[34:37], v[134:137], v[182:185], v[34:37]
	v_mfma_f32_16x16x32_bf16 v[30:33], v[142:145], v[182:185], v[30:33]
	v_mfma_f32_16x16x32_bf16 v[18:21], v[134:137], v[190:193], v[18:21]
	v_mfma_f32_16x16x32_bf16 v[14:17], v[142:145], v[190:193], v[14:17]
	v_mfma_f32_16x16x32_bf16 v[58:61], v[150:153], v[166:169], v[58:61]
	v_mfma_f32_16x16x32_bf16 v[54:57], v[158:161], v[166:169], v[54:57]
	v_mfma_f32_16x16x32_bf16 v[42:45], v[150:153], v[174:177], v[42:45]
	v_mfma_f32_16x16x32_bf16 v[38:41], v[158:161], v[174:177], v[38:41]
	v_mfma_f32_16x16x32_bf16 v[26:29], v[150:153], v[182:185], v[26:29]
	v_mfma_f32_16x16x32_bf16 v[22:25], v[158:161], v[182:185], v[22:25]
	v_mfma_f32_16x16x32_bf16 v[10:13], v[150:153], v[190:193], v[10:13]
	v_mfma_f32_16x16x32_bf16 v[4:7], v[158:161], v[190:193], v[6:9]
	v_mfma_f32_16x16x32_bf16 v[66:69], v[138:141], v[170:173], v[66:69]
	v_mfma_f32_16x16x32_bf16 v[62:65], v[146:149], v[170:173], v[62:65]
	v_mfma_f32_16x16x32_bf16 v[50:53], v[138:141], v[178:181], v[50:53]
	v_mfma_f32_16x16x32_bf16 v[46:49], v[146:149], v[178:181], v[46:49]
	v_mfma_f32_16x16x32_bf16 v[34:37], v[138:141], v[186:189], v[34:37]
	v_mfma_f32_16x16x32_bf16 v[30:33], v[146:149], v[186:189], v[30:33]
	v_mfma_f32_16x16x32_bf16 v[18:21], v[138:141], v[194:197], v[18:21]
	v_mfma_f32_16x16x32_bf16 v[14:17], v[146:149], v[194:197], v[14:17]
	v_mfma_f32_16x16x32_bf16 v[58:61], v[154:157], v[170:173], v[58:61]
	v_mfma_f32_16x16x32_bf16 v[54:57], v[162:165], v[170:173], v[54:57]
	v_mfma_f32_16x16x32_bf16 v[42:45], v[154:157], v[178:181], v[42:45]
	v_mfma_f32_16x16x32_bf16 v[38:41], v[162:165], v[178:181], v[38:41]
	v_mfma_f32_16x16x32_bf16 v[26:29], v[154:157], v[186:189], v[26:29]
	v_mfma_f32_16x16x32_bf16 v[22:25], v[162:165], v[186:189], v[22:25]
	v_mfma_f32_16x16x32_bf16 v[10:13], v[154:157], v[194:197], v[10:13]
	v_mfma_f32_16x16x32_bf16 v[4:7], v[162:165], v[194:197], v[4:7]
	s_setprio 0
	s_barrier
	v_add_u32_e32 v2, 0x18000, v232
	ds_read_b128 v[134:137], v2
	ds_read_b128 v[138:141], v2 offset:1024
	ds_read_b128 v[142:145], v2 offset:2048
	ds_read_b128 v[146:149], v2 offset:3072
	v_add_u32_e32 v2, 0x1c000, v232
	ds_read_b128 v[150:153], v2
	ds_read_b128 v[154:157], v2 offset:1024
	ds_read_b128 v[158:161], v2 offset:2048
	ds_read_b128 v[162:165], v2 offset:3072
	s_mov_b32 m0, s56
	s_add_i32 s53, s92, 0x80000
	ds_read_b128 v[166:169], v233 offset:32768
	ds_read_b128 v[170:173], v233 offset:33792
	ds_read_b128 v[174:177], v233 offset:34816
	ds_read_b128 v[178:181], v233 offset:35840
	ds_read_b128 v[182:185], v233 offset:36864
	ds_read_b128 v[186:189], v233 offset:37888
	ds_read_b128 v[190:193], v233 offset:38912
	ds_read_b128 v[194:197], v233 offset:39936
	buffer_load_dwordx4 v230, s[12:15], s53 offen lds
	s_mov_b32 m0, s57
	s_add_i32 s53, s92, 0xc0000
	buffer_load_dwordx4 v230, s[12:15], s53 offen lds
	s_waitcnt vmcnt(8) lgkmcnt(0)
	s_setprio 1
	v_mfma_f32_16x16x32_bf16 v[130:133], v[134:137], v[166:169], v[130:133]
	s_barrier
	v_mfma_f32_16x16x32_bf16 v[130:133], v[138:141], v[170:173], v[130:133]
	v_mfma_f32_16x16x32_bf16 v[126:129], v[142:145], v[166:169], v[126:129]
	v_mfma_f32_16x16x32_bf16 v[126:129], v[146:149], v[170:173], v[126:129]
	v_mfma_f32_16x16x32_bf16 v[122:125], v[150:153], v[166:169], v[122:125]
	v_mfma_f32_16x16x32_bf16 v[122:125], v[154:157], v[170:173], v[122:125]
	v_mfma_f32_16x16x32_bf16 v[118:121], v[158:161], v[166:169], v[118:121]
	v_mfma_f32_16x16x32_bf16 v[118:121], v[162:165], v[170:173], v[118:121]
	v_mfma_f32_16x16x32_bf16 v[102:105], v[158:161], v[174:177], v[102:105]
	v_mfma_f32_16x16x32_bf16 v[102:105], v[162:165], v[178:181], v[102:105]
	v_mfma_f32_16x16x32_bf16 v[106:109], v[150:153], v[174:177], v[106:109]
	v_mfma_f32_16x16x32_bf16 v[106:109], v[154:157], v[178:181], v[106:109]
	v_mfma_f32_16x16x32_bf16 v[110:113], v[142:145], v[174:177], v[110:113]
	v_mfma_f32_16x16x32_bf16 v[110:113], v[146:149], v[178:181], v[110:113]
	v_mfma_f32_16x16x32_bf16 v[114:117], v[134:137], v[174:177], v[114:117]
	v_mfma_f32_16x16x32_bf16 v[114:117], v[138:141], v[178:181], v[114:117]
	v_mfma_f32_16x16x32_bf16 v[98:101], v[134:137], v[182:185], v[98:101]
	v_mfma_f32_16x16x32_bf16 v[98:101], v[138:141], v[186:189], v[98:101]
	v_mfma_f32_16x16x32_bf16 v[94:97], v[142:145], v[182:185], v[94:97]
	v_mfma_f32_16x16x32_bf16 v[94:97], v[146:149], v[186:189], v[94:97]
	v_mfma_f32_16x16x32_bf16 v[90:93], v[150:153], v[182:185], v[90:93]
	v_mfma_f32_16x16x32_bf16 v[90:93], v[154:157], v[186:189], v[90:93]
	v_mfma_f32_16x16x32_bf16 v[86:89], v[158:161], v[182:185], v[86:89]
	v_mfma_f32_16x16x32_bf16 v[86:89], v[162:165], v[186:189], v[86:89]
	v_mfma_f32_16x16x32_bf16 v[70:73], v[158:161], v[190:193], v[70:73]
	v_mfma_f32_16x16x32_bf16 v[70:73], v[162:165], v[194:197], v[70:73]
	v_mfma_f32_16x16x32_bf16 v[74:77], v[150:153], v[190:193], v[74:77]
	v_mfma_f32_16x16x32_bf16 v[74:77], v[154:157], v[194:197], v[74:77]
	v_mfma_f32_16x16x32_bf16 v[78:81], v[142:145], v[190:193], v[78:81]
	v_mfma_f32_16x16x32_bf16 v[78:81], v[146:149], v[194:197], v[78:81]
	v_mfma_f32_16x16x32_bf16 v[82:85], v[134:137], v[190:193], v[82:85]
	v_mfma_f32_16x16x32_bf16 v[82:85], v[138:141], v[194:197], v[82:85]
	s_setprio 0
	s_barrier
	s_mov_b32 m0, s64
	ds_read_b128 v[166:169], v233 offset:49152
	ds_read_b128 v[170:173], v233 offset:50176
	ds_read_b128 v[174:177], v233 offset:51200
	ds_read_b128 v[178:181], v233 offset:52224
	ds_read_b128 v[182:185], v233 offset:53248
	ds_read_b128 v[186:189], v233 offset:54272
	ds_read_b128 v[190:193], v233 offset:55296
	ds_read_b128 v[194:197], v233 offset:56320
	buffer_load_dwordx4 v231, s[16:19], s52 offen lds
	s_mov_b32 m0, s65
	s_add_i32 s52, s51, 0x18080
	buffer_load_dwordx4 v231, s[16:19], s52 offen lds
	s_add_i32 s52, s51, 0x30080
	s_mov_b32 m0, s68
	s_add_i32 s51, s51, 0x48080
	buffer_load_dwordx4 v231, s[16:19], s52 offen lds
	s_mov_b32 m0, s69
	s_nop 0
	buffer_load_dwordx4 v231, s[16:19], s51 offen lds
	s_mov_b32 m0, s66
	s_add_i32 s18, s92, 0x40080
	buffer_load_dwordx4 v230, s[12:15], s50 offen lds
	s_mov_b32 m0, s67
	s_nop 0
	buffer_load_dwordx4 v230, s[12:15], s18 offen lds
	s_waitcnt vmcnt(8) lgkmcnt(0)
	s_setprio 1
	v_mfma_f32_16x16x32_bf16 v[66:69], v[134:137], v[166:169], v[66:69]
	s_barrier
	v_mfma_f32_16x16x32_bf16 v[62:65], v[142:145], v[166:169], v[62:65]
	v_mfma_f32_16x16x32_bf16 v[50:53], v[134:137], v[174:177], v[50:53]
	v_mfma_f32_16x16x32_bf16 v[46:49], v[142:145], v[174:177], v[46:49]
	v_mfma_f32_16x16x32_bf16 v[34:37], v[134:137], v[182:185], v[34:37]
	v_mfma_f32_16x16x32_bf16 v[30:33], v[142:145], v[182:185], v[30:33]
	v_mfma_f32_16x16x32_bf16 v[18:21], v[134:137], v[190:193], v[18:21]
	v_mfma_f32_16x16x32_bf16 v[14:17], v[142:145], v[190:193], v[14:17]
	v_mfma_f32_16x16x32_bf16 v[58:61], v[150:153], v[166:169], v[58:61]
	v_mfma_f32_16x16x32_bf16 v[54:57], v[158:161], v[166:169], v[54:57]
	v_mfma_f32_16x16x32_bf16 v[42:45], v[150:153], v[174:177], v[42:45]
	v_mfma_f32_16x16x32_bf16 v[38:41], v[158:161], v[174:177], v[38:41]
	v_mfma_f32_16x16x32_bf16 v[26:29], v[150:153], v[182:185], v[26:29]
	v_mfma_f32_16x16x32_bf16 v[22:25], v[158:161], v[182:185], v[22:25]
	v_mfma_f32_16x16x32_bf16 v[8:11], v[150:153], v[190:193], v[10:13]
	v_mfma_f32_16x16x32_bf16 v[4:7], v[158:161], v[190:193], v[4:7]
	v_mfma_f32_16x16x32_bf16 v[66:69], v[138:141], v[170:173], v[66:69]
	v_mfma_f32_16x16x32_bf16 v[62:65], v[146:149], v[170:173], v[62:65]
	v_mfma_f32_16x16x32_bf16 v[50:53], v[138:141], v[178:181], v[50:53]
	v_mfma_f32_16x16x32_bf16 v[46:49], v[146:149], v[178:181], v[46:49]
	v_mfma_f32_16x16x32_bf16 v[34:37], v[138:141], v[186:189], v[34:37]
	v_mfma_f32_16x16x32_bf16 v[30:33], v[146:149], v[186:189], v[30:33]
	v_mfma_f32_16x16x32_bf16 v[18:21], v[138:141], v[194:197], v[18:21]
	v_mfma_f32_16x16x32_bf16 v[14:17], v[146:149], v[194:197], v[14:17]
	v_mfma_f32_16x16x32_bf16 v[58:61], v[154:157], v[170:173], v[58:61]
	v_mfma_f32_16x16x32_bf16 v[54:57], v[162:165], v[170:173], v[54:57]
	v_mfma_f32_16x16x32_bf16 v[42:45], v[154:157], v[178:181], v[42:45]
	v_mfma_f32_16x16x32_bf16 v[38:41], v[162:165], v[178:181], v[38:41]
	v_mfma_f32_16x16x32_bf16 v[26:29], v[154:157], v[186:189], v[26:29]
	v_mfma_f32_16x16x32_bf16 v[22:25], v[162:165], v[186:189], v[22:25]
	v_mfma_f32_16x16x32_bf16 v[10:13], v[154:157], v[194:197], v[8:11]
	v_mfma_f32_16x16x32_bf16 v[6:9], v[162:165], v[194:197], v[4:7]
	s_setprio 0
	s_barrier
	s_add_i32 s91, s91, 2
	s_addk_i32 s90, 0x100
	s_cmp_ge_i32 s91, s3
	s_cbranch_scc1 .LBB0_1193

.LBB0_1290:
	ds_read_b128 v[106:109], v224
	ds_read_b128 v[118:121], v224 offset:1024
	ds_read_b128 v[130:133], v224 offset:2048
	ds_read_b128 v[138:141], v224 offset:3072
	ds_read_b128 v[146:149], v225
	ds_read_b128 v[150:153], v225 offset:1024
	ds_read_b128 v[154:157], v225 offset:2048
	ds_read_b128 v[158:161], v225 offset:3072
	s_add_i32 s18, s72, 0xffe80080
	s_cmp_eq_u32 s56, s74
	s_cselect_b32 s75, s6, s18
	s_cselect_b32 s77, s7, s73
	s_or_b32 s76, s75, 0x80
	s_add_i32 s18, s72, 0xfff80000
	s_mov_b32 m0, s57
	ds_read_b128 v[162:165], v226
	ds_read_b128 v[166:169], v226 offset:1024
	ds_read_b128 v[170:173], v226 offset:2048
	ds_read_b128 v[174:177], v226 offset:3072
	ds_read_b128 v[178:181], v226 offset:4096
	ds_read_b128 v[182:185], v226 offset:5120
	ds_read_b128 v[190:193], v226 offset:6144
	ds_read_b128 v[194:197], v226 offset:7168
	buffer_load_dwordx4 v222, s[12:15], s18 offen lds
	s_mov_b32 m0, s60
	s_nop 0
	buffer_load_dwordx4 v222, s[12:15], s72 offen lds
	s_waitcnt vmcnt(8) lgkmcnt(0)
	s_setprio 1
	v_mfma_f32_16x16x32_bf16 v[142:145], v[106:109], v[162:165], v[142:145]
	s_barrier
	v_mfma_f32_16x16x32_bf16 v[142:145], v[118:121], v[166:169], v[142:145]
	v_mfma_f32_16x16x32_bf16 v[134:137], v[130:133], v[162:165], v[134:137]
	v_mfma_f32_16x16x32_bf16 v[134:137], v[138:141], v[166:169], v[134:137]
	v_mfma_f32_16x16x32_bf16 v[126:129], v[146:149], v[162:165], v[126:129]
	v_mfma_f32_16x16x32_bf16 v[126:129], v[150:153], v[166:169], v[126:129]
	v_mfma_f32_16x16x32_bf16 v[122:125], v[154:157], v[162:165], v[122:125]
	v_mfma_f32_16x16x32_bf16 v[122:125], v[158:161], v[166:169], v[122:125]
	v_mfma_f32_16x16x32_bf16 v[98:101], v[154:157], v[170:173], v[98:101]
	v_mfma_f32_16x16x32_bf16 v[98:101], v[158:161], v[174:177], v[98:101]
	v_mfma_f32_16x16x32_bf16 v[102:105], v[146:149], v[170:173], v[102:105]
	v_mfma_f32_16x16x32_bf16 v[102:105], v[150:153], v[174:177], v[102:105]
	v_mfma_f32_16x16x32_bf16 v[110:113], v[130:133], v[170:173], v[110:113]
	v_mfma_f32_16x16x32_bf16 v[110:113], v[138:141], v[174:177], v[110:113]
	v_mfma_f32_16x16x32_bf16 v[114:117], v[106:109], v[170:173], v[114:117]
	v_mfma_f32_16x16x32_bf16 v[114:117], v[118:121], v[174:177], v[114:117]
	v_mfma_f32_16x16x32_bf16 v[94:97], v[106:109], v[178:181], v[94:97]
	v_mfma_f32_16x16x32_bf16 v[94:97], v[118:121], v[182:185], v[94:97]
	v_mfma_f32_16x16x32_bf16 v[90:93], v[130:133], v[178:181], v[90:93]
	v_mfma_f32_16x16x32_bf16 v[90:93], v[138:141], v[182:185], v[90:93]
	v_mfma_f32_16x16x32_bf16 v[86:89], v[146:149], v[178:181], v[86:89]
	v_mfma_f32_16x16x32_bf16 v[86:89], v[150:153], v[182:185], v[86:89]
	v_mfma_f32_16x16x32_bf16 v[82:85], v[154:157], v[178:181], v[82:85]
	v_mfma_f32_16x16x32_bf16 v[82:85], v[158:161], v[182:185], v[82:85]
	v_mfma_f32_16x16x32_bf16 v[66:69], v[154:157], v[190:193], v[66:69]
	v_mfma_f32_16x16x32_bf16 v[66:69], v[158:161], v[194:197], v[66:69]
	v_mfma_f32_16x16x32_bf16 v[70:73], v[146:149], v[190:193], v[70:73]
	v_mfma_f32_16x16x32_bf16 v[70:73], v[150:153], v[194:197], v[70:73]
	v_mfma_f32_16x16x32_bf16 v[74:77], v[130:133], v[190:193], v[74:77]
	v_mfma_f32_16x16x32_bf16 v[74:77], v[138:141], v[194:197], v[74:77]
	v_mfma_f32_16x16x32_bf16 v[78:81], v[106:109], v[190:193], v[78:81]
	v_mfma_f32_16x16x32_bf16 v[78:81], v[118:121], v[194:197], v[78:81]
	s_setprio 0
	s_barrier
	s_mov_b32 m0, s27
	s_mov_b32 s18, s14
	s_mov_b32 s19, s15
	ds_read_b128 v[162:165], v226 offset:16384
	ds_read_b128 v[166:169], v226 offset:17408
	ds_read_b128 v[170:173], v226 offset:18432
	ds_read_b128 v[174:177], v226 offset:19456
	ds_read_b128 v[178:181], v226 offset:20480
	ds_read_b128 v[182:185], v226 offset:21504
	ds_read_b128 v[190:193], v226 offset:22528
	ds_read_b128 v[194:197], v226 offset:23552
	buffer_load_dwordx4 v223, s[16:19], s77 offen lds
	s_mov_b32 m0, s30
	s_add_i32 s78, s77, 0x80000
	buffer_load_dwordx4 v223, s[16:19], s78 offen lds
	s_mov_b32 m0, s31
	s_add_i32 s78, s77, 0x100000
	buffer_load_dwordx4 v223, s[16:19], s78 offen lds
	s_mov_b32 m0, s41
	s_add_i32 s78, s77, 0x180000
	buffer_load_dwordx4 v223, s[16:19], s78 offen lds
	s_mov_b32 m0, s25
	s_add_i32 s78, s75, 0x80000
	buffer_load_dwordx4 v222, s[12:15], s75 offen lds
	s_mov_b32 m0, s42
	s_nop 0
	buffer_load_dwordx4 v222, s[12:15], s78 offen lds
	s_waitcnt vmcnt(8) lgkmcnt(0)
	s_setprio 1
	v_mfma_f32_16x16x32_bf16 v[62:65], v[106:109], v[162:165], v[62:65]
	s_barrier
	v_mfma_f32_16x16x32_bf16 v[62:65], v[118:121], v[166:169], v[62:65]
	v_mfma_f32_16x16x32_bf16 v[58:61], v[130:133], v[162:165], v[58:61]
	v_mfma_f32_16x16x32_bf16 v[58:61], v[138:141], v[166:169], v[58:61]
	v_mfma_f32_16x16x32_bf16 v[54:57], v[146:149], v[162:165], v[54:57]
	v_mfma_f32_16x16x32_bf16 v[54:57], v[150:153], v[166:169], v[54:57]
	v_mfma_f32_16x16x32_bf16 v[50:53], v[154:157], v[162:165], v[50:53]
	v_mfma_f32_16x16x32_bf16 v[50:53], v[158:161], v[166:169], v[50:53]
	v_mfma_f32_16x16x32_bf16 v[34:37], v[154:157], v[170:173], v[34:37]
	v_mfma_f32_16x16x32_bf16 v[34:37], v[158:161], v[174:177], v[34:37]
	v_mfma_f32_16x16x32_bf16 v[38:41], v[146:149], v[170:173], v[38:41]
	v_mfma_f32_16x16x32_bf16 v[38:41], v[150:153], v[174:177], v[38:41]
	v_mfma_f32_16x16x32_bf16 v[42:45], v[130:133], v[170:173], v[42:45]
	v_mfma_f32_16x16x32_bf16 v[42:45], v[138:141], v[174:177], v[42:45]
	v_mfma_f32_16x16x32_bf16 v[46:49], v[106:109], v[170:173], v[46:49]
	v_mfma_f32_16x16x32_bf16 v[46:49], v[118:121], v[174:177], v[46:49]
	v_mfma_f32_16x16x32_bf16 v[30:33], v[106:109], v[178:181], v[30:33]
	v_mfma_f32_16x16x32_bf16 v[30:33], v[118:121], v[182:185], v[30:33]
	v_mfma_f32_16x16x32_bf16 v[26:29], v[130:133], v[178:181], v[26:29]
	v_mfma_f32_16x16x32_bf16 v[26:29], v[138:141], v[182:185], v[26:29]
	v_mfma_f32_16x16x32_bf16 v[22:25], v[146:149], v[178:181], v[22:25]
	v_mfma_f32_16x16x32_bf16 v[22:25], v[150:153], v[182:185], v[22:25]
	v_mfma_f32_16x16x32_bf16 v[18:21], v[154:157], v[178:181], v[18:21]
	v_mfma_f32_16x16x32_bf16 v[18:21], v[158:161], v[182:185], v[18:21]
	v_mfma_f32_16x16x32_bf16 v[2:5], v[154:157], v[190:193], v[2:5]
	v_mfma_f32_16x16x32_bf16 v[2:5], v[158:161], v[194:197], v[2:5]
	v_mfma_f32_16x16x32_bf16 v[6:9], v[146:149], v[190:193], v[6:9]
	v_mfma_f32_16x16x32_bf16 v[6:9], v[150:153], v[194:197], v[6:9]
	v_mfma_f32_16x16x32_bf16 v[10:13], v[130:133], v[190:193], v[10:13]
	v_mfma_f32_16x16x32_bf16 v[10:13], v[138:141], v[194:197], v[10:13]
	v_mfma_f32_16x16x32_bf16 v[14:17], v[106:109], v[190:193], v[14:17]
	v_mfma_f32_16x16x32_bf16 v[14:17], v[118:121], v[194:197], v[14:17]
	s_setprio 0
	s_barrier
	ds_read_b128 v[106:109], v227
	ds_read_b128 v[118:121], v227 offset:1024
	ds_read_b128 v[130:133], v227 offset:2048
	ds_read_b128 v[138:141], v227 offset:3072
	ds_read_b128 v[146:149], v228
	ds_read_b128 v[150:153], v228 offset:1024
	ds_read_b128 v[154:157], v228 offset:2048
	ds_read_b128 v[158:161], v228 offset:3072
	s_mov_b32 m0, s43
	s_add_i32 s78, s75, 0x100000
	ds_read_b128 v[162:165], v226 offset:32768
	ds_read_b128 v[166:169], v226 offset:33792
	ds_read_b128 v[170:173], v226 offset:34816
	ds_read_b128 v[174:177], v226 offset:35840
	ds_read_b128 v[178:181], v226 offset:36864
	ds_read_b128 v[182:185], v226 offset:37888
	ds_read_b128 v[190:193], v226 offset:38912
	ds_read_b128 v[194:197], v226 offset:39936
	buffer_load_dwordx4 v222, s[12:15], s78 offen lds
	s_mov_b32 m0, s44
	s_add_i32 s78, s75, 0x180000
	buffer_load_dwordx4 v222, s[12:15], s78 offen lds
	s_waitcnt vmcnt(8) lgkmcnt(0)
	s_setprio 1
	v_mfma_f32_16x16x32_bf16 v[142:145], v[106:109], v[162:165], v[142:145]
	s_barrier
	v_mfma_f32_16x16x32_bf16 v[142:145], v[118:121], v[166:169], v[142:145]
	v_mfma_f32_16x16x32_bf16 v[134:137], v[130:133], v[162:165], v[134:137]
	v_mfma_f32_16x16x32_bf16 v[134:137], v[138:141], v[166:169], v[134:137]
	v_mfma_f32_16x16x32_bf16 v[126:129], v[146:149], v[162:165], v[126:129]
	v_mfma_f32_16x16x32_bf16 v[126:129], v[150:153], v[166:169], v[126:129]
	v_mfma_f32_16x16x32_bf16 v[122:125], v[154:157], v[162:165], v[122:125]
	v_mfma_f32_16x16x32_bf16 v[122:125], v[158:161], v[166:169], v[122:125]
	v_mfma_f32_16x16x32_bf16 v[98:101], v[154:157], v[170:173], v[98:101]
	v_mfma_f32_16x16x32_bf16 v[98:101], v[158:161], v[174:177], v[98:101]
	v_mfma_f32_16x16x32_bf16 v[102:105], v[146:149], v[170:173], v[102:105]
	v_mfma_f32_16x16x32_bf16 v[102:105], v[150:153], v[174:177], v[102:105]
	v_mfma_f32_16x16x32_bf16 v[110:113], v[130:133], v[170:173], v[110:113]
	v_mfma_f32_16x16x32_bf16 v[110:113], v[138:141], v[174:177], v[110:113]
	v_mfma_f32_16x16x32_bf16 v[114:117], v[106:109], v[170:173], v[114:117]
	v_mfma_f32_16x16x32_bf16 v[114:117], v[118:121], v[174:177], v[114:117]
	v_mfma_f32_16x16x32_bf16 v[94:97], v[106:109], v[178:181], v[94:97]
	v_mfma_f32_16x16x32_bf16 v[94:97], v[118:121], v[182:185], v[94:97]
	v_mfma_f32_16x16x32_bf16 v[90:93], v[130:133], v[178:181], v[90:93]
	v_mfma_f32_16x16x32_bf16 v[90:93], v[138:141], v[182:185], v[90:93]
	v_mfma_f32_16x16x32_bf16 v[86:89], v[146:149], v[178:181], v[86:89]
	v_mfma_f32_16x16x32_bf16 v[86:89], v[150:153], v[182:185], v[86:89]
	v_mfma_f32_16x16x32_bf16 v[82:85], v[154:157], v[178:181], v[82:85]
	v_mfma_f32_16x16x32_bf16 v[82:85], v[158:161], v[182:185], v[82:85]
	v_mfma_f32_16x16x32_bf16 v[66:69], v[154:157], v[190:193], v[66:69]
	v_mfma_f32_16x16x32_bf16 v[66:69], v[158:161], v[194:197], v[66:69]
	v_mfma_f32_16x16x32_bf16 v[70:73], v[146:149], v[190:193], v[70:73]
	v_mfma_f32_16x16x32_bf16 v[70:73], v[150:153], v[194:197], v[70:73]
	v_mfma_f32_16x16x32_bf16 v[74:77], v[130:133], v[190:193], v[74:77]
	v_mfma_f32_16x16x32_bf16 v[74:77], v[138:141], v[194:197], v[74:77]
	v_mfma_f32_16x16x32_bf16 v[78:81], v[106:109], v[190:193], v[78:81]
	v_mfma_f32_16x16x32_bf16 v[78:81], v[118:121], v[194:197], v[78:81]
	s_setprio 0
	s_barrier
	s_mov_b32 m0, s48
	s_or_b32 s78, s77, 0x80
	ds_read_b128 v[162:165], v226 offset:49152
	ds_read_b128 v[166:169], v226 offset:50176
	ds_read_b128 v[170:173], v226 offset:51200
	ds_read_b128 v[174:177], v226 offset:52224
	ds_read_b128 v[178:181], v226 offset:53248
	ds_read_b128 v[182:185], v226 offset:54272
	ds_read_b128 v[190:193], v226 offset:55296
	ds_read_b128 v[194:197], v226 offset:56320
	buffer_load_dwordx4 v223, s[16:19], s78 offen lds
	s_add_i32 s78, s77, 0x80080
	s_mov_b32 m0, s49
	s_add_i32 s75, s75, 0x80080
	buffer_load_dwordx4 v223, s[16:19], s78 offen lds
	s_add_i32 s78, s77, 0x100080
	s_mov_b32 m0, s52
	s_add_i32 s77, s77, 0x180080
	buffer_load_dwordx4 v223, s[16:19], s78 offen lds
	s_mov_b32 m0, s53
	s_nop 0
	buffer_load_dwordx4 v223, s[16:19], s77 offen lds
	s_mov_b32 m0, s50
	s_nop 0
	buffer_load_dwordx4 v222, s[12:15], s76 offen lds
	s_mov_b32 m0, s51
	s_nop 0
	buffer_load_dwordx4 v222, s[12:15], s75 offen lds
	s_waitcnt vmcnt(8) lgkmcnt(0)
	s_setprio 1
	v_mfma_f32_16x16x32_bf16 v[62:65], v[106:109], v[162:165], v[62:65]
	s_barrier
	v_mfma_f32_16x16x32_bf16 v[62:65], v[118:121], v[166:169], v[62:65]
	v_mfma_f32_16x16x32_bf16 v[58:61], v[130:133], v[162:165], v[58:61]
	v_mfma_f32_16x16x32_bf16 v[58:61], v[138:141], v[166:169], v[58:61]
	v_mfma_f32_16x16x32_bf16 v[54:57], v[146:149], v[162:165], v[54:57]
	v_mfma_f32_16x16x32_bf16 v[54:57], v[150:153], v[166:169], v[54:57]
	v_mfma_f32_16x16x32_bf16 v[50:53], v[154:157], v[162:165], v[50:53]
	v_mfma_f32_16x16x32_bf16 v[50:53], v[158:161], v[166:169], v[50:53]
	v_mfma_f32_16x16x32_bf16 v[34:37], v[154:157], v[170:173], v[34:37]
	v_mfma_f32_16x16x32_bf16 v[34:37], v[158:161], v[174:177], v[34:37]
	v_mfma_f32_16x16x32_bf16 v[38:41], v[146:149], v[170:173], v[38:41]
	v_mfma_f32_16x16x32_bf16 v[38:41], v[150:153], v[174:177], v[38:41]
	v_mfma_f32_16x16x32_bf16 v[42:45], v[130:133], v[170:173], v[42:45]
	v_mfma_f32_16x16x32_bf16 v[42:45], v[138:141], v[174:177], v[42:45]
	v_mfma_f32_16x16x32_bf16 v[46:49], v[106:109], v[170:173], v[46:49]
	v_mfma_f32_16x16x32_bf16 v[46:49], v[118:121], v[174:177], v[46:49]
	v_mfma_f32_16x16x32_bf16 v[30:33], v[106:109], v[178:181], v[30:33]
	v_mfma_f32_16x16x32_bf16 v[30:33], v[118:121], v[182:185], v[30:33]
	v_mfma_f32_16x16x32_bf16 v[26:29], v[130:133], v[178:181], v[26:29]
	v_mfma_f32_16x16x32_bf16 v[26:29], v[138:141], v[182:185], v[26:29]
	v_mfma_f32_16x16x32_bf16 v[22:25], v[146:149], v[178:181], v[22:25]
	v_mfma_f32_16x16x32_bf16 v[22:25], v[150:153], v[182:185], v[22:25]
	v_mfma_f32_16x16x32_bf16 v[18:21], v[154:157], v[178:181], v[18:21]
	v_mfma_f32_16x16x32_bf16 v[18:21], v[158:161], v[182:185], v[18:21]
	v_mfma_f32_16x16x32_bf16 v[2:5], v[154:157], v[190:193], v[2:5]
	v_mfma_f32_16x16x32_bf16 v[2:5], v[158:161], v[194:197], v[2:5]
	v_mfma_f32_16x16x32_bf16 v[6:9], v[146:149], v[190:193], v[6:9]
	v_mfma_f32_16x16x32_bf16 v[6:9], v[150:153], v[194:197], v[6:9]
	v_mfma_f32_16x16x32_bf16 v[10:13], v[130:133], v[190:193], v[10:13]
	v_mfma_f32_16x16x32_bf16 v[10:13], v[138:141], v[194:197], v[10:13]
	v_mfma_f32_16x16x32_bf16 v[14:17], v[106:109], v[190:193], v[14:17]
	v_mfma_f32_16x16x32_bf16 v[14:17], v[118:121], v[194:197], v[14:17]
	s_setprio 0
	s_barrier
	s_add_i32 s74, s74, 2
	s_addk_i32 s72, 0x100
	s_addk_i32 s73, 0x100
	s_cmp_ge_i32 s74, s3
	s_cbranch_scc0 .LBB0_1290
	s_and_b64 vcc, exec, s[38:39]
	s_cbranch_vccz .LBB0_1293

.LBB0_1382:
	ds_read_b128 v[144:147], v138
	ds_read_b128 v[148:151], v138 offset:1024
	ds_read_b128 v[152:155], v138 offset:2048
	ds_read_b128 v[156:159], v138 offset:3072
	ds_read_b128 v[160:163], v139
	ds_read_b128 v[164:167], v139 offset:1024
	ds_read_b128 v[168:171], v139 offset:2048
	ds_read_b128 v[172:175], v139 offset:3072
	s_add_i32 s14, s74, 0xffe80080
	s_cmp_eq_u32 s61, s76
	s_cselect_b32 s77, s72, s14
	s_cselect_b32 s79, s73, s75
	s_or_b32 s78, s77, 0x80
	s_add_i32 s14, s74, 0xfff80000
	s_mov_b32 m0, s62
	ds_read_b128 v[176:179], v140
	ds_read_b128 v[180:183], v140 offset:1024
	ds_read_b128 v[184:187], v140 offset:2048
	ds_read_b128 v[188:191], v140 offset:3072
	ds_read_b128 v[192:195], v140 offset:4096
	ds_read_b128 v[196:199], v140 offset:5120
	ds_read_b128 v[200:203], v140 offset:6144
	ds_read_b128 v[204:207], v140 offset:7168
	buffer_load_dwordx4 v136, s[16:19], s14 offen lds
	s_mov_b32 m0, s63
	s_nop 0
	buffer_load_dwordx4 v136, s[16:19], s74 offen lds
	s_waitcnt vmcnt(8) lgkmcnt(0)
	s_setprio 1
	v_mfma_f32_16x16x32_bf16 v[118:121], v[144:147], v[176:179], v[118:121]
	s_barrier
	v_mfma_f32_16x16x32_bf16 v[118:121], v[148:151], v[180:183], v[118:121]
	v_mfma_f32_16x16x32_bf16 v[114:117], v[152:155], v[176:179], v[114:117]
	v_mfma_f32_16x16x32_bf16 v[114:117], v[156:159], v[180:183], v[114:117]
	v_mfma_f32_16x16x32_bf16 v[126:129], v[160:163], v[176:179], v[126:129]
	v_mfma_f32_16x16x32_bf16 v[126:129], v[164:167], v[180:183], v[126:129]
	v_mfma_f32_16x16x32_bf16 v[122:125], v[168:171], v[176:179], v[122:125]
	v_mfma_f32_16x16x32_bf16 v[122:125], v[172:175], v[180:183], v[122:125]
	v_mfma_f32_16x16x32_bf16 v[98:101], v[168:171], v[184:187], v[98:101]
	v_mfma_f32_16x16x32_bf16 v[98:101], v[172:175], v[188:191], v[98:101]
	v_mfma_f32_16x16x32_bf16 v[106:109], v[160:163], v[184:187], v[106:109]
	v_mfma_f32_16x16x32_bf16 v[106:109], v[164:167], v[188:191], v[106:109]
	v_mfma_f32_16x16x32_bf16 v[102:105], v[152:155], v[184:187], v[102:105]
	v_mfma_f32_16x16x32_bf16 v[102:105], v[156:159], v[188:191], v[102:105]
	v_mfma_f32_16x16x32_bf16 v[110:113], v[144:147], v[184:187], v[110:113]
	v_mfma_f32_16x16x32_bf16 v[110:113], v[148:151], v[188:191], v[110:113]
	v_mfma_f32_16x16x32_bf16 v[94:97], v[144:147], v[192:195], v[94:97]
	v_mfma_f32_16x16x32_bf16 v[94:97], v[148:151], v[196:199], v[94:97]
	v_mfma_f32_16x16x32_bf16 v[86:89], v[152:155], v[192:195], v[86:89]
	v_mfma_f32_16x16x32_bf16 v[86:89], v[156:159], v[196:199], v[86:89]
	v_mfma_f32_16x16x32_bf16 v[90:93], v[160:163], v[192:195], v[90:93]
	v_mfma_f32_16x16x32_bf16 v[90:93], v[164:167], v[196:199], v[90:93]
	v_mfma_f32_16x16x32_bf16 v[82:85], v[168:171], v[192:195], v[82:85]
	v_mfma_f32_16x16x32_bf16 v[82:85], v[172:175], v[196:199], v[82:85]
	v_mfma_f32_16x16x32_bf16 v[70:73], v[168:171], v[200:203], v[70:73]
	v_mfma_f32_16x16x32_bf16 v[70:73], v[172:175], v[204:207], v[70:73]
	v_mfma_f32_16x16x32_bf16 v[74:77], v[160:163], v[200:203], v[74:77]
	v_mfma_f32_16x16x32_bf16 v[74:77], v[164:167], v[204:207], v[74:77]
	v_mfma_f32_16x16x32_bf16 v[66:69], v[152:155], v[200:203], v[66:69]
	v_mfma_f32_16x16x32_bf16 v[66:69], v[156:159], v[204:207], v[66:69]
	v_mfma_f32_16x16x32_bf16 v[78:81], v[144:147], v[200:203], v[78:81]
	v_mfma_f32_16x16x32_bf16 v[78:81], v[148:151], v[204:207], v[78:81]
	s_setprio 0
	s_barrier
	s_mov_b32 m0, s45
	s_mov_b32 s14, s18
	s_mov_b32 s15, s19
	ds_read_b128 v[176:179], v140 offset:16384
	ds_read_b128 v[180:183], v140 offset:17408
	ds_read_b128 v[184:187], v140 offset:18432
	ds_read_b128 v[188:191], v140 offset:19456
	ds_read_b128 v[192:195], v140 offset:20480
	ds_read_b128 v[196:199], v140 offset:21504
	ds_read_b128 v[200:203], v140 offset:22528
	ds_read_b128 v[204:207], v140 offset:23552
	buffer_load_dwordx4 v137, s[12:15], s79 offen lds
	s_mov_b32 m0, s46
	s_add_i32 s80, s79, 0x80000
	buffer_load_dwordx4 v137, s[12:15], s80 offen lds
	s_mov_b32 m0, s47
	s_add_i32 s80, s79, 0x100000
	buffer_load_dwordx4 v137, s[12:15], s80 offen lds
	s_mov_b32 m0, s48
	s_add_i32 s80, s79, 0x180000
	buffer_load_dwordx4 v137, s[12:15], s80 offen lds
	s_mov_b32 m0, s44
	s_add_i32 s80, s77, 0x80000
	buffer_load_dwordx4 v136, s[16:19], s77 offen lds
	s_mov_b32 m0, s49
	s_nop 0
	buffer_load_dwordx4 v136, s[16:19], s80 offen lds
	s_waitcnt vmcnt(8) lgkmcnt(0)
	s_setprio 1
	v_mfma_f32_16x16x32_bf16 v[62:65], v[144:147], v[176:179], v[62:65]
	s_barrier
	v_mfma_f32_16x16x32_bf16 v[62:65], v[148:151], v[180:183], v[62:65]
	v_mfma_f32_16x16x32_bf16 v[54:57], v[152:155], v[176:179], v[54:57]
	v_mfma_f32_16x16x32_bf16 v[54:57], v[156:159], v[180:183], v[54:57]
	v_mfma_f32_16x16x32_bf16 v[58:61], v[160:163], v[176:179], v[58:61]
	v_mfma_f32_16x16x32_bf16 v[58:61], v[164:167], v[180:183], v[58:61]
	v_mfma_f32_16x16x32_bf16 v[50:53], v[168:171], v[176:179], v[50:53]
	v_mfma_f32_16x16x32_bf16 v[50:53], v[172:175], v[180:183], v[50:53]
	v_mfma_f32_16x16x32_bf16 v[34:37], v[168:171], v[184:187], v[34:37]
	v_mfma_f32_16x16x32_bf16 v[34:37], v[172:175], v[188:191], v[34:37]
	v_mfma_f32_16x16x32_bf16 v[42:45], v[160:163], v[184:187], v[42:45]
	v_mfma_f32_16x16x32_bf16 v[42:45], v[164:167], v[188:191], v[42:45]
	v_mfma_f32_16x16x32_bf16 v[38:41], v[152:155], v[184:187], v[38:41]
	v_mfma_f32_16x16x32_bf16 v[38:41], v[156:159], v[188:191], v[38:41]
	v_mfma_f32_16x16x32_bf16 v[46:49], v[144:147], v[184:187], v[46:49]
	v_mfma_f32_16x16x32_bf16 v[46:49], v[148:151], v[188:191], v[46:49]
	v_mfma_f32_16x16x32_bf16 v[30:33], v[144:147], v[192:195], v[30:33]
	v_mfma_f32_16x16x32_bf16 v[30:33], v[148:151], v[196:199], v[30:33]
	v_mfma_f32_16x16x32_bf16 v[22:25], v[152:155], v[192:195], v[22:25]
	v_mfma_f32_16x16x32_bf16 v[22:25], v[156:159], v[196:199], v[22:25]
	v_mfma_f32_16x16x32_bf16 v[26:29], v[160:163], v[192:195], v[26:29]
	v_mfma_f32_16x16x32_bf16 v[26:29], v[164:167], v[196:199], v[26:29]
	v_mfma_f32_16x16x32_bf16 v[18:21], v[168:171], v[192:195], v[18:21]
	v_mfma_f32_16x16x32_bf16 v[18:21], v[172:175], v[196:199], v[18:21]
	v_mfma_f32_16x16x32_bf16 v[2:5], v[168:171], v[200:203], v[2:5]
	v_mfma_f32_16x16x32_bf16 v[2:5], v[172:175], v[204:207], v[2:5]
	v_mfma_f32_16x16x32_bf16 v[10:13], v[160:163], v[200:203], v[10:13]
	v_mfma_f32_16x16x32_bf16 v[10:13], v[164:167], v[204:207], v[10:13]
	v_mfma_f32_16x16x32_bf16 v[6:9], v[152:155], v[200:203], v[6:9]
	v_mfma_f32_16x16x32_bf16 v[6:9], v[156:159], v[204:207], v[6:9]
	v_mfma_f32_16x16x32_bf16 v[14:17], v[144:147], v[200:203], v[14:17]
	v_mfma_f32_16x16x32_bf16 v[14:17], v[148:151], v[204:207], v[14:17]
	s_setprio 0
	s_barrier
	ds_read_b128 v[144:147], v141
	ds_read_b128 v[148:151], v141 offset:1024
	ds_read_b128 v[152:155], v141 offset:2048
	ds_read_b128 v[156:159], v141 offset:3072
	ds_read_b128 v[160:163], v142
	ds_read_b128 v[164:167], v142 offset:1024
	ds_read_b128 v[168:171], v142 offset:2048
	ds_read_b128 v[172:175], v142 offset:3072
	s_mov_b32 m0, s50
	s_add_i32 s80, s77, 0x100000
	ds_read_b128 v[176:179], v140 offset:32768
	ds_read_b128 v[180:183], v140 offset:33792
	ds_read_b128 v[184:187], v140 offset:34816
	ds_read_b128 v[188:191], v140 offset:35840
	ds_read_b128 v[192:195], v140 offset:36864
	ds_read_b128 v[196:199], v140 offset:37888
	ds_read_b128 v[200:203], v140 offset:38912
	ds_read_b128 v[204:207], v140 offset:39936
	buffer_load_dwordx4 v136, s[16:19], s80 offen lds
	s_mov_b32 m0, s51
	s_add_i32 s80, s77, 0x180000
	buffer_load_dwordx4 v136, s[16:19], s80 offen lds
	s_waitcnt vmcnt(8) lgkmcnt(0)
	s_setprio 1
	v_mfma_f32_16x16x32_bf16 v[118:121], v[144:147], v[176:179], v[118:121]
	s_barrier
	v_mfma_f32_16x16x32_bf16 v[118:121], v[148:151], v[180:183], v[118:121]
	v_mfma_f32_16x16x32_bf16 v[114:117], v[152:155], v[176:179], v[114:117]
	v_mfma_f32_16x16x32_bf16 v[114:117], v[156:159], v[180:183], v[114:117]
	v_mfma_f32_16x16x32_bf16 v[126:129], v[160:163], v[176:179], v[126:129]
	v_mfma_f32_16x16x32_bf16 v[126:129], v[164:167], v[180:183], v[126:129]
	v_mfma_f32_16x16x32_bf16 v[122:125], v[168:171], v[176:179], v[122:125]
	v_mfma_f32_16x16x32_bf16 v[122:125], v[172:175], v[180:183], v[122:125]
	v_mfma_f32_16x16x32_bf16 v[98:101], v[168:171], v[184:187], v[98:101]
	v_mfma_f32_16x16x32_bf16 v[98:101], v[172:175], v[188:191], v[98:101]
	v_mfma_f32_16x16x32_bf16 v[106:109], v[160:163], v[184:187], v[106:109]
	v_mfma_f32_16x16x32_bf16 v[106:109], v[164:167], v[188:191], v[106:109]
	v_mfma_f32_16x16x32_bf16 v[102:105], v[152:155], v[184:187], v[102:105]
	v_mfma_f32_16x16x32_bf16 v[102:105], v[156:159], v[188:191], v[102:105]
	v_mfma_f32_16x16x32_bf16 v[110:113], v[144:147], v[184:187], v[110:113]
	v_mfma_f32_16x16x32_bf16 v[110:113], v[148:151], v[188:191], v[110:113]
	v_mfma_f32_16x16x32_bf16 v[94:97], v[144:147], v[192:195], v[94:97]
	v_mfma_f32_16x16x32_bf16 v[94:97], v[148:151], v[196:199], v[94:97]
	v_mfma_f32_16x16x32_bf16 v[86:89], v[152:155], v[192:195], v[86:89]
	v_mfma_f32_16x16x32_bf16 v[86:89], v[156:159], v[196:199], v[86:89]
	v_mfma_f32_16x16x32_bf16 v[90:93], v[160:163], v[192:195], v[90:93]
	v_mfma_f32_16x16x32_bf16 v[90:93], v[164:167], v[196:199], v[90:93]
	v_mfma_f32_16x16x32_bf16 v[82:85], v[168:171], v[192:195], v[82:85]
	v_mfma_f32_16x16x32_bf16 v[82:85], v[172:175], v[196:199], v[82:85]
	v_mfma_f32_16x16x32_bf16 v[70:73], v[168:171], v[200:203], v[70:73]
	v_mfma_f32_16x16x32_bf16 v[70:73], v[172:175], v[204:207], v[70:73]
	v_mfma_f32_16x16x32_bf16 v[74:77], v[160:163], v[200:203], v[74:77]
	v_mfma_f32_16x16x32_bf16 v[74:77], v[164:167], v[204:207], v[74:77]
	v_mfma_f32_16x16x32_bf16 v[66:69], v[152:155], v[200:203], v[66:69]
	v_mfma_f32_16x16x32_bf16 v[66:69], v[156:159], v[204:207], v[66:69]
	v_mfma_f32_16x16x32_bf16 v[78:81], v[144:147], v[200:203], v[78:81]
	v_mfma_f32_16x16x32_bf16 v[78:81], v[148:151], v[204:207], v[78:81]
	s_setprio 0
	s_barrier
	s_mov_b32 m0, s53
	s_or_b32 s80, s79, 0x80
	ds_read_b128 v[176:179], v140 offset:49152
	ds_read_b128 v[180:183], v140 offset:50176
	ds_read_b128 v[184:187], v140 offset:51200
	ds_read_b128 v[188:191], v140 offset:52224
	ds_read_b128 v[192:195], v140 offset:53248
	ds_read_b128 v[196:199], v140 offset:54272
	ds_read_b128 v[200:203], v140 offset:55296
	ds_read_b128 v[204:207], v140 offset:56320
	buffer_load_dwordx4 v137, s[12:15], s80 offen lds
	s_add_i32 s80, s79, 0x80080
	s_mov_b32 m0, s54
	s_add_i32 s77, s77, 0x80080
	buffer_load_dwordx4 v137, s[12:15], s80 offen lds
	s_add_i32 s80, s79, 0x100080
	s_mov_b32 m0, s57
	s_add_i32 s79, s79, 0x180080
	buffer_load_dwordx4 v137, s[12:15], s80 offen lds
	s_mov_b32 m0, s58
	s_nop 0
	buffer_load_dwordx4 v137, s[12:15], s79 offen lds
	s_mov_b32 m0, s55
	s_nop 0
	buffer_load_dwordx4 v136, s[16:19], s78 offen lds
	s_mov_b32 m0, s56
	s_nop 0
	buffer_load_dwordx4 v136, s[16:19], s77 offen lds
	s_waitcnt vmcnt(8) lgkmcnt(0)
	s_setprio 1
	v_mfma_f32_16x16x32_bf16 v[62:65], v[144:147], v[176:179], v[62:65]
	s_barrier
	v_mfma_f32_16x16x32_bf16 v[62:65], v[148:151], v[180:183], v[62:65]
	v_mfma_f32_16x16x32_bf16 v[54:57], v[152:155], v[176:179], v[54:57]
	v_mfma_f32_16x16x32_bf16 v[54:57], v[156:159], v[180:183], v[54:57]
	v_mfma_f32_16x16x32_bf16 v[58:61], v[160:163], v[176:179], v[58:61]
	v_mfma_f32_16x16x32_bf16 v[58:61], v[164:167], v[180:183], v[58:61]
	v_mfma_f32_16x16x32_bf16 v[50:53], v[168:171], v[176:179], v[50:53]
	v_mfma_f32_16x16x32_bf16 v[50:53], v[172:175], v[180:183], v[50:53]
	v_mfma_f32_16x16x32_bf16 v[34:37], v[168:171], v[184:187], v[34:37]
	v_mfma_f32_16x16x32_bf16 v[34:37], v[172:175], v[188:191], v[34:37]
	v_mfma_f32_16x16x32_bf16 v[42:45], v[160:163], v[184:187], v[42:45]
	v_mfma_f32_16x16x32_bf16 v[42:45], v[164:167], v[188:191], v[42:45]
	v_mfma_f32_16x16x32_bf16 v[38:41], v[152:155], v[184:187], v[38:41]
	v_mfma_f32_16x16x32_bf16 v[38:41], v[156:159], v[188:191], v[38:41]
	v_mfma_f32_16x16x32_bf16 v[46:49], v[144:147], v[184:187], v[46:49]
	v_mfma_f32_16x16x32_bf16 v[46:49], v[148:151], v[188:191], v[46:49]
	v_mfma_f32_16x16x32_bf16 v[30:33], v[144:147], v[192:195], v[30:33]
	v_mfma_f32_16x16x32_bf16 v[30:33], v[148:151], v[196:199], v[30:33]
	v_mfma_f32_16x16x32_bf16 v[22:25], v[152:155], v[192:195], v[22:25]
	v_mfma_f32_16x16x32_bf16 v[22:25], v[156:159], v[196:199], v[22:25]
	v_mfma_f32_16x16x32_bf16 v[26:29], v[160:163], v[192:195], v[26:29]
	v_mfma_f32_16x16x32_bf16 v[26:29], v[164:167], v[196:199], v[26:29]
	v_mfma_f32_16x16x32_bf16 v[18:21], v[168:171], v[192:195], v[18:21]
	v_mfma_f32_16x16x32_bf16 v[18:21], v[172:175], v[196:199], v[18:21]
	v_mfma_f32_16x16x32_bf16 v[2:5], v[168:171], v[200:203], v[2:5]
	v_mfma_f32_16x16x32_bf16 v[2:5], v[172:175], v[204:207], v[2:5]
	v_mfma_f32_16x16x32_bf16 v[10:13], v[160:163], v[200:203], v[10:13]
	v_mfma_f32_16x16x32_bf16 v[10:13], v[164:167], v[204:207], v[10:13]
	v_mfma_f32_16x16x32_bf16 v[6:9], v[152:155], v[200:203], v[6:9]
	v_mfma_f32_16x16x32_bf16 v[6:9], v[156:159], v[204:207], v[6:9]
	v_mfma_f32_16x16x32_bf16 v[14:17], v[144:147], v[200:203], v[14:17]
	v_mfma_f32_16x16x32_bf16 v[14:17], v[148:151], v[204:207], v[14:17]
	s_setprio 0
	s_barrier
	s_add_i32 s76, s76, 2
	s_addk_i32 s74, 0x100
	s_addk_i32 s75, 0x100
	s_cmp_ge_i32 s76, s27
	s_cbranch_scc0 .LBB0_1382
	s_and_b64 vcc, exec, s[42:43]
	s_cbranch_vccz .LBB0_1385

.LBB0_1402:
	ds_read_b128 v[146:149], v138
	ds_read_b128 v[150:153], v138 offset:1024
	ds_read_b128 v[154:157], v138 offset:2048
	ds_read_b128 v[158:161], v138 offset:3072
	ds_read_b128 v[162:165], v139
	ds_read_b128 v[166:169], v139 offset:1024
	ds_read_b128 v[170:173], v139 offset:2048
	ds_read_b128 v[174:177], v139 offset:3072
	s_add_i32 s22, s75, 0xffe80080
	s_cmp_eq_u32 s62, s77
	s_cselect_b32 s78, s73, s22
	s_cselect_b32 s80, s74, s76
	s_or_b32 s79, s78, 0x80
	s_add_i32 s22, s75, 0xfff80000
	s_mov_b32 m0, s63
	ds_read_b128 v[178:181], v140
	ds_read_b128 v[182:185], v140 offset:1024
	ds_read_b128 v[186:189], v140 offset:2048
	ds_read_b128 v[190:193], v140 offset:3072
	ds_read_b128 v[194:197], v140 offset:4096
	ds_read_b128 v[198:201], v140 offset:5120
	ds_read_b128 v[202:205], v140 offset:6144
	ds_read_b128 v[206:209], v140 offset:7168
	buffer_load_dwordx4 v136, s[16:19], s22 offen lds
	s_mov_b32 m0, s64
	s_nop 0
	buffer_load_dwordx4 v136, s[16:19], s75 offen lds
	s_waitcnt vmcnt(8) lgkmcnt(0)
	s_setprio 1
	v_mfma_f32_16x16x32_bf16 v[118:121], v[146:149], v[178:181], v[118:121]
	s_barrier
	v_mfma_f32_16x16x32_bf16 v[118:121], v[150:153], v[182:185], v[118:121]
	v_mfma_f32_16x16x32_bf16 v[114:117], v[154:157], v[178:181], v[114:117]
	v_mfma_f32_16x16x32_bf16 v[114:117], v[158:161], v[182:185], v[114:117]
	v_mfma_f32_16x16x32_bf16 v[126:129], v[162:165], v[178:181], v[126:129]
	v_mfma_f32_16x16x32_bf16 v[126:129], v[166:169], v[182:185], v[126:129]
	v_mfma_f32_16x16x32_bf16 v[122:125], v[170:173], v[178:181], v[122:125]
	v_mfma_f32_16x16x32_bf16 v[122:125], v[174:177], v[182:185], v[122:125]
	v_mfma_f32_16x16x32_bf16 v[98:101], v[170:173], v[186:189], v[98:101]
	v_mfma_f32_16x16x32_bf16 v[98:101], v[174:177], v[190:193], v[98:101]
	v_mfma_f32_16x16x32_bf16 v[106:109], v[162:165], v[186:189], v[106:109]
	v_mfma_f32_16x16x32_bf16 v[106:109], v[166:169], v[190:193], v[106:109]
	v_mfma_f32_16x16x32_bf16 v[102:105], v[154:157], v[186:189], v[102:105]
	v_mfma_f32_16x16x32_bf16 v[102:105], v[158:161], v[190:193], v[102:105]
	v_mfma_f32_16x16x32_bf16 v[110:113], v[146:149], v[186:189], v[110:113]
	v_mfma_f32_16x16x32_bf16 v[110:113], v[150:153], v[190:193], v[110:113]
	v_mfma_f32_16x16x32_bf16 v[94:97], v[146:149], v[194:197], v[94:97]
	v_mfma_f32_16x16x32_bf16 v[94:97], v[150:153], v[198:201], v[94:97]
	v_mfma_f32_16x16x32_bf16 v[86:89], v[154:157], v[194:197], v[86:89]
	v_mfma_f32_16x16x32_bf16 v[86:89], v[158:161], v[198:201], v[86:89]
	v_mfma_f32_16x16x32_bf16 v[90:93], v[162:165], v[194:197], v[90:93]
	v_mfma_f32_16x16x32_bf16 v[90:93], v[166:169], v[198:201], v[90:93]
	v_mfma_f32_16x16x32_bf16 v[82:85], v[170:173], v[194:197], v[82:85]
	v_mfma_f32_16x16x32_bf16 v[82:85], v[174:177], v[198:201], v[82:85]
	v_mfma_f32_16x16x32_bf16 v[70:73], v[170:173], v[202:205], v[70:73]
	v_mfma_f32_16x16x32_bf16 v[70:73], v[174:177], v[206:209], v[70:73]
	v_mfma_f32_16x16x32_bf16 v[74:77], v[162:165], v[202:205], v[74:77]
	v_mfma_f32_16x16x32_bf16 v[74:77], v[166:169], v[206:209], v[74:77]
	v_mfma_f32_16x16x32_bf16 v[66:69], v[154:157], v[202:205], v[66:69]
	v_mfma_f32_16x16x32_bf16 v[66:69], v[158:161], v[206:209], v[66:69]
	v_mfma_f32_16x16x32_bf16 v[78:81], v[146:149], v[202:205], v[78:81]
	v_mfma_f32_16x16x32_bf16 v[78:81], v[150:153], v[206:209], v[78:81]
	s_setprio 0
	s_barrier
	s_mov_b32 m0, s31
	s_mov_b32 s22, s18
	s_mov_b32 s23, s19
	ds_read_b128 v[178:181], v140 offset:16384
	ds_read_b128 v[182:185], v140 offset:17408
	ds_read_b128 v[186:189], v140 offset:18432
	ds_read_b128 v[190:193], v140 offset:19456
	ds_read_b128 v[194:197], v140 offset:20480
	ds_read_b128 v[198:201], v140 offset:21504
	ds_read_b128 v[202:205], v140 offset:22528
	ds_read_b128 v[206:209], v140 offset:23552
	buffer_load_dwordx4 v137, s[20:23], s80 offen lds
	s_mov_b32 m0, s48
	s_add_i32 s81, s80, 0x80000
	buffer_load_dwordx4 v137, s[20:23], s81 offen lds
	s_mov_b32 m0, s49
	s_add_i32 s81, s80, 0x100000
	buffer_load_dwordx4 v137, s[20:23], s81 offen lds
	s_mov_b32 m0, s50
	s_add_i32 s81, s80, 0x180000
	buffer_load_dwordx4 v137, s[20:23], s81 offen lds
	s_mov_b32 m0, s30
	s_add_i32 s81, s78, 0x80000
	buffer_load_dwordx4 v136, s[16:19], s78 offen lds
	s_mov_b32 m0, s51
	s_nop 0
	buffer_load_dwordx4 v136, s[16:19], s81 offen lds
	s_waitcnt vmcnt(8) lgkmcnt(0)
	s_setprio 1
	v_mfma_f32_16x16x32_bf16 v[62:65], v[146:149], v[178:181], v[62:65]
	s_barrier
	v_mfma_f32_16x16x32_bf16 v[62:65], v[150:153], v[182:185], v[62:65]
	v_mfma_f32_16x16x32_bf16 v[54:57], v[154:157], v[178:181], v[54:57]
	v_mfma_f32_16x16x32_bf16 v[54:57], v[158:161], v[182:185], v[54:57]
	v_mfma_f32_16x16x32_bf16 v[58:61], v[162:165], v[178:181], v[58:61]
	v_mfma_f32_16x16x32_bf16 v[58:61], v[166:169], v[182:185], v[58:61]
	v_mfma_f32_16x16x32_bf16 v[50:53], v[170:173], v[178:181], v[50:53]
	v_mfma_f32_16x16x32_bf16 v[50:53], v[174:177], v[182:185], v[50:53]
	v_mfma_f32_16x16x32_bf16 v[34:37], v[170:173], v[186:189], v[34:37]
	v_mfma_f32_16x16x32_bf16 v[34:37], v[174:177], v[190:193], v[34:37]
	v_mfma_f32_16x16x32_bf16 v[42:45], v[162:165], v[186:189], v[42:45]
	v_mfma_f32_16x16x32_bf16 v[42:45], v[166:169], v[190:193], v[42:45]
	v_mfma_f32_16x16x32_bf16 v[38:41], v[154:157], v[186:189], v[38:41]
	v_mfma_f32_16x16x32_bf16 v[38:41], v[158:161], v[190:193], v[38:41]
	v_mfma_f32_16x16x32_bf16 v[46:49], v[146:149], v[186:189], v[46:49]
	v_mfma_f32_16x16x32_bf16 v[46:49], v[150:153], v[190:193], v[46:49]
	v_mfma_f32_16x16x32_bf16 v[30:33], v[146:149], v[194:197], v[30:33]
	v_mfma_f32_16x16x32_bf16 v[30:33], v[150:153], v[198:201], v[30:33]
	v_mfma_f32_16x16x32_bf16 v[22:25], v[154:157], v[194:197], v[22:25]
	v_mfma_f32_16x16x32_bf16 v[22:25], v[158:161], v[198:201], v[22:25]
	v_mfma_f32_16x16x32_bf16 v[26:29], v[162:165], v[194:197], v[26:29]
	v_mfma_f32_16x16x32_bf16 v[26:29], v[166:169], v[198:201], v[26:29]
	v_mfma_f32_16x16x32_bf16 v[18:21], v[170:173], v[194:197], v[18:21]
	v_mfma_f32_16x16x32_bf16 v[18:21], v[174:177], v[198:201], v[18:21]
	v_mfma_f32_16x16x32_bf16 v[2:5], v[170:173], v[202:205], v[2:5]
	v_mfma_f32_16x16x32_bf16 v[2:5], v[174:177], v[206:209], v[2:5]
	v_mfma_f32_16x16x32_bf16 v[10:13], v[162:165], v[202:205], v[10:13]
	v_mfma_f32_16x16x32_bf16 v[10:13], v[166:169], v[206:209], v[10:13]
	v_mfma_f32_16x16x32_bf16 v[6:9], v[154:157], v[202:205], v[6:9]
	v_mfma_f32_16x16x32_bf16 v[6:9], v[158:161], v[206:209], v[6:9]
	v_mfma_f32_16x16x32_bf16 v[14:17], v[146:149], v[202:205], v[14:17]
	v_mfma_f32_16x16x32_bf16 v[14:17], v[150:153], v[206:209], v[14:17]
	s_setprio 0
	s_barrier
	ds_read_b128 v[146:149], v141
	ds_read_b128 v[150:153], v141 offset:1024
	ds_read_b128 v[154:157], v141 offset:2048
	ds_read_b128 v[158:161], v141 offset:3072
	ds_read_b128 v[162:165], v142
	ds_read_b128 v[166:169], v142 offset:1024
	ds_read_b128 v[170:173], v142 offset:2048
	ds_read_b128 v[174:177], v142 offset:3072
	s_mov_b32 m0, s52
	s_add_i32 s81, s78, 0x100000
	ds_read_b128 v[178:181], v140 offset:32768
	ds_read_b128 v[182:185], v140 offset:33792
	ds_read_b128 v[186:189], v140 offset:34816
	ds_read_b128 v[190:193], v140 offset:35840
	ds_read_b128 v[194:197], v140 offset:36864
	ds_read_b128 v[198:201], v140 offset:37888
	ds_read_b128 v[202:205], v140 offset:38912
	ds_read_b128 v[206:209], v140 offset:39936
	buffer_load_dwordx4 v136, s[16:19], s81 offen lds
	s_mov_b32 m0, s53
	s_add_i32 s81, s78, 0x180000
	buffer_load_dwordx4 v136, s[16:19], s81 offen lds
	s_waitcnt vmcnt(8) lgkmcnt(0)
	s_setprio 1
	v_mfma_f32_16x16x32_bf16 v[118:121], v[146:149], v[178:181], v[118:121]
	s_barrier
	v_mfma_f32_16x16x32_bf16 v[118:121], v[150:153], v[182:185], v[118:121]
	v_mfma_f32_16x16x32_bf16 v[114:117], v[154:157], v[178:181], v[114:117]
	v_mfma_f32_16x16x32_bf16 v[114:117], v[158:161], v[182:185], v[114:117]
	v_mfma_f32_16x16x32_bf16 v[126:129], v[162:165], v[178:181], v[126:129]
	v_mfma_f32_16x16x32_bf16 v[126:129], v[166:169], v[182:185], v[126:129]
	v_mfma_f32_16x16x32_bf16 v[122:125], v[170:173], v[178:181], v[122:125]
	v_mfma_f32_16x16x32_bf16 v[122:125], v[174:177], v[182:185], v[122:125]
	v_mfma_f32_16x16x32_bf16 v[98:101], v[170:173], v[186:189], v[98:101]
	v_mfma_f32_16x16x32_bf16 v[98:101], v[174:177], v[190:193], v[98:101]
	v_mfma_f32_16x16x32_bf16 v[106:109], v[162:165], v[186:189], v[106:109]
	v_mfma_f32_16x16x32_bf16 v[106:109], v[166:169], v[190:193], v[106:109]
	v_mfma_f32_16x16x32_bf16 v[102:105], v[154:157], v[186:189], v[102:105]
	v_mfma_f32_16x16x32_bf16 v[102:105], v[158:161], v[190:193], v[102:105]
	v_mfma_f32_16x16x32_bf16 v[110:113], v[146:149], v[186:189], v[110:113]
	v_mfma_f32_16x16x32_bf16 v[110:113], v[150:153], v[190:193], v[110:113]
	v_mfma_f32_16x16x32_bf16 v[94:97], v[146:149], v[194:197], v[94:97]
	v_mfma_f32_16x16x32_bf16 v[94:97], v[150:153], v[198:201], v[94:97]
	v_mfma_f32_16x16x32_bf16 v[86:89], v[154:157], v[194:197], v[86:89]
	v_mfma_f32_16x16x32_bf16 v[86:89], v[158:161], v[198:201], v[86:89]
	v_mfma_f32_16x16x32_bf16 v[90:93], v[162:165], v[194:197], v[90:93]
	v_mfma_f32_16x16x32_bf16 v[90:93], v[166:169], v[198:201], v[90:93]
	v_mfma_f32_16x16x32_bf16 v[82:85], v[170:173], v[194:197], v[82:85]
	v_mfma_f32_16x16x32_bf16 v[82:85], v[174:177], v[198:201], v[82:85]
	v_mfma_f32_16x16x32_bf16 v[70:73], v[170:173], v[202:205], v[70:73]
	v_mfma_f32_16x16x32_bf16 v[70:73], v[174:177], v[206:209], v[70:73]
	v_mfma_f32_16x16x32_bf16 v[74:77], v[162:165], v[202:205], v[74:77]
	v_mfma_f32_16x16x32_bf16 v[74:77], v[166:169], v[206:209], v[74:77]
	v_mfma_f32_16x16x32_bf16 v[66:69], v[154:157], v[202:205], v[66:69]
	v_mfma_f32_16x16x32_bf16 v[66:69], v[158:161], v[206:209], v[66:69]
	v_mfma_f32_16x16x32_bf16 v[78:81], v[146:149], v[202:205], v[78:81]
	v_mfma_f32_16x16x32_bf16 v[78:81], v[150:153], v[206:209], v[78:81]
	s_setprio 0
	s_barrier
	s_mov_b32 m0, s54
	s_or_b32 s81, s80, 0x80
	ds_read_b128 v[178:181], v140 offset:49152
	ds_read_b128 v[182:185], v140 offset:50176
	ds_read_b128 v[186:189], v140 offset:51200
	ds_read_b128 v[190:193], v140 offset:52224
	ds_read_b128 v[194:197], v140 offset:53248
	ds_read_b128 v[198:201], v140 offset:54272
	ds_read_b128 v[202:205], v140 offset:55296
	ds_read_b128 v[206:209], v140 offset:56320
	buffer_load_dwordx4 v137, s[20:23], s81 offen lds
	s_add_i32 s81, s80, 0x80080
	s_mov_b32 m0, s55
	s_add_i32 s78, s78, 0x80080
	buffer_load_dwordx4 v137, s[20:23], s81 offen lds
	s_add_i32 s81, s80, 0x100080
	s_mov_b32 m0, s58
	s_add_i32 s80, s80, 0x180080
	buffer_load_dwordx4 v137, s[20:23], s81 offen lds
	s_mov_b32 m0, s59
	s_nop 0
	buffer_load_dwordx4 v137, s[20:23], s80 offen lds
	s_mov_b32 m0, s56
	s_nop 0
	buffer_load_dwordx4 v136, s[16:19], s79 offen lds
	s_mov_b32 m0, s57
	s_nop 0
	buffer_load_dwordx4 v136, s[16:19], s78 offen lds
	s_waitcnt vmcnt(8) lgkmcnt(0)
	s_setprio 1
	v_mfma_f32_16x16x32_bf16 v[62:65], v[146:149], v[178:181], v[62:65]
	s_barrier
	v_mfma_f32_16x16x32_bf16 v[62:65], v[150:153], v[182:185], v[62:65]
	v_mfma_f32_16x16x32_bf16 v[54:57], v[154:157], v[178:181], v[54:57]
	v_mfma_f32_16x16x32_bf16 v[54:57], v[158:161], v[182:185], v[54:57]
	v_mfma_f32_16x16x32_bf16 v[58:61], v[162:165], v[178:181], v[58:61]
	v_mfma_f32_16x16x32_bf16 v[58:61], v[166:169], v[182:185], v[58:61]
	v_mfma_f32_16x16x32_bf16 v[50:53], v[170:173], v[178:181], v[50:53]
	v_mfma_f32_16x16x32_bf16 v[50:53], v[174:177], v[182:185], v[50:53]
	v_mfma_f32_16x16x32_bf16 v[34:37], v[170:173], v[186:189], v[34:37]
	v_mfma_f32_16x16x32_bf16 v[34:37], v[174:177], v[190:193], v[34:37]
	v_mfma_f32_16x16x32_bf16 v[42:45], v[162:165], v[186:189], v[42:45]
	v_mfma_f32_16x16x32_bf16 v[42:45], v[166:169], v[190:193], v[42:45]
	v_mfma_f32_16x16x32_bf16 v[38:41], v[154:157], v[186:189], v[38:41]
	v_mfma_f32_16x16x32_bf16 v[38:41], v[158:161], v[190:193], v[38:41]
	v_mfma_f32_16x16x32_bf16 v[46:49], v[146:149], v[186:189], v[46:49]
	v_mfma_f32_16x16x32_bf16 v[46:49], v[150:153], v[190:193], v[46:49]
	v_mfma_f32_16x16x32_bf16 v[30:33], v[146:149], v[194:197], v[30:33]
	v_mfma_f32_16x16x32_bf16 v[30:33], v[150:153], v[198:201], v[30:33]
	v_mfma_f32_16x16x32_bf16 v[22:25], v[154:157], v[194:197], v[22:25]
	v_mfma_f32_16x16x32_bf16 v[22:25], v[158:161], v[198:201], v[22:25]
	v_mfma_f32_16x16x32_bf16 v[26:29], v[162:165], v[194:197], v[26:29]
	v_mfma_f32_16x16x32_bf16 v[26:29], v[166:169], v[198:201], v[26:29]
	v_mfma_f32_16x16x32_bf16 v[18:21], v[170:173], v[194:197], v[18:21]
	v_mfma_f32_16x16x32_bf16 v[18:21], v[174:177], v[198:201], v[18:21]
	v_mfma_f32_16x16x32_bf16 v[2:5], v[170:173], v[202:205], v[2:5]
	v_mfma_f32_16x16x32_bf16 v[2:5], v[174:177], v[206:209], v[2:5]
	v_mfma_f32_16x16x32_bf16 v[10:13], v[162:165], v[202:205], v[10:13]
	v_mfma_f32_16x16x32_bf16 v[10:13], v[166:169], v[206:209], v[10:13]
	v_mfma_f32_16x16x32_bf16 v[6:9], v[154:157], v[202:205], v[6:9]
	v_mfma_f32_16x16x32_bf16 v[6:9], v[158:161], v[206:209], v[6:9]
	v_mfma_f32_16x16x32_bf16 v[14:17], v[146:149], v[202:205], v[14:17]
	v_mfma_f32_16x16x32_bf16 v[14:17], v[150:153], v[206:209], v[14:17]
	s_setprio 0
	s_barrier
	s_add_i32 s77, s77, 2
	s_addk_i32 s75, 0x100
	s_addk_i32 s76, 0x100
	s_cmp_ge_i32 s77, s13
	s_cbranch_scc0 .LBB0_1402
	s_and_b64 vcc, exec, s[46:47]
	s_cbranch_vccz .LBB0_1405

.LBB0_1420:
	ds_read_b128 v[146:149], v138
	ds_read_b128 v[150:153], v138 offset:1024
	ds_read_b128 v[154:157], v138 offset:2048
	ds_read_b128 v[158:161], v138 offset:3072
	ds_read_b128 v[162:165], v139
	ds_read_b128 v[166:169], v139 offset:1024
	ds_read_b128 v[170:173], v139 offset:2048
	ds_read_b128 v[174:177], v139 offset:3072
	s_add_i32 s14, s73, 0xfff40080
	s_cmp_eq_u32 s60, s75
	s_cselect_b32 s76, s71, s14
	s_cselect_b32 s78, s72, s74
	s_or_b32 s77, s76, 0x80
	s_add_i32 s14, s73, 0xfffc0000
	s_mov_b32 m0, s61
	ds_read_b128 v[178:181], v140
	ds_read_b128 v[182:185], v140 offset:1024
	ds_read_b128 v[186:189], v140 offset:2048
	ds_read_b128 v[190:193], v140 offset:3072
	ds_read_b128 v[194:197], v140 offset:4096
	ds_read_b128 v[198:201], v140 offset:5120
	ds_read_b128 v[202:205], v140 offset:6144
	ds_read_b128 v[206:209], v140 offset:7168
	buffer_load_dwordx4 v136, s[16:19], s14 offen lds
	s_mov_b32 m0, s62
	s_nop 0
	buffer_load_dwordx4 v136, s[16:19], s73 offen lds
	s_waitcnt vmcnt(8) lgkmcnt(0)
	s_setprio 1
	s_waitcnt lgkmcnt(6)
	v_mfma_f32_16x16x128_f8f6f4 v[118:121], v[146:153], v[178:185], v[118:121]
	s_barrier
	v_mfma_f32_16x16x128_f8f6f4 v[114:117], v[154:161], v[178:185], v[114:117]
	s_waitcnt lgkmcnt(4)
	v_mfma_f32_16x16x128_f8f6f4 v[110:113], v[146:153], v[186:193], v[110:113]
	v_mfma_f32_16x16x128_f8f6f4 v[102:105], v[154:161], v[186:193], v[102:105]
	v_mfma_f32_16x16x128_f8f6f4 v[126:129], v[162:169], v[178:185], v[126:129]
	v_mfma_f32_16x16x128_f8f6f4 v[122:125], v[170:177], v[178:185], v[122:125]
	v_mfma_f32_16x16x128_f8f6f4 v[106:109], v[162:169], v[186:193], v[106:109]
	v_mfma_f32_16x16x128_f8f6f4 v[98:101], v[170:177], v[186:193], v[98:101]
	s_waitcnt lgkmcnt(2)
	v_mfma_f32_16x16x128_f8f6f4 v[210:213], v[146:153], v[194:201], v[94:97]
	v_mfma_f32_16x16x128_f8f6f4 v[214:217], v[154:161], v[194:201], v[86:89]
	s_waitcnt lgkmcnt(0)
	v_mfma_f32_16x16x128_f8f6f4 v[218:221], v[146:153], v[202:209], v[78:81]
	v_mfma_f32_16x16x128_f8f6f4 v[222:225], v[154:161], v[202:209], v[70:73]
	v_mfma_f32_16x16x128_f8f6f4 v[178:181], v[162:169], v[194:201], v[90:93]
	v_mfma_f32_16x16x128_f8f6f4 v[182:185], v[170:177], v[194:201], v[82:85]
	v_mfma_f32_16x16x128_f8f6f4 v[186:189], v[162:169], v[202:209], v[74:77]
	v_mfma_f32_16x16x128_f8f6f4 v[190:193], v[170:177], v[202:209], v[66:69]
	s_setprio 0
	s_barrier
	s_mov_b32 m0, s31
	s_mov_b32 s14, s18
	s_mov_b32 s15, s19
	s_nop 1
	ds_read_b128 v[66:69], v140 offset:16384
	ds_read_b128 v[70:73], v140 offset:17408
	ds_read_b128 v[74:77], v140 offset:18432
	ds_read_b128 v[78:81], v140 offset:19456
	ds_read_b128 v[82:85], v140 offset:20480
	ds_read_b128 v[86:89], v140 offset:21504
	ds_read_b128 v[90:93], v140 offset:22528
	ds_read_b128 v[94:97], v140 offset:23552
	buffer_load_dwordx4 v137, s[12:15], s78 offen lds
	s_mov_b32 m0, s46
	s_add_i32 s79, s78, 0x40000
	buffer_load_dwordx4 v137, s[12:15], s79 offen lds
	s_mov_b32 m0, s47
	s_add_i32 s79, s78, 0x80000
	buffer_load_dwordx4 v137, s[12:15], s79 offen lds
	s_mov_b32 m0, s48
	s_add_i32 s79, s78, 0xc0000
	buffer_load_dwordx4 v137, s[12:15], s79 offen lds
	s_mov_b32 m0, s30
	s_add_i32 s79, s76, 0x40000
	buffer_load_dwordx4 v136, s[16:19], s76 offen lds
	s_mov_b32 m0, s49
	s_nop 0
	buffer_load_dwordx4 v136, s[16:19], s79 offen lds
	s_waitcnt vmcnt(8) lgkmcnt(0)
	s_setprio 1
	s_waitcnt lgkmcnt(6)
	v_mfma_f32_16x16x128_f8f6f4 v[62:65], v[146:153], v[66:73], v[62:65]
	s_barrier
	v_mfma_f32_16x16x128_f8f6f4 v[54:57], v[154:161], v[66:73], v[54:57]
	s_waitcnt lgkmcnt(4)
	v_mfma_f32_16x16x128_f8f6f4 v[46:49], v[146:153], v[74:81], v[46:49]
	v_mfma_f32_16x16x128_f8f6f4 v[58:61], v[162:169], v[66:73], v[58:61]
	v_mfma_f32_16x16x128_f8f6f4 v[50:53], v[170:177], v[66:73], v[50:53]
	v_mfma_f32_16x16x128_f8f6f4 v[42:45], v[162:169], v[74:81], v[42:45]
	v_mfma_f32_16x16x128_f8f6f4 v[202:205], v[154:161], v[74:81], v[38:41]
	s_waitcnt lgkmcnt(2)
	v_mfma_f32_16x16x128_f8f6f4 v[206:209], v[146:153], v[82:89], v[30:33]
	v_mfma_f32_16x16x128_f8f6f4 v[226:229], v[154:161], v[82:89], v[22:25]
	s_waitcnt lgkmcnt(0)
	v_mfma_f32_16x16x128_f8f6f4 v[230:233], v[146:153], v[90:97], v[14:17]
	v_mfma_f32_16x16x128_f8f6f4 v[234:237], v[154:161], v[90:97], v[6:9]
	v_mfma_f32_16x16x128_f8f6f4 v[238:241], v[170:177], v[74:81], v[34:37]
	v_mfma_f32_16x16x128_f8f6f4 v[242:245], v[162:169], v[82:89], v[26:29]
	v_mfma_f32_16x16x128_f8f6f4 v[246:249], v[170:177], v[82:89], v[18:21]
	v_mfma_f32_16x16x128_f8f6f4 v[250:253], v[162:169], v[90:97], v[10:13]
	v_mfma_f32_16x16x128_f8f6f4 v[130:133], v[170:177], v[90:97], v[2:5]
	s_setprio 0
	s_barrier
	s_nop 4
	ds_read_b128 v[2:5], v141
	ds_read_b128 v[6:9], v141 offset:1024
	ds_read_b128 v[146:149], v141 offset:2048
	ds_read_b128 v[150:153], v141 offset:3072
	ds_read_b128 v[154:157], v142
	ds_read_b128 v[158:161], v142 offset:1024
	ds_read_b128 v[162:165], v142 offset:2048
	ds_read_b128 v[166:169], v142 offset:3072
	s_mov_b32 m0, s50
	s_add_i32 s79, s76, 0x80000
	ds_read_b128 v[10:13], v140 offset:32768
	ds_read_b128 v[14:17], v140 offset:33792
	ds_read_b128 v[18:21], v140 offset:34816
	ds_read_b128 v[22:25], v140 offset:35840
	ds_read_b128 v[26:29], v140 offset:36864
	ds_read_b128 v[30:33], v140 offset:37888
	ds_read_b128 v[34:37], v140 offset:38912
	ds_read_b128 v[38:41], v140 offset:39936
	buffer_load_dwordx4 v136, s[16:19], s79 offen lds
	s_mov_b32 m0, s51
	s_add_i32 s79, s76, 0xc0000
	buffer_load_dwordx4 v136, s[16:19], s79 offen lds
	s_waitcnt vmcnt(8) lgkmcnt(0)
	s_setprio 1
	s_waitcnt lgkmcnt(6)
	v_mfma_f32_16x16x128_f8f6f4 v[118:121], v[2:9], v[10:17], v[118:121]
	s_barrier
	v_mfma_f32_16x16x128_f8f6f4 v[114:117], v[146:153], v[10:17], v[114:117]
	s_waitcnt lgkmcnt(4)
	v_mfma_f32_16x16x128_f8f6f4 v[110:113], v[2:9], v[18:25], v[110:113]
	v_mfma_f32_16x16x128_f8f6f4 v[102:105], v[146:153], v[18:25], v[102:105]
	s_waitcnt lgkmcnt(2)
	v_mfma_f32_16x16x128_f8f6f4 v[94:97], v[2:9], v[26:33], v[210:213]
	v_mfma_f32_16x16x128_f8f6f4 v[86:89], v[146:153], v[26:33], v[214:217]
	s_waitcnt lgkmcnt(0)
	v_mfma_f32_16x16x128_f8f6f4 v[78:81], v[2:9], v[34:41], v[218:221]
	v_mfma_f32_16x16x128_f8f6f4 v[70:73], v[146:153], v[34:41], v[222:225]
	v_mfma_f32_16x16x128_f8f6f4 v[126:129], v[154:161], v[10:17], v[126:129]
	v_mfma_f32_16x16x128_f8f6f4 v[122:125], v[162:169], v[10:17], v[122:125]
	v_mfma_f32_16x16x128_f8f6f4 v[106:109], v[154:161], v[18:25], v[106:109]
	v_mfma_f32_16x16x128_f8f6f4 v[98:101], v[162:169], v[18:25], v[98:101]
	v_mfma_f32_16x16x128_f8f6f4 v[90:93], v[154:161], v[26:33], v[178:181]
	v_mfma_f32_16x16x128_f8f6f4 v[82:85], v[162:169], v[26:33], v[182:185]
	v_mfma_f32_16x16x128_f8f6f4 v[74:77], v[154:161], v[34:41], v[186:189]
	v_mfma_f32_16x16x128_f8f6f4 v[66:69], v[162:169], v[34:41], v[190:193]
	s_setprio 0
	s_barrier
	s_mov_b32 m0, s54
	s_or_b32 s79, s78, 0x80
	ds_read_b128 v[170:173], v140 offset:49152
	ds_read_b128 v[174:177], v140 offset:50176
	ds_read_b128 v[178:181], v140 offset:51200
	ds_read_b128 v[182:185], v140 offset:52224
	ds_read_b128 v[186:189], v140 offset:53248
	ds_read_b128 v[190:193], v140 offset:54272
	ds_read_b128 v[194:197], v140 offset:55296
	ds_read_b128 v[198:201], v140 offset:56320
	buffer_load_dwordx4 v137, s[12:15], s79 offen lds
	s_add_i32 s79, s78, 0x40080
	s_mov_b32 m0, s55
	s_add_i32 s76, s76, 0x40080
	buffer_load_dwordx4 v137, s[12:15], s79 offen lds
	s_add_i32 s79, s78, 0x80080
	s_mov_b32 m0, s58
	s_add_i32 s78, s78, 0xc0080
	buffer_load_dwordx4 v137, s[12:15], s79 offen lds
	s_mov_b32 m0, s59
	s_nop 0
	buffer_load_dwordx4 v137, s[12:15], s78 offen lds
	s_mov_b32 m0, s56
	s_nop 0
	buffer_load_dwordx4 v136, s[16:19], s77 offen lds
	s_mov_b32 m0, s57
	s_nop 0
	buffer_load_dwordx4 v136, s[16:19], s76 offen lds
	s_waitcnt vmcnt(8) lgkmcnt(0)
	s_setprio 1
	s_waitcnt lgkmcnt(6)
	v_mfma_f32_16x16x128_f8f6f4 v[62:65], v[2:9], v[170:177], v[62:65]
	s_barrier
	v_mfma_f32_16x16x128_f8f6f4 v[54:57], v[146:153], v[170:177], v[54:57]
	s_waitcnt lgkmcnt(4)
	v_mfma_f32_16x16x128_f8f6f4 v[46:49], v[2:9], v[178:185], v[46:49]
	v_mfma_f32_16x16x128_f8f6f4 v[38:41], v[146:153], v[178:185], v[202:205]
	s_waitcnt lgkmcnt(2)
	v_mfma_f32_16x16x128_f8f6f4 v[30:33], v[2:9], v[186:193], v[206:209]
	v_mfma_f32_16x16x128_f8f6f4 v[22:25], v[146:153], v[186:193], v[226:229]
	s_waitcnt lgkmcnt(0)
	v_mfma_f32_16x16x128_f8f6f4 v[14:17], v[2:9], v[194:201], v[230:233]
	v_mfma_f32_16x16x128_f8f6f4 v[6:9], v[146:153], v[194:201], v[234:237]
	v_mfma_f32_16x16x128_f8f6f4 v[58:61], v[154:161], v[170:177], v[58:61]
	v_mfma_f32_16x16x128_f8f6f4 v[50:53], v[162:169], v[170:177], v[50:53]
	v_mfma_f32_16x16x128_f8f6f4 v[42:45], v[154:161], v[178:185], v[42:45]
	v_mfma_f32_16x16x128_f8f6f4 v[34:37], v[162:169], v[178:185], v[238:241]
	v_mfma_f32_16x16x128_f8f6f4 v[26:29], v[154:161], v[186:193], v[242:245]
	v_mfma_f32_16x16x128_f8f6f4 v[18:21], v[162:169], v[186:193], v[246:249]
	v_mfma_f32_16x16x128_f8f6f4 v[10:13], v[154:161], v[194:201], v[250:253]
	v_mfma_f32_16x16x128_f8f6f4 v[2:5], v[162:169], v[194:201], v[130:133]
	s_setprio 0
	s_barrier
	s_add_i32 s75, s75, 2
	s_addk_i32 s73, 0x100
	s_addk_i32 s74, 0x100
	s_cmp_ge_i32 s75, s25
	s_cbranch_scc0 .LBB0_1420
	s_and_b64 vcc, exec, s[44:45]
	s_cbranch_vccz .LBB0_1423

.LBB0_1519:
	ds_read_b128 v[134:137], v208
	ds_read_b128 v[138:141], v208 offset:1024
	ds_read_b128 v[142:145], v208 offset:2048
	ds_read_b128 v[146:149], v208 offset:3072
	ds_read_b128 v[150:153], v209
	ds_read_b128 v[154:157], v209 offset:1024
	ds_read_b128 v[158:161], v209 offset:2048
	ds_read_b128 v[162:165], v209 offset:3072
	s_add_i32 s18, s80, 0xffbf8080
	s_cmp_eq_u32 s65, s82
	s_cselect_b32 s83, s6, s18
	s_cselect_b32 s85, s7, s81
	s_or_b32 s84, s83, 0x80
	s_add_i32 s18, s80, 0xffea8000
	s_mov_b32 m0, s66
	ds_read_b128 v[166:169], v210
	ds_read_b128 v[170:173], v210 offset:1024
	ds_read_b128 v[174:177], v210 offset:2048
	ds_read_b128 v[178:181], v210 offset:3072
	ds_read_b128 v[182:185], v210 offset:4096
	ds_read_b128 v[186:189], v210 offset:5120
	ds_read_b128 v[190:193], v210 offset:6144
	ds_read_b128 v[194:197], v210 offset:7168
	buffer_load_dwordx4 v206, s[12:15], s18 offen lds
	s_mov_b32 m0, s69
	s_nop 0
	buffer_load_dwordx4 v206, s[12:15], s80 offen lds
	s_waitcnt vmcnt(8) lgkmcnt(0)
	s_setprio 1
	v_mfma_f32_16x16x32_bf16 v[126:129], v[134:137], v[166:169], v[126:129]
	s_barrier
	v_mfma_f32_16x16x32_bf16 v[126:129], v[138:141], v[170:173], v[126:129]
	v_mfma_f32_16x16x32_bf16 v[122:125], v[142:145], v[166:169], v[122:125]
	v_mfma_f32_16x16x32_bf16 v[122:125], v[146:149], v[170:173], v[122:125]
	v_mfma_f32_16x16x32_bf16 v[110:113], v[150:153], v[166:169], v[110:113]
	v_mfma_f32_16x16x32_bf16 v[110:113], v[154:157], v[170:173], v[110:113]
	v_mfma_f32_16x16x32_bf16 v[102:105], v[158:161], v[166:169], v[102:105]
	v_mfma_f32_16x16x32_bf16 v[102:105], v[162:165], v[170:173], v[102:105]
	v_mfma_f32_16x16x32_bf16 v[86:89], v[158:161], v[174:177], v[86:89]
	v_mfma_f32_16x16x32_bf16 v[86:89], v[162:165], v[178:181], v[86:89]
	v_mfma_f32_16x16x32_bf16 v[94:97], v[150:153], v[174:177], v[94:97]
	v_mfma_f32_16x16x32_bf16 v[94:97], v[154:157], v[178:181], v[94:97]
	v_mfma_f32_16x16x32_bf16 v[114:117], v[142:145], v[174:177], v[114:117]
	v_mfma_f32_16x16x32_bf16 v[114:117], v[146:149], v[178:181], v[114:117]
	v_mfma_f32_16x16x32_bf16 v[118:121], v[134:137], v[174:177], v[118:121]
	v_mfma_f32_16x16x32_bf16 v[118:121], v[138:141], v[178:181], v[118:121]
	v_mfma_f32_16x16x32_bf16 v[106:109], v[134:137], v[182:185], v[106:109]
	v_mfma_f32_16x16x32_bf16 v[106:109], v[138:141], v[186:189], v[106:109]
	v_mfma_f32_16x16x32_bf16 v[98:101], v[142:145], v[182:185], v[98:101]
	v_mfma_f32_16x16x32_bf16 v[98:101], v[146:149], v[186:189], v[98:101]
	v_mfma_f32_16x16x32_bf16 v[78:81], v[150:153], v[182:185], v[78:81]
	v_mfma_f32_16x16x32_bf16 v[78:81], v[154:157], v[186:189], v[78:81]
	v_mfma_f32_16x16x32_bf16 v[74:77], v[158:161], v[182:185], v[74:77]
	v_mfma_f32_16x16x32_bf16 v[74:77], v[162:165], v[186:189], v[74:77]
	v_mfma_f32_16x16x32_bf16 v[66:69], v[158:161], v[190:193], v[66:69]
	v_mfma_f32_16x16x32_bf16 v[66:69], v[162:165], v[194:197], v[66:69]
	v_mfma_f32_16x16x32_bf16 v[70:73], v[150:153], v[190:193], v[70:73]
	v_mfma_f32_16x16x32_bf16 v[70:73], v[154:157], v[194:197], v[70:73]
	v_mfma_f32_16x16x32_bf16 v[82:85], v[142:145], v[190:193], v[82:85]
	v_mfma_f32_16x16x32_bf16 v[82:85], v[146:149], v[194:197], v[82:85]
	v_mfma_f32_16x16x32_bf16 v[90:93], v[134:137], v[190:193], v[90:93]
	v_mfma_f32_16x16x32_bf16 v[90:93], v[138:141], v[194:197], v[90:93]
	s_setprio 0
	s_barrier
	s_mov_b32 m0, s27
	s_mov_b32 s18, s14
	s_mov_b32 s19, s15
	ds_read_b128 v[166:169], v210 offset:16384
	ds_read_b128 v[170:173], v210 offset:17408
	ds_read_b128 v[174:177], v210 offset:18432
	ds_read_b128 v[178:181], v210 offset:19456
	ds_read_b128 v[182:185], v210 offset:20480
	ds_read_b128 v[186:189], v210 offset:21504
	ds_read_b128 v[190:193], v210 offset:22528
	ds_read_b128 v[194:197], v210 offset:23552
	buffer_load_dwordx4 v207, s[16:19], s85 offen lds
	s_mov_b32 m0, s30
	s_add_i32 s86, s85, 0x158000
	buffer_load_dwordx4 v207, s[16:19], s86 offen lds
	s_mov_b32 m0, s31
	s_add_i32 s86, s85, 0x2b0000
	buffer_load_dwordx4 v207, s[16:19], s86 offen lds
	s_mov_b32 m0, s50
	s_add_i32 s86, s85, 0x408000
	buffer_load_dwordx4 v207, s[16:19], s86 offen lds
	s_mov_b32 m0, s25
	s_add_i32 s86, s83, 0x158000
	buffer_load_dwordx4 v206, s[12:15], s83 offen lds
	s_mov_b32 m0, s51
	s_nop 0
	buffer_load_dwordx4 v206, s[12:15], s86 offen lds
	s_waitcnt vmcnt(8) lgkmcnt(0)
	s_setprio 1
	v_mfma_f32_16x16x32_bf16 v[62:65], v[134:137], v[166:169], v[62:65]
	s_barrier
	v_mfma_f32_16x16x32_bf16 v[62:65], v[138:141], v[170:173], v[62:65]
	v_mfma_f32_16x16x32_bf16 v[58:61], v[142:145], v[166:169], v[58:61]
	v_mfma_f32_16x16x32_bf16 v[58:61], v[146:149], v[170:173], v[58:61]
	v_mfma_f32_16x16x32_bf16 v[46:49], v[150:153], v[166:169], v[46:49]
	v_mfma_f32_16x16x32_bf16 v[46:49], v[154:157], v[170:173], v[46:49]
	v_mfma_f32_16x16x32_bf16 v[38:41], v[158:161], v[166:169], v[38:41]
	v_mfma_f32_16x16x32_bf16 v[38:41], v[162:165], v[170:173], v[38:41]
	v_mfma_f32_16x16x32_bf16 v[22:25], v[158:161], v[174:177], v[22:25]
	v_mfma_f32_16x16x32_bf16 v[22:25], v[162:165], v[178:181], v[22:25]
	v_mfma_f32_16x16x32_bf16 v[30:33], v[150:153], v[174:177], v[30:33]
	v_mfma_f32_16x16x32_bf16 v[30:33], v[154:157], v[178:181], v[30:33]
	v_mfma_f32_16x16x32_bf16 v[50:53], v[142:145], v[174:177], v[50:53]
	v_mfma_f32_16x16x32_bf16 v[50:53], v[146:149], v[178:181], v[50:53]
	v_mfma_f32_16x16x32_bf16 v[54:57], v[134:137], v[174:177], v[54:57]
	v_mfma_f32_16x16x32_bf16 v[54:57], v[138:141], v[178:181], v[54:57]
	v_mfma_f32_16x16x32_bf16 v[42:45], v[134:137], v[182:185], v[42:45]
	v_mfma_f32_16x16x32_bf16 v[42:45], v[138:141], v[186:189], v[42:45]
	v_mfma_f32_16x16x32_bf16 v[34:37], v[142:145], v[182:185], v[34:37]
	v_mfma_f32_16x16x32_bf16 v[34:37], v[146:149], v[186:189], v[34:37]
	v_mfma_f32_16x16x32_bf16 v[14:17], v[150:153], v[182:185], v[14:17]
	v_mfma_f32_16x16x32_bf16 v[14:17], v[154:157], v[186:189], v[14:17]
	v_mfma_f32_16x16x32_bf16 v[10:13], v[158:161], v[182:185], v[10:13]
	v_mfma_f32_16x16x32_bf16 v[10:13], v[162:165], v[186:189], v[10:13]
	v_mfma_f32_16x16x32_bf16 v[2:5], v[158:161], v[190:193], v[2:5]
	v_mfma_f32_16x16x32_bf16 v[2:5], v[162:165], v[194:197], v[2:5]
	v_mfma_f32_16x16x32_bf16 v[6:9], v[150:153], v[190:193], v[6:9]
	v_mfma_f32_16x16x32_bf16 v[6:9], v[154:157], v[194:197], v[6:9]
	v_mfma_f32_16x16x32_bf16 v[18:21], v[142:145], v[190:193], v[18:21]
	v_mfma_f32_16x16x32_bf16 v[18:21], v[146:149], v[194:197], v[18:21]
	v_mfma_f32_16x16x32_bf16 v[26:29], v[134:137], v[190:193], v[26:29]
	v_mfma_f32_16x16x32_bf16 v[26:29], v[138:141], v[194:197], v[26:29]
	s_setprio 0
	s_barrier
	ds_read_b128 v[134:137], v211
	ds_read_b128 v[138:141], v211 offset:1024
	ds_read_b128 v[142:145], v211 offset:2048
	ds_read_b128 v[146:149], v211 offset:3072
	ds_read_b128 v[150:153], v212
	ds_read_b128 v[154:157], v212 offset:1024
	ds_read_b128 v[158:161], v212 offset:2048
	ds_read_b128 v[162:165], v212 offset:3072
	s_mov_b32 m0, s52
	s_add_i32 s86, s83, 0x2b0000
	ds_read_b128 v[166:169], v210 offset:32768
	ds_read_b128 v[170:173], v210 offset:33792
	ds_read_b128 v[174:177], v210 offset:34816
	ds_read_b128 v[178:181], v210 offset:35840
	ds_read_b128 v[182:185], v210 offset:36864
	ds_read_b128 v[186:189], v210 offset:37888
	ds_read_b128 v[190:193], v210 offset:38912
	ds_read_b128 v[194:197], v210 offset:39936
	buffer_load_dwordx4 v206, s[12:15], s86 offen lds
	s_mov_b32 m0, s53
	s_add_i32 s86, s83, 0x408000
	buffer_load_dwordx4 v206, s[12:15], s86 offen lds
	s_waitcnt vmcnt(8) lgkmcnt(0)
	s_setprio 1
	v_mfma_f32_16x16x32_bf16 v[126:129], v[134:137], v[166:169], v[126:129]
	s_barrier
	v_mfma_f32_16x16x32_bf16 v[126:129], v[138:141], v[170:173], v[126:129]
	v_mfma_f32_16x16x32_bf16 v[122:125], v[142:145], v[166:169], v[122:125]
	v_mfma_f32_16x16x32_bf16 v[122:125], v[146:149], v[170:173], v[122:125]
	v_mfma_f32_16x16x32_bf16 v[110:113], v[150:153], v[166:169], v[110:113]
	v_mfma_f32_16x16x32_bf16 v[110:113], v[154:157], v[170:173], v[110:113]
	v_mfma_f32_16x16x32_bf16 v[102:105], v[158:161], v[166:169], v[102:105]
	v_mfma_f32_16x16x32_bf16 v[102:105], v[162:165], v[170:173], v[102:105]
	v_mfma_f32_16x16x32_bf16 v[86:89], v[158:161], v[174:177], v[86:89]
	v_mfma_f32_16x16x32_bf16 v[86:89], v[162:165], v[178:181], v[86:89]
	v_mfma_f32_16x16x32_bf16 v[94:97], v[150:153], v[174:177], v[94:97]
	v_mfma_f32_16x16x32_bf16 v[94:97], v[154:157], v[178:181], v[94:97]
	v_mfma_f32_16x16x32_bf16 v[114:117], v[142:145], v[174:177], v[114:117]
	v_mfma_f32_16x16x32_bf16 v[114:117], v[146:149], v[178:181], v[114:117]
	v_mfma_f32_16x16x32_bf16 v[118:121], v[134:137], v[174:177], v[118:121]
	v_mfma_f32_16x16x32_bf16 v[118:121], v[138:141], v[178:181], v[118:121]
	v_mfma_f32_16x16x32_bf16 v[106:109], v[134:137], v[182:185], v[106:109]
	v_mfma_f32_16x16x32_bf16 v[106:109], v[138:141], v[186:189], v[106:109]
	v_mfma_f32_16x16x32_bf16 v[98:101], v[142:145], v[182:185], v[98:101]
	v_mfma_f32_16x16x32_bf16 v[98:101], v[146:149], v[186:189], v[98:101]
	v_mfma_f32_16x16x32_bf16 v[78:81], v[150:153], v[182:185], v[78:81]
	v_mfma_f32_16x16x32_bf16 v[78:81], v[154:157], v[186:189], v[78:81]
	v_mfma_f32_16x16x32_bf16 v[74:77], v[158:161], v[182:185], v[74:77]
	v_mfma_f32_16x16x32_bf16 v[74:77], v[162:165], v[186:189], v[74:77]
	v_mfma_f32_16x16x32_bf16 v[66:69], v[158:161], v[190:193], v[66:69]
	v_mfma_f32_16x16x32_bf16 v[66:69], v[162:165], v[194:197], v[66:69]
	v_mfma_f32_16x16x32_bf16 v[70:73], v[150:153], v[190:193], v[70:73]
	v_mfma_f32_16x16x32_bf16 v[70:73], v[154:157], v[194:197], v[70:73]
	v_mfma_f32_16x16x32_bf16 v[82:85], v[142:145], v[190:193], v[82:85]
	v_mfma_f32_16x16x32_bf16 v[82:85], v[146:149], v[194:197], v[82:85]
	v_mfma_f32_16x16x32_bf16 v[90:93], v[134:137], v[190:193], v[90:93]
	v_mfma_f32_16x16x32_bf16 v[90:93], v[138:141], v[194:197], v[90:93]
	s_setprio 0
	s_barrier
	s_mov_b32 m0, s57
	s_or_b32 s86, s85, 0x80
	ds_read_b128 v[166:169], v210 offset:49152
	ds_read_b128 v[170:173], v210 offset:50176
	ds_read_b128 v[174:177], v210 offset:51200
	ds_read_b128 v[178:181], v210 offset:52224
	ds_read_b128 v[182:185], v210 offset:53248
	ds_read_b128 v[186:189], v210 offset:54272
	ds_read_b128 v[190:193], v210 offset:55296
	ds_read_b128 v[194:197], v210 offset:56320
	buffer_load_dwordx4 v207, s[16:19], s86 offen lds
	s_add_i32 s86, s85, 0x158080
	s_mov_b32 m0, s58
	s_add_i32 s83, s83, 0x158080
	buffer_load_dwordx4 v207, s[16:19], s86 offen lds
	s_add_i32 s86, s85, 0x2b0080
	s_mov_b32 m0, s61
	s_add_i32 s85, s85, 0x408080
	buffer_load_dwordx4 v207, s[16:19], s86 offen lds
	s_mov_b32 m0, s62
	s_nop 0
	buffer_load_dwordx4 v207, s[16:19], s85 offen lds
	s_mov_b32 m0, s59
	s_nop 0
	buffer_load_dwordx4 v206, s[12:15], s84 offen lds
	s_mov_b32 m0, s60
	s_nop 0
	buffer_load_dwordx4 v206, s[12:15], s83 offen lds
	s_waitcnt vmcnt(8) lgkmcnt(0)
	s_setprio 1
	v_mfma_f32_16x16x32_bf16 v[62:65], v[134:137], v[166:169], v[62:65]
	s_barrier
	v_mfma_f32_16x16x32_bf16 v[62:65], v[138:141], v[170:173], v[62:65]
	v_mfma_f32_16x16x32_bf16 v[58:61], v[142:145], v[166:169], v[58:61]
	v_mfma_f32_16x16x32_bf16 v[58:61], v[146:149], v[170:173], v[58:61]
	v_mfma_f32_16x16x32_bf16 v[46:49], v[150:153], v[166:169], v[46:49]
	v_mfma_f32_16x16x32_bf16 v[46:49], v[154:157], v[170:173], v[46:49]
	v_mfma_f32_16x16x32_bf16 v[38:41], v[158:161], v[166:169], v[38:41]
	v_mfma_f32_16x16x32_bf16 v[38:41], v[162:165], v[170:173], v[38:41]
	v_mfma_f32_16x16x32_bf16 v[22:25], v[158:161], v[174:177], v[22:25]
	v_mfma_f32_16x16x32_bf16 v[22:25], v[162:165], v[178:181], v[22:25]
	v_mfma_f32_16x16x32_bf16 v[30:33], v[150:153], v[174:177], v[30:33]
	v_mfma_f32_16x16x32_bf16 v[30:33], v[154:157], v[178:181], v[30:33]
	v_mfma_f32_16x16x32_bf16 v[50:53], v[142:145], v[174:177], v[50:53]
	v_mfma_f32_16x16x32_bf16 v[50:53], v[146:149], v[178:181], v[50:53]
	v_mfma_f32_16x16x32_bf16 v[54:57], v[134:137], v[174:177], v[54:57]
	v_mfma_f32_16x16x32_bf16 v[54:57], v[138:141], v[178:181], v[54:57]
	v_mfma_f32_16x16x32_bf16 v[42:45], v[134:137], v[182:185], v[42:45]
	v_mfma_f32_16x16x32_bf16 v[42:45], v[138:141], v[186:189], v[42:45]
	v_mfma_f32_16x16x32_bf16 v[34:37], v[142:145], v[182:185], v[34:37]
	v_mfma_f32_16x16x32_bf16 v[34:37], v[146:149], v[186:189], v[34:37]
	v_mfma_f32_16x16x32_bf16 v[14:17], v[150:153], v[182:185], v[14:17]
	v_mfma_f32_16x16x32_bf16 v[14:17], v[154:157], v[186:189], v[14:17]
	v_mfma_f32_16x16x32_bf16 v[10:13], v[158:161], v[182:185], v[10:13]
	v_mfma_f32_16x16x32_bf16 v[10:13], v[162:165], v[186:189], v[10:13]
	v_mfma_f32_16x16x32_bf16 v[2:5], v[158:161], v[190:193], v[2:5]
	v_mfma_f32_16x16x32_bf16 v[2:5], v[162:165], v[194:197], v[2:5]
	v_mfma_f32_16x16x32_bf16 v[6:9], v[150:153], v[190:193], v[6:9]
	v_mfma_f32_16x16x32_bf16 v[6:9], v[154:157], v[194:197], v[6:9]
	v_mfma_f32_16x16x32_bf16 v[18:21], v[142:145], v[190:193], v[18:21]
	v_mfma_f32_16x16x32_bf16 v[18:21], v[146:149], v[194:197], v[18:21]
	v_mfma_f32_16x16x32_bf16 v[26:29], v[134:137], v[190:193], v[26:29]
	v_mfma_f32_16x16x32_bf16 v[26:29], v[138:141], v[194:197], v[26:29]
	s_setprio 0
	s_barrier
	s_add_i32 s82, s82, 2
	s_addk_i32 s80, 0x100
	s_addk_i32 s81, 0x100
	s_cmp_ge_i32 s82, s3
	s_cbranch_scc0 .LBB0_1519
	v_pk_mul_f32 v[182:183], v[128:129], 0.5 op_sel_hi:[1,0]
	v_pk_mul_f32 v[184:185], v[126:127], 0.5 op_sel_hi:[1,0]
	v_pk_mul_f32 v[186:187], v[124:125], 0.5 op_sel_hi:[1,0]
	v_pk_mul_f32 v[188:189], v[122:123], 0.5 op_sel_hi:[1,0]
	v_pk_mul_f32 v[196:197], v[112:113], 0.5 op_sel_hi:[1,0]
	v_pk_mul_f32 v[194:195], v[110:111], 0.5 op_sel_hi:[1,0]
	v_pk_mul_f32 v[192:193], v[104:105], 0.5 op_sel_hi:[1,0]
	v_pk_mul_f32 v[190:191], v[102:103], 0.5 op_sel_hi:[1,0]
	v_pk_mul_f32 v[180:181], v[120:121], 0.5 op_sel_hi:[1,0]
	v_pk_mul_f32 v[178:179], v[118:119], 0.5 op_sel_hi:[1,0]
	v_pk_mul_f32 v[176:177], v[116:117], 0.5 op_sel_hi:[1,0]
	v_pk_mul_f32 v[174:175], v[114:115], 0.5 op_sel_hi:[1,0]
	v_pk_mul_f32 v[170:171], v[96:97], 0.5 op_sel_hi:[1,0]
	v_pk_mul_f32 v[168:169], v[94:95], 0.5 op_sel_hi:[1,0]
	v_pk_mul_f32 v[166:167], v[88:89], 0.5 op_sel_hi:[1,0]
	v_pk_mul_f32 v[164:165], v[86:87], 0.5 op_sel_hi:[1,0]
	v_pk_mul_f32 v[162:163], v[108:109], 0.5 op_sel_hi:[1,0]
	v_pk_mul_f32 v[160:161], v[106:107], 0.5 op_sel_hi:[1,0]
	v_pk_mul_f32 v[158:159], v[100:101], 0.5 op_sel_hi:[1,0]
	v_pk_mul_f32 v[156:157], v[98:99], 0.5 op_sel_hi:[1,0]
	v_pk_mul_f32 v[154:155], v[80:81], 0.5 op_sel_hi:[1,0]
	v_pk_mul_f32 v[152:153], v[78:79], 0.5 op_sel_hi:[1,0]
	v_pk_mul_f32 v[150:151], v[76:77], 0.5 op_sel_hi:[1,0]
	v_pk_mul_f32 v[148:149], v[74:75], 0.5 op_sel_hi:[1,0]
	v_pk_mul_f32 v[144:145], v[92:93], 0.5 op_sel_hi:[1,0]
	v_pk_mul_f32 v[142:143], v[90:91], 0.5 op_sel_hi:[1,0]
	v_pk_mul_f32 v[140:141], v[84:85], 0.5 op_sel_hi:[1,0]
	v_pk_mul_f32 v[138:139], v[82:83], 0.5 op_sel_hi:[1,0]
	v_pk_mul_f32 v[136:137], v[72:73], 0.5 op_sel_hi:[1,0]
	v_pk_mul_f32 v[134:135], v[70:71], 0.5 op_sel_hi:[1,0]
	v_pk_mul_f32 v[128:129], v[68:69], 0.5 op_sel_hi:[1,0]
	v_pk_mul_f32 v[126:127], v[66:67], 0.5 op_sel_hi:[1,0]
	v_pk_mul_f32 v[122:123], v[64:65], 0.5 op_sel_hi:[1,0]
	v_pk_mul_f32 v[120:121], v[62:63], 0.5 op_sel_hi:[1,0]
	v_pk_mul_f32 v[118:119], v[60:61], 0.5 op_sel_hi:[1,0]
	v_pk_mul_f32 v[116:117], v[58:59], 0.5 op_sel_hi:[1,0]
	v_pk_mul_f32 v[112:113], v[48:49], 0.5 op_sel_hi:[1,0]
	v_pk_mul_f32 v[110:111], v[46:47], 0.5 op_sel_hi:[1,0]
	v_pk_mul_f32 v[108:109], v[40:41], 0.5 op_sel_hi:[1,0]
	v_pk_mul_f32 v[106:107], v[38:39], 0.5 op_sel_hi:[1,0]
	v_pk_mul_f32 v[104:105], v[56:57], 0.5 op_sel_hi:[1,0]
	v_pk_mul_f32 v[102:103], v[54:55], 0.5 op_sel_hi:[1,0]
	v_pk_mul_f32 v[100:101], v[52:53], 0.5 op_sel_hi:[1,0]
	v_pk_mul_f32 v[98:99], v[50:51], 0.5 op_sel_hi:[1,0]
	v_pk_mul_f32 v[96:97], v[32:33], 0.5 op_sel_hi:[1,0]
	v_pk_mul_f32 v[94:95], v[30:31], 0.5 op_sel_hi:[1,0]
	v_pk_mul_f32 v[92:93], v[24:25], 0.5 op_sel_hi:[1,0]
	v_pk_mul_f32 v[90:91], v[22:23], 0.5 op_sel_hi:[1,0]
	v_pk_mul_f32 v[88:89], v[44:45], 0.5 op_sel_hi:[1,0]
	v_pk_mul_f32 v[86:87], v[42:43], 0.5 op_sel_hi:[1,0]
	v_pk_mul_f32 v[84:85], v[36:37], 0.5 op_sel_hi:[1,0]
	v_pk_mul_f32 v[82:83], v[34:35], 0.5 op_sel_hi:[1,0]
	v_pk_mul_f32 v[80:81], v[16:17], 0.5 op_sel_hi:[1,0]
	v_pk_mul_f32 v[78:79], v[14:15], 0.5 op_sel_hi:[1,0]
	v_pk_mul_f32 v[76:77], v[12:13], 0.5 op_sel_hi:[1,0]
	v_pk_mul_f32 v[74:75], v[10:11], 0.5 op_sel_hi:[1,0]
	v_pk_mul_f32 v[72:73], v[28:29], 0.5 op_sel_hi:[1,0]
	v_pk_mul_f32 v[70:71], v[26:27], 0.5 op_sel_hi:[1,0]
	v_pk_mul_f32 v[68:69], v[20:21], 0.5 op_sel_hi:[1,0]
	v_pk_mul_f32 v[66:67], v[18:19], 0.5 op_sel_hi:[1,0]
	v_pk_mul_f32 v[64:65], v[8:9], 0.5 op_sel_hi:[1,0]
	v_pk_mul_f32 v[62:63], v[6:7], 0.5 op_sel_hi:[1,0]
	v_pk_mul_f32 v[60:61], v[4:5], 0.5 op_sel_hi:[1,0]
	v_pk_mul_f32 v[58:59], v[2:3], 0.5 op_sel_hi:[1,0]
	s_and_b64 vcc, exec, s[40:41]
	s_cbranch_vccz .LBB0_1522

.LBB0_1567:
	ds_read_b128 v[134:137], v225
	ds_read_b128 v[138:141], v225 offset:1024
	ds_read_b128 v[142:145], v225 offset:2048
	ds_read_b128 v[146:149], v225 offset:3072
	ds_read_b128 v[150:153], v226
	ds_read_b128 v[154:157], v226 offset:1024
	ds_read_b128 v[158:161], v226 offset:2048
	ds_read_b128 v[162:165], v226 offset:3072
	s_add_i32 s18, s8, 0xffdfc080
	s_cmp_eq_u32 s71, s55
	s_cselect_b32 s56, s6, s18
	s_cselect_b32 s91, s7, s9
	s_or_b32 s57, s56, 0x80
	s_add_i32 s18, s8, 0xfff54000
	s_mov_b32 m0, s72
	ds_read_b128 v[166:169], v227
	ds_read_b128 v[170:173], v227 offset:1024
	ds_read_b128 v[174:177], v227 offset:2048
	ds_read_b128 v[178:181], v227 offset:3072
	ds_read_b128 v[182:185], v227 offset:4096
	ds_read_b128 v[186:189], v227 offset:5120
	ds_read_b128 v[190:193], v227 offset:6144
	ds_read_b128 v[194:197], v227 offset:7168
	buffer_load_dwordx4 v223, s[12:15], s18 offen lds
	s_mov_b32 m0, s75
	s_nop 0
	buffer_load_dwordx4 v223, s[12:15], s8 offen lds
	s_waitcnt vmcnt(8) lgkmcnt(0)
	s_setprio 1
	s_waitcnt lgkmcnt(6)
	v_mfma_f32_16x16x128_f8f6f4 v[126:129], v[134:141], v[166:173], v[126:129]
	s_barrier
	v_mfma_f32_16x16x128_f8f6f4 v[122:125], v[142:149], v[166:173], v[122:125]
	s_waitcnt lgkmcnt(4)
	v_mfma_f32_16x16x128_f8f6f4 v[118:121], v[134:141], v[174:181], v[118:121]
	v_mfma_f32_16x16x128_f8f6f4 v[114:117], v[142:149], v[174:181], v[114:117]
	s_waitcnt lgkmcnt(2)
	v_mfma_f32_16x16x128_f8f6f4 v[106:109], v[134:141], v[182:189], v[106:109]
	v_mfma_f32_16x16x128_f8f6f4 v[98:101], v[142:149], v[182:189], v[98:101]
	v_mfma_f32_16x16x128_f8f6f4 v[110:113], v[150:157], v[166:173], v[110:113]
	v_mfma_f32_16x16x128_f8f6f4 v[102:105], v[158:165], v[166:173], v[102:105]
	s_waitcnt lgkmcnt(0)
	v_mfma_f32_16x16x128_f8f6f4 v[198:201], v[134:141], v[190:197], v[90:93]
	v_mfma_f32_16x16x128_f8f6f4 v[202:205], v[142:149], v[190:197], v[82:85]
	v_mfma_f32_16x16x128_f8f6f4 v[166:169], v[150:157], v[174:181], v[94:97]
	v_mfma_f32_16x16x128_f8f6f4 v[170:173], v[158:165], v[174:181], v[86:89]
	v_mfma_f32_16x16x128_f8f6f4 v[174:177], v[150:157], v[182:189], v[78:81]
	v_mfma_f32_16x16x128_f8f6f4 v[178:181], v[158:165], v[182:189], v[74:77]
	v_mfma_f32_16x16x128_f8f6f4 v[182:185], v[150:157], v[190:197], v[70:73]
	v_mfma_f32_16x16x128_f8f6f4 v[186:189], v[158:165], v[190:197], v[66:69]
	s_setprio 0
	s_barrier
	s_mov_b32 m0, s27
	s_mov_b32 s18, s14
	s_mov_b32 s19, s15
	s_nop 1
	ds_read_b128 v[66:69], v227 offset:16384
	ds_read_b128 v[70:73], v227 offset:17408
	ds_read_b128 v[74:77], v227 offset:18432
	ds_read_b128 v[78:81], v227 offset:19456
	ds_read_b128 v[82:85], v227 offset:20480
	ds_read_b128 v[86:89], v227 offset:21504
	ds_read_b128 v[90:93], v227 offset:22528
	ds_read_b128 v[94:97], v227 offset:23552
	buffer_load_dwordx4 v224, s[16:19], s91 offen lds
	s_mov_b32 m0, s30
	s_add_i32 s92, s91, 0xac000
	buffer_load_dwordx4 v224, s[16:19], s92 offen lds
	s_mov_b32 m0, s31
	s_add_i32 s92, s91, 0x158000
	buffer_load_dwordx4 v224, s[16:19], s92 offen lds
	s_mov_b32 m0, s51
	s_add_i32 s92, s91, 0x204000
	buffer_load_dwordx4 v224, s[16:19], s92 offen lds
	s_mov_b32 m0, s25
	s_add_i32 s92, s56, 0xac000
	buffer_load_dwordx4 v223, s[12:15], s56 offen lds
	s_mov_b32 m0, s58
	s_nop 0
	buffer_load_dwordx4 v223, s[12:15], s92 offen lds
	s_waitcnt vmcnt(8) lgkmcnt(0)
	s_setprio 1
	s_waitcnt lgkmcnt(6)
	v_mfma_f32_16x16x128_f8f6f4 v[62:65], v[134:141], v[66:73], v[62:65]
	s_barrier
	v_mfma_f32_16x16x128_f8f6f4 v[58:61], v[142:149], v[66:73], v[58:61]
	s_waitcnt lgkmcnt(4)
	v_mfma_f32_16x16x128_f8f6f4 v[54:57], v[134:141], v[74:81], v[54:57]
	v_mfma_f32_16x16x128_f8f6f4 v[50:53], v[142:149], v[74:81], v[50:53]
	s_waitcnt lgkmcnt(2)
	v_mfma_f32_16x16x128_f8f6f4 v[190:193], v[134:141], v[82:89], v[42:45]
	v_mfma_f32_16x16x128_f8f6f4 v[194:197], v[142:149], v[82:89], v[34:37]
	s_waitcnt lgkmcnt(0)
	v_mfma_f32_16x16x128_f8f6f4 v[206:209], v[134:141], v[90:97], v[26:29]
	v_mfma_f32_16x16x128_f8f6f4 v[210:213], v[142:149], v[90:97], v[18:21]
	v_mfma_f32_16x16x128_f8f6f4 v[214:217], v[150:157], v[66:73], v[46:49]
	v_mfma_f32_16x16x128_f8f6f4 v[218:221], v[158:165], v[66:73], v[38:41]
	v_mfma_f32_16x16x128_f8f6f4 v[234:237], v[150:157], v[74:81], v[30:33]
	v_mfma_f32_16x16x128_f8f6f4 v[238:241], v[158:165], v[74:81], v[22:25]
	v_mfma_f32_16x16x128_f8f6f4 v[242:245], v[150:157], v[82:89], v[14:17]
	v_mfma_f32_16x16x128_f8f6f4 v[246:249], v[158:165], v[82:89], v[10:13]
	v_mfma_f32_16x16x128_f8f6f4 v[250:253], v[150:157], v[90:97], v[6:9]
	v_mfma_f32_16x16x128_f8f6f4 v[130:133], v[158:165], v[90:97], v[2:5]
	s_setprio 0
	s_barrier
	s_nop 4
	ds_read_b128 v[2:5], v228
	ds_read_b128 v[6:9], v228 offset:1024
	ds_read_b128 v[10:13], v228 offset:2048
	ds_read_b128 v[14:17], v228 offset:3072
	ds_read_b128 v[134:137], v229
	ds_read_b128 v[138:141], v229 offset:1024
	ds_read_b128 v[142:145], v229 offset:2048
	ds_read_b128 v[146:149], v229 offset:3072
	s_mov_b32 m0, s59
	s_add_i32 s92, s56, 0x158000
	ds_read_b128 v[18:21], v227 offset:32768
	ds_read_b128 v[22:25], v227 offset:33792
	ds_read_b128 v[26:29], v227 offset:34816
	ds_read_b128 v[30:33], v227 offset:35840
	ds_read_b128 v[34:37], v227 offset:36864
	ds_read_b128 v[38:41], v227 offset:37888
	ds_read_b128 v[42:45], v227 offset:38912
	ds_read_b128 v[46:49], v227 offset:39936
	buffer_load_dwordx4 v223, s[12:15], s92 offen lds
	s_mov_b32 m0, s60
	s_add_i32 s92, s56, 0x204000
	buffer_load_dwordx4 v223, s[12:15], s92 offen lds
	s_waitcnt vmcnt(8) lgkmcnt(0)
	s_setprio 1
	s_waitcnt lgkmcnt(6)
	v_mfma_f32_16x16x128_f8f6f4 v[126:129], v[2:9], v[18:25], v[126:129]
	s_barrier
	v_mfma_f32_16x16x128_f8f6f4 v[122:125], v[10:17], v[18:25], v[122:125]
	s_waitcnt lgkmcnt(4)
	v_mfma_f32_16x16x128_f8f6f4 v[118:121], v[2:9], v[26:33], v[118:121]
	v_mfma_f32_16x16x128_f8f6f4 v[114:117], v[10:17], v[26:33], v[114:117]
	s_waitcnt lgkmcnt(2)
	v_mfma_f32_16x16x128_f8f6f4 v[106:109], v[2:9], v[34:41], v[106:109]
	v_mfma_f32_16x16x128_f8f6f4 v[98:101], v[10:17], v[34:41], v[98:101]
	s_waitcnt lgkmcnt(0)
	v_mfma_f32_16x16x128_f8f6f4 v[90:93], v[2:9], v[42:49], v[198:201]
	v_mfma_f32_16x16x128_f8f6f4 v[82:85], v[10:17], v[42:49], v[202:205]
	v_mfma_f32_16x16x128_f8f6f4 v[110:113], v[134:141], v[18:25], v[110:113]
	v_mfma_f32_16x16x128_f8f6f4 v[102:105], v[142:149], v[18:25], v[102:105]
	v_mfma_f32_16x16x128_f8f6f4 v[94:97], v[134:141], v[26:33], v[166:169]
	v_mfma_f32_16x16x128_f8f6f4 v[86:89], v[142:149], v[26:33], v[170:173]
	v_mfma_f32_16x16x128_f8f6f4 v[78:81], v[134:141], v[34:41], v[174:177]
	v_mfma_f32_16x16x128_f8f6f4 v[74:77], v[142:149], v[34:41], v[178:181]
	v_mfma_f32_16x16x128_f8f6f4 v[70:73], v[134:141], v[42:49], v[182:185]
	v_mfma_f32_16x16x128_f8f6f4 v[66:69], v[142:149], v[42:49], v[186:189]
	s_setprio 0
	s_barrier
	s_mov_b32 m0, s63
	s_or_b32 s92, s91, 0x80
	ds_read_b128 v[150:153], v227 offset:49152
	ds_read_b128 v[154:157], v227 offset:50176
	ds_read_b128 v[158:161], v227 offset:51200
	ds_read_b128 v[162:165], v227 offset:52224
	ds_read_b128 v[166:169], v227 offset:53248
	ds_read_b128 v[170:173], v227 offset:54272
	ds_read_b128 v[174:177], v227 offset:55296
	ds_read_b128 v[178:181], v227 offset:56320
	buffer_load_dwordx4 v224, s[16:19], s92 offen lds
	s_add_i32 s92, s91, 0xac080
	s_mov_b32 m0, s64
	s_add_i32 s56, s56, 0xac080
	buffer_load_dwordx4 v224, s[16:19], s92 offen lds
	s_add_i32 s92, s91, 0x158080
	s_mov_b32 m0, s67
	s_add_i32 s91, s91, 0x204080
	buffer_load_dwordx4 v224, s[16:19], s92 offen lds
	s_mov_b32 m0, s68
	s_nop 0
	buffer_load_dwordx4 v224, s[16:19], s91 offen lds
	s_mov_b32 m0, s65
	s_nop 0
	buffer_load_dwordx4 v223, s[12:15], s57 offen lds
	s_mov_b32 m0, s66
	s_nop 0
	buffer_load_dwordx4 v223, s[12:15], s56 offen lds
	s_waitcnt vmcnt(8) lgkmcnt(0)
	s_setprio 1
	s_waitcnt lgkmcnt(6)
	v_mfma_f32_16x16x128_f8f6f4 v[62:65], v[2:9], v[150:157], v[62:65]
	s_barrier
	v_mfma_f32_16x16x128_f8f6f4 v[58:61], v[10:17], v[150:157], v[58:61]
	s_waitcnt lgkmcnt(4)
	v_mfma_f32_16x16x128_f8f6f4 v[54:57], v[2:9], v[158:165], v[54:57]
	v_mfma_f32_16x16x128_f8f6f4 v[50:53], v[10:17], v[158:165], v[50:53]
	s_waitcnt lgkmcnt(2)
	v_mfma_f32_16x16x128_f8f6f4 v[42:45], v[2:9], v[166:173], v[190:193]
	v_mfma_f32_16x16x128_f8f6f4 v[34:37], v[10:17], v[166:173], v[194:197]
	s_waitcnt lgkmcnt(0)
	v_mfma_f32_16x16x128_f8f6f4 v[26:29], v[2:9], v[174:181], v[206:209]
	v_mfma_f32_16x16x128_f8f6f4 v[18:21], v[10:17], v[174:181], v[210:213]
	v_mfma_f32_16x16x128_f8f6f4 v[46:49], v[134:141], v[150:157], v[214:217]
	v_mfma_f32_16x16x128_f8f6f4 v[38:41], v[142:149], v[150:157], v[218:221]
	v_mfma_f32_16x16x128_f8f6f4 v[30:33], v[134:141], v[158:165], v[234:237]
	v_mfma_f32_16x16x128_f8f6f4 v[22:25], v[142:149], v[158:165], v[238:241]
	v_mfma_f32_16x16x128_f8f6f4 v[14:17], v[134:141], v[166:173], v[242:245]
	v_mfma_f32_16x16x128_f8f6f4 v[10:13], v[142:149], v[166:173], v[246:249]
	v_mfma_f32_16x16x128_f8f6f4 v[6:9], v[134:141], v[174:181], v[250:253]
	v_mfma_f32_16x16x128_f8f6f4 v[2:5], v[142:149], v[174:181], v[130:133]
	s_setprio 0
	s_barrier
	s_add_i32 s55, s55, 2
	s_addk_i32 s8, 0x100
	s_addk_i32 s9, 0x100
	s_cmp_ge_i32 s55, s3
	s_cbranch_scc0 .LBB0_1567
	v_pk_mul_f32 v[208:209], v[128:129], s[50:51] op_sel_hi:[1,0]
	v_pk_mul_f32 v[210:211], v[126:127], s[50:51] op_sel_hi:[1,0]
	v_pk_mul_f32 v[212:213], v[124:125], s[50:51] op_sel_hi:[1,0]
	v_pk_mul_f32 v[122:123], v[122:123], s[50:51] op_sel_hi:[1,0]
	v_pk_mul_f32 v[220:221], v[112:113], s[50:51] op_sel_hi:[1,0]
	v_pk_mul_f32 v[218:219], v[110:111], s[50:51] op_sel_hi:[1,0]
	v_pk_mul_f32 v[216:217], v[104:105], s[50:51] op_sel_hi:[1,0]
	v_pk_mul_f32 v[214:215], v[102:103], s[50:51] op_sel_hi:[1,0]
	v_pk_mul_f32 v[206:207], v[120:121], s[50:51] op_sel_hi:[1,0]
	v_pk_mul_f32 v[146:147], v[118:119], s[50:51] op_sel_hi:[1,0]
	v_pk_mul_f32 v[204:205], v[116:117], s[50:51] op_sel_hi:[1,0]
	v_pk_mul_f32 v[144:145], v[114:115], s[50:51] op_sel_hi:[1,0]
	v_pk_mul_f32 v[148:149], v[96:97], s[50:51] op_sel_hi:[1,0]
	v_pk_mul_f32 v[154:155], v[94:95], s[50:51] op_sel_hi:[1,0]
	v_pk_mul_f32 v[202:203], v[88:89], s[50:51] op_sel_hi:[1,0]
	v_pk_mul_f32 v[200:201], v[86:87], s[50:51] op_sel_hi:[1,0]
	v_pk_mul_f32 v[198:199], v[108:109], s[50:51] op_sel_hi:[1,0]
	v_pk_mul_f32 v[152:153], v[106:107], s[50:51] op_sel_hi:[1,0]
	v_pk_mul_f32 v[196:197], v[100:101], s[50:51] op_sel_hi:[1,0]
	v_pk_mul_f32 v[150:151], v[98:99], s[50:51] op_sel_hi:[1,0]
	v_pk_mul_f32 v[156:157], v[80:81], s[50:51] op_sel_hi:[1,0]
	v_pk_mul_f32 v[162:163], v[78:79], s[50:51] op_sel_hi:[1,0]
	v_pk_mul_f32 v[194:195], v[76:77], s[50:51] op_sel_hi:[1,0]
	v_pk_mul_f32 v[192:193], v[74:75], s[50:51] op_sel_hi:[1,0]
	v_pk_mul_f32 v[190:191], v[92:93], s[50:51] op_sel_hi:[1,0]
	v_pk_mul_f32 v[160:161], v[90:91], s[50:51] op_sel_hi:[1,0]
	v_pk_mul_f32 v[188:189], v[84:85], s[50:51] op_sel_hi:[1,0]
	v_pk_mul_f32 v[158:159], v[82:83], s[50:51] op_sel_hi:[1,0]
	v_pk_mul_f32 v[164:165], v[72:73], s[50:51] op_sel_hi:[1,0]
	v_pk_mul_f32 v[170:171], v[70:71], s[50:51] op_sel_hi:[1,0]
	v_pk_mul_f32 v[186:187], v[68:69], s[50:51] op_sel_hi:[1,0]
	v_pk_mul_f32 v[184:185], v[66:67], s[50:51] op_sel_hi:[1,0]
	v_pk_mul_f32 v[182:183], v[64:65], s[50:51] op_sel_hi:[1,0]
	v_pk_mul_f32 v[168:169], v[62:63], s[50:51] op_sel_hi:[1,0]
	v_pk_mul_f32 v[180:181], v[60:61], s[50:51] op_sel_hi:[1,0]
	v_pk_mul_f32 v[166:167], v[58:59], s[50:51] op_sel_hi:[1,0]
	v_pk_mul_f32 v[172:173], v[48:49], s[50:51] op_sel_hi:[1,0]
	v_pk_mul_f32 v[178:179], v[46:47], s[50:51] op_sel_hi:[1,0]
	v_pk_mul_f32 v[176:177], v[40:41], s[50:51] op_sel_hi:[1,0]
	v_pk_mul_f32 v[174:175], v[38:39], s[50:51] op_sel_hi:[1,0]
	v_pk_mul_f32 v[142:143], v[56:57], s[50:51] op_sel_hi:[1,0]
	v_pk_mul_f32 v[140:141], v[54:55], s[50:51] op_sel_hi:[1,0]
	v_pk_mul_f32 v[138:139], v[52:53], s[50:51] op_sel_hi:[1,0]
	v_pk_mul_f32 v[134:135], v[50:51], s[50:51] op_sel_hi:[1,0]
	v_pk_mul_f32 v[136:137], v[32:33], s[50:51] op_sel_hi:[1,0]
	v_pk_mul_f32 v[128:129], v[30:31], s[50:51] op_sel_hi:[1,0]
	v_pk_mul_f32 v[126:127], v[24:25], s[50:51] op_sel_hi:[1,0]
	v_pk_mul_f32 v[124:125], v[22:23], s[50:51] op_sel_hi:[1,0]
	v_pk_mul_f32 v[102:103], v[44:45], s[50:51] op_sel_hi:[1,0]
	v_pk_mul_f32 v[100:101], v[42:43], s[50:51] op_sel_hi:[1,0]
	v_pk_mul_f32 v[98:99], v[36:37], s[50:51] op_sel_hi:[1,0]
	v_pk_mul_f32 v[94:95], v[34:35], s[50:51] op_sel_hi:[1,0]
	v_pk_mul_f32 v[96:97], v[16:17], s[50:51] op_sel_hi:[1,0]
	v_pk_mul_f32 v[92:93], v[14:15], s[50:51] op_sel_hi:[1,0]
	v_pk_mul_f32 v[90:91], v[12:13], s[50:51] op_sel_hi:[1,0]
	v_pk_mul_f32 v[88:89], v[10:11], s[50:51] op_sel_hi:[1,0]
	v_pk_mul_f32 v[86:87], v[28:29], s[50:51] op_sel_hi:[1,0]
	v_pk_mul_f32 v[84:85], v[26:27], s[50:51] op_sel_hi:[1,0]
	v_pk_mul_f32 v[82:83], v[20:21], s[50:51] op_sel_hi:[1,0]
	v_pk_mul_f32 v[78:79], v[18:19], s[50:51] op_sel_hi:[1,0]
	v_pk_mul_f32 v[80:81], v[8:9], s[50:51] op_sel_hi:[1,0]
	v_pk_mul_f32 v[76:77], v[6:7], s[50:51] op_sel_hi:[1,0]
	v_pk_mul_f32 v[74:75], v[4:5], s[50:51] op_sel_hi:[1,0]
	v_pk_mul_f32 v[72:73], v[2:3], s[50:51] op_sel_hi:[1,0]
	s_and_b64 vcc, exec, s[48:49]
	s_cbranch_vccz .LBB0_1570
